# removed the redundant s_waitcnt lgkmcnt(0) at the head of every 32-MFMA segment (already waited before the barrier), on top of peel-all
# speedup vs baseline: 1.0021x; 1.0021x over previous
.LBB0_255:
	s_ashr_i32 s29, s28, 31
	s_lshl_b64 s[30:31], s[28:29], 19
	s_add_u32 s30, s38, s30
	s_addc_u32 s31, s39, s31
	s_and_b64 s[34:35], s[8:9], exec
	s_cselect_b32 s1, s31, s11
	s_cselect_b32 s3, s30, s10
	s_ashr_i32 s27, s26, 31
	s_lshl_b64 s[34:35], s[26:27], 19
	s_add_u32 s34, s40, s34
	s_addc_u32 s35, s41, s35
	s_and_b64 s[36:37], s[8:9], exec
	s_cselect_b32 s27, s35, s13
	s_cselect_b32 s29, s34, s12
	s_add_u32 s10, s10, 0x40080
	s_addc_u32 s11, s11, 0
	s_add_u32 s33, s12, 0x100
	s_addc_u32 s58, s13, 0
	s_mov_b32 s59, -2
	ds_read_b128 v[32:35], v225
	ds_read_b128 v[36:39], v225 offset:1024
	ds_read_b128 v[40:43], v225 offset:2048
	ds_read_b128 v[44:47], v225 offset:3072
	ds_read_b128 v[144:147], v228
	ds_read_b128 v[148:151], v228 offset:1024
	ds_read_b128 v[152:155], v228 offset:2048
	ds_read_b128 v[156:159], v228 offset:3072
	s_add_u32 s12, s10, 0xfffc0080
	s_addc_u32 s13, s11, -1
	s_cmp_eq_u32 s59, 12
	s_cselect_b32 s37, s1, s13
	s_cselect_b32 s36, s3, s12
	s_cselect_b32 s13, s27, s58
	s_cselect_b32 s12, s29, s33
	v_lshl_add_u64 v[216:217], s[10:11], 0, v[206:207]
	s_add_i32 m0, s43, 0xc000
	ds_read_b128 v[160:163], v229
	ds_read_b128 v[164:167], v229 offset:1024
	ds_read_b128 v[168:171], v229 offset:2048
	ds_read_b128 v[172:175], v229 offset:3072
	ds_read_b128 v[176:179], v229 offset:4096
	ds_read_b128 v[180:183], v229 offset:5120
	ds_read_b128 v[184:187], v229 offset:6144
	ds_read_b128 v[188:191], v229 offset:7168
	global_load_lds_dwordx4 v[216:217], off
	v_lshl_add_u64 v[216:217], s[10:11], 0, v[208:209]
	s_add_i32 m0, s43, 0xe000
	s_nop 0
	global_load_lds_dwordx4 v[216:217], off
	s_waitcnt vmcnt(8)
	s_waitcnt lgkmcnt(0)
	s_barrier
	s_setprio 1
	v_mfma_f32_16x16x32_bf16 v[140:143], v[32:35], v[160:163], 0
	v_mfma_f32_16x16x32_bf16 v[136:139], v[40:43], v[160:163], 0
	v_mfma_f32_16x16x32_bf16 v[124:127], v[32:35], v[168:171], 0
	v_mfma_f32_16x16x32_bf16 v[120:123], v[40:43], v[168:171], 0
	v_mfma_f32_16x16x32_bf16 v[108:111], v[32:35], v[176:179], 0
	v_mfma_f32_16x16x32_bf16 v[104:107], v[40:43], v[176:179], 0
	v_mfma_f32_16x16x32_bf16 v[92:95], v[32:35], v[184:187], 0
	v_mfma_f32_16x16x32_bf16 v[88:91], v[40:43], v[184:187], 0
	v_mfma_f32_16x16x32_bf16 v[140:143], v[36:39], v[164:167], v[140:143]
	v_mfma_f32_16x16x32_bf16 v[136:139], v[44:47], v[164:167], v[136:139]
	v_mfma_f32_16x16x32_bf16 v[124:127], v[36:39], v[172:175], v[124:127]
	v_mfma_f32_16x16x32_bf16 v[120:123], v[44:47], v[172:175], v[120:123]
	v_mfma_f32_16x16x32_bf16 v[108:111], v[36:39], v[180:183], v[108:111]
	v_mfma_f32_16x16x32_bf16 v[104:107], v[44:47], v[180:183], v[104:107]
	v_mfma_f32_16x16x32_bf16 v[92:95], v[36:39], v[188:191], v[92:95]
	v_mfma_f32_16x16x32_bf16 v[88:91], v[44:47], v[188:191], v[88:91]
	s_setprio 0
	s_setprio 1
	v_mfma_f32_16x16x32_bf16 v[132:135], v[144:147], v[160:163], 0
	v_mfma_f32_16x16x32_bf16 v[128:131], v[152:155], v[160:163], 0
	v_mfma_f32_16x16x32_bf16 v[116:119], v[144:147], v[168:171], 0
	v_mfma_f32_16x16x32_bf16 v[112:115], v[152:155], v[168:171], 0
	v_mfma_f32_16x16x32_bf16 v[100:103], v[144:147], v[176:179], 0
	v_mfma_f32_16x16x32_bf16 v[96:99], v[152:155], v[176:179], 0
	v_mfma_f32_16x16x32_bf16 v[84:87], v[144:147], v[184:187], 0
	v_mfma_f32_16x16x32_bf16 v[80:83], v[152:155], v[184:187], 0
	v_mfma_f32_16x16x32_bf16 v[132:135], v[148:151], v[164:167], v[132:135]
	v_mfma_f32_16x16x32_bf16 v[128:131], v[156:159], v[164:167], v[128:131]
	v_mfma_f32_16x16x32_bf16 v[116:119], v[148:151], v[172:175], v[116:119]
	v_mfma_f32_16x16x32_bf16 v[112:115], v[156:159], v[172:175], v[112:115]
	v_mfma_f32_16x16x32_bf16 v[100:103], v[148:151], v[180:183], v[100:103]
	v_mfma_f32_16x16x32_bf16 v[96:99], v[156:159], v[180:183], v[96:99]
	v_mfma_f32_16x16x32_bf16 v[84:87], v[148:151], v[188:191], v[84:87]
	v_mfma_f32_16x16x32_bf16 v[80:83], v[156:159], v[188:191], v[80:83]
	s_setprio 0
	s_barrier
	s_add_i32 s60, s54, s42
	v_lshl_add_u64 v[216:217], s[12:13], 0, v[194:195]
	s_mov_b32 m0, s60
	ds_read_b128 v[160:163], v229 offset:16384
	ds_read_b128 v[164:167], v229 offset:17408
	ds_read_b128 v[168:171], v229 offset:18432
	ds_read_b128 v[172:175], v229 offset:19456
	ds_read_b128 v[176:179], v229 offset:20480
	ds_read_b128 v[180:183], v229 offset:21504
	ds_read_b128 v[184:187], v229 offset:22528
	ds_read_b128 v[188:191], v229 offset:23552
	global_load_lds_dwordx4 v[216:217], off
	s_add_i32 m0, s60, 0x2000
	s_add_u32 s60, s12, 0x40000
	v_lshl_add_u64 v[218:219], s[12:13], 0, v[198:199]
	s_addc_u32 s61, s13, 0
	s_add_i32 s62, s55, s42
	global_load_lds_dwordx4 v[218:219], off
	v_lshl_add_u64 v[220:221], s[60:61], 0, v[194:195]
	s_mov_b32 m0, s62
	v_lshl_add_u64 v[222:223], s[36:37], 0, v[196:197]
	global_load_lds_dwordx4 v[220:221], off
	v_lshl_add_u64 v[220:221], s[60:61], 0, v[198:199]
	s_add_i32 m0, s62, 0x2000
	s_nop 0
	global_load_lds_dwordx4 v[220:221], off
	v_lshl_add_u64 v[220:221], s[36:37], 0, v[192:193]
	s_mov_b32 m0, s43
	s_nop 0
	global_load_lds_dwordx4 v[220:221], off
	s_mov_b32 m0, s44
	s_nop 0
	global_load_lds_dwordx4 v[222:223], off
	s_waitcnt vmcnt(8)
	s_waitcnt lgkmcnt(0)
	s_barrier
	s_setprio 1
	v_mfma_f32_16x16x32_bf16 v[76:79], v[32:35], v[160:163], 0
	v_mfma_f32_16x16x32_bf16 v[72:75], v[40:43], v[160:163], 0
	v_mfma_f32_16x16x32_bf16 v[60:63], v[32:35], v[168:171], 0
	v_mfma_f32_16x16x32_bf16 v[56:59], v[40:43], v[168:171], 0
	v_mfma_f32_16x16x32_bf16 v[28:31], v[32:35], v[176:179], 0
	v_mfma_f32_16x16x32_bf16 v[24:27], v[40:43], v[176:179], 0
	v_mfma_f32_16x16x32_bf16 v[12:15], v[32:35], v[184:187], 0
	v_mfma_f32_16x16x32_bf16 v[8:11], v[40:43], v[184:187], 0
	v_mfma_f32_16x16x32_bf16 v[76:79], v[36:39], v[164:167], v[76:79]
	v_mfma_f32_16x16x32_bf16 v[72:75], v[44:47], v[164:167], v[72:75]
	v_mfma_f32_16x16x32_bf16 v[60:63], v[36:39], v[172:175], v[60:63]
	v_mfma_f32_16x16x32_bf16 v[56:59], v[44:47], v[172:175], v[56:59]
	v_mfma_f32_16x16x32_bf16 v[28:31], v[36:39], v[180:183], v[28:31]
	v_mfma_f32_16x16x32_bf16 v[24:27], v[44:47], v[180:183], v[24:27]
	v_mfma_f32_16x16x32_bf16 v[12:15], v[36:39], v[188:191], v[12:15]
	v_mfma_f32_16x16x32_bf16 v[8:11], v[44:47], v[188:191], v[8:11]
	s_setprio 0
	s_setprio 1
	v_mfma_f32_16x16x32_bf16 v[20:23], v[144:147], v[176:179], 0
	v_mfma_f32_16x16x32_bf16 v[16:19], v[152:155], v[176:179], 0
	v_mfma_f32_16x16x32_bf16 v[4:7], v[144:147], v[184:187], 0
	v_mfma_f32_16x16x32_bf16 v[0:3], v[152:155], v[184:187], 0
	v_mfma_f32_16x16x32_bf16 v[32:35], v[144:147], v[160:163], 0
	v_mfma_f32_16x16x32_bf16 v[36:39], v[152:155], v[160:163], 0
	v_mfma_f32_16x16x32_bf16 v[40:43], v[144:147], v[168:171], 0
	v_mfma_f32_16x16x32_bf16 v[44:47], v[152:155], v[168:171], 0
	v_mfma_f32_16x16x32_bf16 v[20:23], v[148:151], v[180:183], v[20:23]
	v_mfma_f32_16x16x32_bf16 v[16:19], v[156:159], v[180:183], v[16:19]
	v_mfma_f32_16x16x32_bf16 v[4:7], v[148:151], v[188:191], v[4:7]
	v_mfma_f32_16x16x32_bf16 v[0:3], v[156:159], v[188:191], v[0:3]
	v_mfma_f32_16x16x32_bf16 v[32:35], v[148:151], v[164:167], v[32:35]
	v_mfma_f32_16x16x32_bf16 v[36:39], v[156:159], v[164:167], v[36:39]
	v_mfma_f32_16x16x32_bf16 v[40:43], v[148:151], v[172:175], v[40:43]
	v_mfma_f32_16x16x32_bf16 v[44:47], v[156:159], v[172:175], v[44:47]
	s_setprio 0
	s_barrier
	s_add_i32 s60, 0, 0x18000
	s_add_i32 s61, 0, 0x1c000
	v_add_u32_e32 v68, s60, v224
	v_add_u32_e32 v156, s61, v224
	ds_read_b128 v[48:51], v68
	ds_read_b128 v[52:55], v68 offset:1024
	ds_read_b128 v[64:67], v68 offset:2048
	ds_read_b128 v[68:71], v68 offset:3072
	ds_read_b128 v[144:147], v156
	ds_read_b128 v[148:151], v156 offset:1024
	ds_read_b128 v[152:155], v156 offset:2048
	ds_read_b128 v[156:159], v156 offset:3072
	s_add_u32 s36, s36, 0x40000
	s_addc_u32 s37, s37, 0
	s_mov_b32 m0, s45
	v_lshl_add_u64 v[236:237], s[36:37], 0, v[192:193]
	ds_read_b128 v[160:163], v229 offset:32768
	ds_read_b128 v[164:167], v229 offset:33792
	ds_read_b128 v[168:171], v229 offset:34816
	ds_read_b128 v[172:175], v229 offset:35840
	ds_read_b128 v[176:179], v229 offset:36864
	ds_read_b128 v[180:183], v229 offset:37888
	ds_read_b128 v[184:187], v229 offset:38912
	ds_read_b128 v[188:191], v229 offset:39936
	global_load_lds_dwordx4 v[236:237], off
	v_lshl_add_u64 v[236:237], s[36:37], 0, v[196:197]
	s_mov_b32 m0, s46
	s_nop 0
	global_load_lds_dwordx4 v[236:237], off
	s_waitcnt vmcnt(8)
	s_waitcnt lgkmcnt(0)
	s_barrier
	s_setprio 1
	v_mfma_f32_16x16x32_bf16 v[140:143], v[48:51], v[160:163], v[140:143]
	v_mfma_f32_16x16x32_bf16 v[136:139], v[64:67], v[160:163], v[136:139]
	v_mfma_f32_16x16x32_bf16 v[124:127], v[48:51], v[168:171], v[124:127]
	v_mfma_f32_16x16x32_bf16 v[120:123], v[64:67], v[168:171], v[120:123]
	v_mfma_f32_16x16x32_bf16 v[108:111], v[48:51], v[176:179], v[108:111]
	v_mfma_f32_16x16x32_bf16 v[104:107], v[64:67], v[176:179], v[104:107]
	v_mfma_f32_16x16x32_bf16 v[92:95], v[48:51], v[184:187], v[92:95]
	v_mfma_f32_16x16x32_bf16 v[88:91], v[64:67], v[184:187], v[88:91]
	v_mfma_f32_16x16x32_bf16 v[140:143], v[52:55], v[164:167], v[140:143]
	v_mfma_f32_16x16x32_bf16 v[136:139], v[68:71], v[164:167], v[136:139]
	v_mfma_f32_16x16x32_bf16 v[124:127], v[52:55], v[172:175], v[124:127]
	v_mfma_f32_16x16x32_bf16 v[120:123], v[68:71], v[172:175], v[120:123]
	v_mfma_f32_16x16x32_bf16 v[108:111], v[52:55], v[180:183], v[108:111]
	v_mfma_f32_16x16x32_bf16 v[104:107], v[68:71], v[180:183], v[104:107]
	v_mfma_f32_16x16x32_bf16 v[92:95], v[52:55], v[188:191], v[92:95]
	v_mfma_f32_16x16x32_bf16 v[88:91], v[68:71], v[188:191], v[88:91]
	s_setprio 0
	s_setprio 1
	v_mfma_f32_16x16x32_bf16 v[132:135], v[144:147], v[160:163], v[132:135]
	v_mfma_f32_16x16x32_bf16 v[128:131], v[152:155], v[160:163], v[128:131]
	v_mfma_f32_16x16x32_bf16 v[116:119], v[144:147], v[168:171], v[116:119]
	v_mfma_f32_16x16x32_bf16 v[112:115], v[152:155], v[168:171], v[112:115]
	v_mfma_f32_16x16x32_bf16 v[100:103], v[144:147], v[176:179], v[100:103]
	v_mfma_f32_16x16x32_bf16 v[96:99], v[152:155], v[176:179], v[96:99]
	v_mfma_f32_16x16x32_bf16 v[84:87], v[144:147], v[184:187], v[84:87]
	v_mfma_f32_16x16x32_bf16 v[80:83], v[152:155], v[184:187], v[80:83]
	v_mfma_f32_16x16x32_bf16 v[132:135], v[148:151], v[164:167], v[132:135]
	v_mfma_f32_16x16x32_bf16 v[128:131], v[156:159], v[164:167], v[128:131]
	v_mfma_f32_16x16x32_bf16 v[116:119], v[148:151], v[172:175], v[116:119]
	v_mfma_f32_16x16x32_bf16 v[112:115], v[156:159], v[172:175], v[112:115]
	v_mfma_f32_16x16x32_bf16 v[100:103], v[148:151], v[180:183], v[100:103]
	v_mfma_f32_16x16x32_bf16 v[96:99], v[156:159], v[180:183], v[96:99]
	v_mfma_f32_16x16x32_bf16 v[84:87], v[148:151], v[188:191], v[84:87]
	v_mfma_f32_16x16x32_bf16 v[80:83], v[156:159], v[188:191], v[80:83]
	s_setprio 0
	s_barrier
	s_add_i32 s36, s60, s42
	v_lshl_add_u64 v[216:217], v[216:217], 0, s[22:23]
	s_mov_b32 m0, s36
	ds_read_b128 v[160:163], v229 offset:49152
	ds_read_b128 v[164:167], v229 offset:50176
	ds_read_b128 v[168:171], v229 offset:51200
	ds_read_b128 v[172:175], v229 offset:52224
	ds_read_b128 v[176:179], v229 offset:53248
	ds_read_b128 v[180:183], v229 offset:54272
	ds_read_b128 v[184:187], v229 offset:55296
	ds_read_b128 v[188:191], v229 offset:56320
	global_load_lds_dwordx4 v[216:217], off
	s_add_i32 m0, s36, 0x2000
	s_add_u32 s12, s12, 0x40080
	v_lshl_add_u64 v[216:217], v[218:219], 0, s[22:23]
	s_addc_u32 s13, s13, 0
	s_add_i32 s36, s61, s42
	global_load_lds_dwordx4 v[216:217], off
	v_lshl_add_u64 v[216:217], s[12:13], 0, v[194:195]
	s_mov_b32 m0, s36
	s_nop 0
	global_load_lds_dwordx4 v[216:217], off
	v_lshl_add_u64 v[216:217], s[12:13], 0, v[198:199]
	s_add_i32 m0, s36, 0x2000
	s_nop 0
	global_load_lds_dwordx4 v[216:217], off
	v_lshl_add_u64 v[216:217], v[220:221], 0, s[22:23]
	s_mov_b32 m0, s49
	s_nop 0
	global_load_lds_dwordx4 v[216:217], off
	v_lshl_add_u64 v[216:217], v[222:223], 0, s[22:23]
	s_mov_b32 m0, s50
	s_nop 0
	global_load_lds_dwordx4 v[216:217], off
	s_waitcnt vmcnt(8)
	s_waitcnt lgkmcnt(0)
	s_barrier
	s_setprio 1
	v_mfma_f32_16x16x32_bf16 v[76:79], v[48:51], v[160:163], v[76:79]
	v_mfma_f32_16x16x32_bf16 v[72:75], v[64:67], v[160:163], v[72:75]
	v_mfma_f32_16x16x32_bf16 v[60:63], v[48:51], v[168:171], v[60:63]
	v_mfma_f32_16x16x32_bf16 v[56:59], v[64:67], v[168:171], v[56:59]
	v_mfma_f32_16x16x32_bf16 v[28:31], v[48:51], v[176:179], v[28:31]
	v_mfma_f32_16x16x32_bf16 v[24:27], v[64:67], v[176:179], v[24:27]
	v_mfma_f32_16x16x32_bf16 v[12:15], v[48:51], v[184:187], v[12:15]
	v_mfma_f32_16x16x32_bf16 v[8:11], v[64:67], v[184:187], v[8:11]
	v_mfma_f32_16x16x32_bf16 v[76:79], v[52:55], v[164:167], v[76:79]
	v_mfma_f32_16x16x32_bf16 v[72:75], v[68:71], v[164:167], v[72:75]
	v_mfma_f32_16x16x32_bf16 v[60:63], v[52:55], v[172:175], v[60:63]
	v_mfma_f32_16x16x32_bf16 v[56:59], v[68:71], v[172:175], v[56:59]
	v_mfma_f32_16x16x32_bf16 v[28:31], v[52:55], v[180:183], v[28:31]
	v_mfma_f32_16x16x32_bf16 v[24:27], v[68:71], v[180:183], v[24:27]
	v_mfma_f32_16x16x32_bf16 v[12:15], v[52:55], v[188:191], v[12:15]
	v_mfma_f32_16x16x32_bf16 v[8:11], v[68:71], v[188:191], v[8:11]
	s_setprio 0
	s_setprio 1
	v_mfma_f32_16x16x32_bf16 v[32:35], v[144:147], v[160:163], v[32:35]
	v_mfma_f32_16x16x32_bf16 v[68:71], v[148:151], v[164:167], v[32:35]
	v_mfma_f32_16x16x32_bf16 v[32:35], v[152:155], v[160:163], v[36:39]
	v_mfma_f32_16x16x32_bf16 v[64:67], v[156:159], v[164:167], v[32:35]
	v_mfma_f32_16x16x32_bf16 v[32:35], v[144:147], v[168:171], v[40:43]
	v_mfma_f32_16x16x32_bf16 v[52:55], v[148:151], v[172:175], v[32:35]
	v_mfma_f32_16x16x32_bf16 v[32:35], v[152:155], v[168:171], v[44:47]
	v_mfma_f32_16x16x32_bf16 v[20:23], v[144:147], v[176:179], v[20:23]
	v_mfma_f32_16x16x32_bf16 v[16:19], v[152:155], v[176:179], v[16:19]
	v_mfma_f32_16x16x32_bf16 v[4:7], v[144:147], v[184:187], v[4:7]
	v_mfma_f32_16x16x32_bf16 v[0:3], v[152:155], v[184:187], v[0:3]
	v_mfma_f32_16x16x32_bf16 v[48:51], v[156:159], v[172:175], v[32:35]
	v_mfma_f32_16x16x32_bf16 v[20:23], v[148:151], v[180:183], v[20:23]
	v_mfma_f32_16x16x32_bf16 v[16:19], v[156:159], v[180:183], v[16:19]
	v_mfma_f32_16x16x32_bf16 v[4:7], v[148:151], v[188:191], v[4:7]
	v_mfma_f32_16x16x32_bf16 v[0:3], v[156:159], v[188:191], v[0:3]
	s_setprio 0
	s_barrier
	s_add_i32 s59, s59, 2
	s_add_u32 s10, s10, 0x100
	s_addc_u32 s11, s11, 0
	s_add_u32 s33, s33, 0x100
	s_addc_u32 s58, s58, 0
	s_cmp_gt_u32 s59, 13
.LBB0_256:
	ds_read_b128 v[32:35], v225
	ds_read_b128 v[36:39], v225 offset:1024
	ds_read_b128 v[40:43], v225 offset:2048
	ds_read_b128 v[44:47], v225 offset:3072
	ds_read_b128 v[144:147], v228
	ds_read_b128 v[148:151], v228 offset:1024
	ds_read_b128 v[152:155], v228 offset:2048
	ds_read_b128 v[156:159], v228 offset:3072
	s_add_u32 s12, s10, 0xfffc0080
	s_addc_u32 s13, s11, -1
	s_cmp_eq_u32 s59, 12
	s_cselect_b32 s37, s1, s13
	s_cselect_b32 s36, s3, s12
	s_cselect_b32 s13, s27, s58
	s_cselect_b32 s12, s29, s33
	v_lshl_add_u64 v[216:217], s[10:11], 0, v[206:207]
	s_add_i32 m0, s43, 0xc000
	ds_read_b128 v[160:163], v229
	ds_read_b128 v[164:167], v229 offset:1024
	ds_read_b128 v[168:171], v229 offset:2048
	ds_read_b128 v[172:175], v229 offset:3072
	ds_read_b128 v[176:179], v229 offset:4096
	ds_read_b128 v[180:183], v229 offset:5120
	ds_read_b128 v[184:187], v229 offset:6144
	ds_read_b128 v[188:191], v229 offset:7168
	global_load_lds_dwordx4 v[216:217], off
	v_lshl_add_u64 v[216:217], s[10:11], 0, v[208:209]
	s_add_i32 m0, s43, 0xe000
	s_nop 0
	global_load_lds_dwordx4 v[216:217], off
	s_waitcnt vmcnt(8)
	s_waitcnt lgkmcnt(0)
	s_barrier
	s_setprio 1
	v_mfma_f32_16x16x32_bf16 v[140:143], v[32:35], v[160:163], v[140:143]
	v_mfma_f32_16x16x32_bf16 v[136:139], v[40:43], v[160:163], v[136:139]
	v_mfma_f32_16x16x32_bf16 v[124:127], v[32:35], v[168:171], v[124:127]
	v_mfma_f32_16x16x32_bf16 v[120:123], v[40:43], v[168:171], v[120:123]
	v_mfma_f32_16x16x32_bf16 v[108:111], v[32:35], v[176:179], v[108:111]
	v_mfma_f32_16x16x32_bf16 v[104:107], v[40:43], v[176:179], v[104:107]
	v_mfma_f32_16x16x32_bf16 v[92:95], v[32:35], v[184:187], v[92:95]
	v_mfma_f32_16x16x32_bf16 v[88:91], v[40:43], v[184:187], v[88:91]
	v_mfma_f32_16x16x32_bf16 v[140:143], v[36:39], v[164:167], v[140:143]
	v_mfma_f32_16x16x32_bf16 v[136:139], v[44:47], v[164:167], v[136:139]
	v_mfma_f32_16x16x32_bf16 v[124:127], v[36:39], v[172:175], v[124:127]
	v_mfma_f32_16x16x32_bf16 v[120:123], v[44:47], v[172:175], v[120:123]
	v_mfma_f32_16x16x32_bf16 v[108:111], v[36:39], v[180:183], v[108:111]
	v_mfma_f32_16x16x32_bf16 v[104:107], v[44:47], v[180:183], v[104:107]
	v_mfma_f32_16x16x32_bf16 v[92:95], v[36:39], v[188:191], v[92:95]
	v_mfma_f32_16x16x32_bf16 v[88:91], v[44:47], v[188:191], v[88:91]
	s_setprio 0
	s_setprio 1
	v_mfma_f32_16x16x32_bf16 v[132:135], v[144:147], v[160:163], v[132:135]
	v_mfma_f32_16x16x32_bf16 v[128:131], v[152:155], v[160:163], v[128:131]
	v_mfma_f32_16x16x32_bf16 v[116:119], v[144:147], v[168:171], v[116:119]
	v_mfma_f32_16x16x32_bf16 v[112:115], v[152:155], v[168:171], v[112:115]
	v_mfma_f32_16x16x32_bf16 v[100:103], v[144:147], v[176:179], v[100:103]
	v_mfma_f32_16x16x32_bf16 v[96:99], v[152:155], v[176:179], v[96:99]
	v_mfma_f32_16x16x32_bf16 v[84:87], v[144:147], v[184:187], v[84:87]
	v_mfma_f32_16x16x32_bf16 v[80:83], v[152:155], v[184:187], v[80:83]
	v_mfma_f32_16x16x32_bf16 v[132:135], v[148:151], v[164:167], v[132:135]
	v_mfma_f32_16x16x32_bf16 v[128:131], v[156:159], v[164:167], v[128:131]
	v_mfma_f32_16x16x32_bf16 v[116:119], v[148:151], v[172:175], v[116:119]
	v_mfma_f32_16x16x32_bf16 v[112:115], v[156:159], v[172:175], v[112:115]
	v_mfma_f32_16x16x32_bf16 v[100:103], v[148:151], v[180:183], v[100:103]
	v_mfma_f32_16x16x32_bf16 v[96:99], v[156:159], v[180:183], v[96:99]
	v_mfma_f32_16x16x32_bf16 v[84:87], v[148:151], v[188:191], v[84:87]
	v_mfma_f32_16x16x32_bf16 v[80:83], v[156:159], v[188:191], v[80:83]
	s_setprio 0
	s_barrier
	s_add_i32 s60, s54, s42
	v_lshl_add_u64 v[216:217], s[12:13], 0, v[194:195]
	s_mov_b32 m0, s60
	ds_read_b128 v[160:163], v229 offset:16384
	ds_read_b128 v[164:167], v229 offset:17408
	ds_read_b128 v[168:171], v229 offset:18432
	ds_read_b128 v[172:175], v229 offset:19456
	ds_read_b128 v[176:179], v229 offset:20480
	ds_read_b128 v[180:183], v229 offset:21504
	ds_read_b128 v[184:187], v229 offset:22528
	ds_read_b128 v[188:191], v229 offset:23552
	global_load_lds_dwordx4 v[216:217], off
	s_add_i32 m0, s60, 0x2000
	s_add_u32 s60, s12, 0x40000
	v_lshl_add_u64 v[218:219], s[12:13], 0, v[198:199]
	s_addc_u32 s61, s13, 0
	s_add_i32 s62, s55, s42
	global_load_lds_dwordx4 v[218:219], off
	v_lshl_add_u64 v[220:221], s[60:61], 0, v[194:195]
	s_mov_b32 m0, s62
	v_lshl_add_u64 v[222:223], s[36:37], 0, v[196:197]
	global_load_lds_dwordx4 v[220:221], off
	v_lshl_add_u64 v[220:221], s[60:61], 0, v[198:199]
	s_add_i32 m0, s62, 0x2000
	s_nop 0
	global_load_lds_dwordx4 v[220:221], off
	v_lshl_add_u64 v[220:221], s[36:37], 0, v[192:193]
	s_mov_b32 m0, s43
	s_nop 0
	global_load_lds_dwordx4 v[220:221], off
	s_mov_b32 m0, s44
	s_nop 0
	global_load_lds_dwordx4 v[222:223], off
	s_waitcnt vmcnt(8)
	s_waitcnt lgkmcnt(0)
	s_barrier
	s_setprio 1
	v_mfma_f32_16x16x32_bf16 v[76:79], v[32:35], v[160:163], v[76:79]
	v_mfma_f32_16x16x32_bf16 v[72:75], v[40:43], v[160:163], v[72:75]
	v_mfma_f32_16x16x32_bf16 v[60:63], v[32:35], v[168:171], v[60:63]
	v_mfma_f32_16x16x32_bf16 v[56:59], v[40:43], v[168:171], v[56:59]
	v_mfma_f32_16x16x32_bf16 v[28:31], v[32:35], v[176:179], v[28:31]
	v_mfma_f32_16x16x32_bf16 v[24:27], v[40:43], v[176:179], v[24:27]
	v_mfma_f32_16x16x32_bf16 v[12:15], v[32:35], v[184:187], v[12:15]
	v_mfma_f32_16x16x32_bf16 v[8:11], v[40:43], v[184:187], v[8:11]
	v_mfma_f32_16x16x32_bf16 v[76:79], v[36:39], v[164:167], v[76:79]
	v_mfma_f32_16x16x32_bf16 v[72:75], v[44:47], v[164:167], v[72:75]
	v_mfma_f32_16x16x32_bf16 v[60:63], v[36:39], v[172:175], v[60:63]
	v_mfma_f32_16x16x32_bf16 v[56:59], v[44:47], v[172:175], v[56:59]
	v_mfma_f32_16x16x32_bf16 v[28:31], v[36:39], v[180:183], v[28:31]
	v_mfma_f32_16x16x32_bf16 v[24:27], v[44:47], v[180:183], v[24:27]
	v_mfma_f32_16x16x32_bf16 v[12:15], v[36:39], v[188:191], v[12:15]
	v_mfma_f32_16x16x32_bf16 v[8:11], v[44:47], v[188:191], v[8:11]
	s_setprio 0
	s_setprio 1
	v_mfma_f32_16x16x32_bf16 v[20:23], v[144:147], v[176:179], v[20:23]
	v_mfma_f32_16x16x32_bf16 v[16:19], v[152:155], v[176:179], v[16:19]
	v_mfma_f32_16x16x32_bf16 v[4:7], v[144:147], v[184:187], v[4:7]
	v_mfma_f32_16x16x32_bf16 v[0:3], v[152:155], v[184:187], v[0:3]
	v_mfma_f32_16x16x32_bf16 v[32:35], v[144:147], v[160:163], v[68:71]
	v_mfma_f32_16x16x32_bf16 v[36:39], v[152:155], v[160:163], v[64:67]
	v_mfma_f32_16x16x32_bf16 v[40:43], v[144:147], v[168:171], v[52:55]
	v_mfma_f32_16x16x32_bf16 v[44:47], v[152:155], v[168:171], v[48:51]
	v_mfma_f32_16x16x32_bf16 v[20:23], v[148:151], v[180:183], v[20:23]
	v_mfma_f32_16x16x32_bf16 v[16:19], v[156:159], v[180:183], v[16:19]
	v_mfma_f32_16x16x32_bf16 v[4:7], v[148:151], v[188:191], v[4:7]
	v_mfma_f32_16x16x32_bf16 v[0:3], v[156:159], v[188:191], v[0:3]
	v_mfma_f32_16x16x32_bf16 v[32:35], v[148:151], v[164:167], v[32:35]
	v_mfma_f32_16x16x32_bf16 v[36:39], v[156:159], v[164:167], v[36:39]
	v_mfma_f32_16x16x32_bf16 v[40:43], v[148:151], v[172:175], v[40:43]
	v_mfma_f32_16x16x32_bf16 v[44:47], v[156:159], v[172:175], v[44:47]
	s_setprio 0
	s_barrier
	s_add_i32 s60, 0, 0x18000
	s_add_i32 s61, 0, 0x1c000
	v_add_u32_e32 v68, s60, v224
	v_add_u32_e32 v156, s61, v224
	ds_read_b128 v[48:51], v68
	ds_read_b128 v[52:55], v68 offset:1024
	ds_read_b128 v[64:67], v68 offset:2048
	ds_read_b128 v[68:71], v68 offset:3072
	ds_read_b128 v[144:147], v156
	ds_read_b128 v[148:151], v156 offset:1024
	ds_read_b128 v[152:155], v156 offset:2048
	ds_read_b128 v[156:159], v156 offset:3072
	s_add_u32 s36, s36, 0x40000
	s_addc_u32 s37, s37, 0
	s_mov_b32 m0, s45
	v_lshl_add_u64 v[236:237], s[36:37], 0, v[192:193]
	ds_read_b128 v[160:163], v229 offset:32768
	ds_read_b128 v[164:167], v229 offset:33792
	ds_read_b128 v[168:171], v229 offset:34816
	ds_read_b128 v[172:175], v229 offset:35840
	ds_read_b128 v[176:179], v229 offset:36864
	ds_read_b128 v[180:183], v229 offset:37888
	ds_read_b128 v[184:187], v229 offset:38912
	ds_read_b128 v[188:191], v229 offset:39936
	global_load_lds_dwordx4 v[236:237], off
	v_lshl_add_u64 v[236:237], s[36:37], 0, v[196:197]
	s_mov_b32 m0, s46
	s_nop 0
	global_load_lds_dwordx4 v[236:237], off
	s_waitcnt vmcnt(8)
	s_waitcnt lgkmcnt(0)
	s_barrier
	s_setprio 1
	v_mfma_f32_16x16x32_bf16 v[140:143], v[48:51], v[160:163], v[140:143]
	v_mfma_f32_16x16x32_bf16 v[136:139], v[64:67], v[160:163], v[136:139]
	v_mfma_f32_16x16x32_bf16 v[124:127], v[48:51], v[168:171], v[124:127]
	v_mfma_f32_16x16x32_bf16 v[120:123], v[64:67], v[168:171], v[120:123]
	v_mfma_f32_16x16x32_bf16 v[108:111], v[48:51], v[176:179], v[108:111]
	v_mfma_f32_16x16x32_bf16 v[104:107], v[64:67], v[176:179], v[104:107]
	v_mfma_f32_16x16x32_bf16 v[92:95], v[48:51], v[184:187], v[92:95]
	v_mfma_f32_16x16x32_bf16 v[88:91], v[64:67], v[184:187], v[88:91]
	v_mfma_f32_16x16x32_bf16 v[140:143], v[52:55], v[164:167], v[140:143]
	v_mfma_f32_16x16x32_bf16 v[136:139], v[68:71], v[164:167], v[136:139]
	v_mfma_f32_16x16x32_bf16 v[124:127], v[52:55], v[172:175], v[124:127]
	v_mfma_f32_16x16x32_bf16 v[120:123], v[68:71], v[172:175], v[120:123]
	v_mfma_f32_16x16x32_bf16 v[108:111], v[52:55], v[180:183], v[108:111]
	v_mfma_f32_16x16x32_bf16 v[104:107], v[68:71], v[180:183], v[104:107]
	v_mfma_f32_16x16x32_bf16 v[92:95], v[52:55], v[188:191], v[92:95]
	v_mfma_f32_16x16x32_bf16 v[88:91], v[68:71], v[188:191], v[88:91]
	s_setprio 0
	s_setprio 1
	v_mfma_f32_16x16x32_bf16 v[132:135], v[144:147], v[160:163], v[132:135]
	v_mfma_f32_16x16x32_bf16 v[128:131], v[152:155], v[160:163], v[128:131]
	v_mfma_f32_16x16x32_bf16 v[116:119], v[144:147], v[168:171], v[116:119]
	v_mfma_f32_16x16x32_bf16 v[112:115], v[152:155], v[168:171], v[112:115]
	v_mfma_f32_16x16x32_bf16 v[100:103], v[144:147], v[176:179], v[100:103]
	v_mfma_f32_16x16x32_bf16 v[96:99], v[152:155], v[176:179], v[96:99]
	v_mfma_f32_16x16x32_bf16 v[84:87], v[144:147], v[184:187], v[84:87]
	v_mfma_f32_16x16x32_bf16 v[80:83], v[152:155], v[184:187], v[80:83]
	v_mfma_f32_16x16x32_bf16 v[132:135], v[148:151], v[164:167], v[132:135]
	v_mfma_f32_16x16x32_bf16 v[128:131], v[156:159], v[164:167], v[128:131]
	v_mfma_f32_16x16x32_bf16 v[116:119], v[148:151], v[172:175], v[116:119]
	v_mfma_f32_16x16x32_bf16 v[112:115], v[156:159], v[172:175], v[112:115]
	v_mfma_f32_16x16x32_bf16 v[100:103], v[148:151], v[180:183], v[100:103]
	v_mfma_f32_16x16x32_bf16 v[96:99], v[156:159], v[180:183], v[96:99]
	v_mfma_f32_16x16x32_bf16 v[84:87], v[148:151], v[188:191], v[84:87]
	v_mfma_f32_16x16x32_bf16 v[80:83], v[156:159], v[188:191], v[80:83]
	s_setprio 0
	s_barrier
	s_add_i32 s36, s60, s42
	v_lshl_add_u64 v[216:217], v[216:217], 0, s[22:23]
	s_mov_b32 m0, s36
	ds_read_b128 v[160:163], v229 offset:49152
	ds_read_b128 v[164:167], v229 offset:50176
	ds_read_b128 v[168:171], v229 offset:51200
	ds_read_b128 v[172:175], v229 offset:52224
	ds_read_b128 v[176:179], v229 offset:53248
	ds_read_b128 v[180:183], v229 offset:54272
	ds_read_b128 v[184:187], v229 offset:55296
	ds_read_b128 v[188:191], v229 offset:56320
	global_load_lds_dwordx4 v[216:217], off
	s_add_i32 m0, s36, 0x2000
	s_add_u32 s12, s12, 0x40080
	v_lshl_add_u64 v[216:217], v[218:219], 0, s[22:23]
	s_addc_u32 s13, s13, 0
	s_add_i32 s36, s61, s42
	global_load_lds_dwordx4 v[216:217], off
	v_lshl_add_u64 v[216:217], s[12:13], 0, v[194:195]
	s_mov_b32 m0, s36
	s_nop 0
	global_load_lds_dwordx4 v[216:217], off
	v_lshl_add_u64 v[216:217], s[12:13], 0, v[198:199]
	s_add_i32 m0, s36, 0x2000
	s_nop 0
	global_load_lds_dwordx4 v[216:217], off
	v_lshl_add_u64 v[216:217], v[220:221], 0, s[22:23]
	s_mov_b32 m0, s49
	s_nop 0
	global_load_lds_dwordx4 v[216:217], off
	v_lshl_add_u64 v[216:217], v[222:223], 0, s[22:23]
	s_mov_b32 m0, s50
	s_nop 0
	global_load_lds_dwordx4 v[216:217], off
	s_waitcnt vmcnt(8)
	s_waitcnt lgkmcnt(0)
	s_barrier
	s_setprio 1
	v_mfma_f32_16x16x32_bf16 v[76:79], v[48:51], v[160:163], v[76:79]
	v_mfma_f32_16x16x32_bf16 v[72:75], v[64:67], v[160:163], v[72:75]
	v_mfma_f32_16x16x32_bf16 v[60:63], v[48:51], v[168:171], v[60:63]
	v_mfma_f32_16x16x32_bf16 v[56:59], v[64:67], v[168:171], v[56:59]
	v_mfma_f32_16x16x32_bf16 v[28:31], v[48:51], v[176:179], v[28:31]
	v_mfma_f32_16x16x32_bf16 v[24:27], v[64:67], v[176:179], v[24:27]
	v_mfma_f32_16x16x32_bf16 v[12:15], v[48:51], v[184:187], v[12:15]
	v_mfma_f32_16x16x32_bf16 v[8:11], v[64:67], v[184:187], v[8:11]
	v_mfma_f32_16x16x32_bf16 v[76:79], v[52:55], v[164:167], v[76:79]
	v_mfma_f32_16x16x32_bf16 v[72:75], v[68:71], v[164:167], v[72:75]
	v_mfma_f32_16x16x32_bf16 v[60:63], v[52:55], v[172:175], v[60:63]
	v_mfma_f32_16x16x32_bf16 v[56:59], v[68:71], v[172:175], v[56:59]
	v_mfma_f32_16x16x32_bf16 v[28:31], v[52:55], v[180:183], v[28:31]
	v_mfma_f32_16x16x32_bf16 v[24:27], v[68:71], v[180:183], v[24:27]
	v_mfma_f32_16x16x32_bf16 v[12:15], v[52:55], v[188:191], v[12:15]
	v_mfma_f32_16x16x32_bf16 v[8:11], v[68:71], v[188:191], v[8:11]
	s_setprio 0
	s_setprio 1
	v_mfma_f32_16x16x32_bf16 v[32:35], v[144:147], v[160:163], v[32:35]
	v_mfma_f32_16x16x32_bf16 v[68:71], v[148:151], v[164:167], v[32:35]
	v_mfma_f32_16x16x32_bf16 v[32:35], v[152:155], v[160:163], v[36:39]
	v_mfma_f32_16x16x32_bf16 v[64:67], v[156:159], v[164:167], v[32:35]
	v_mfma_f32_16x16x32_bf16 v[32:35], v[144:147], v[168:171], v[40:43]
	v_mfma_f32_16x16x32_bf16 v[52:55], v[148:151], v[172:175], v[32:35]
	v_mfma_f32_16x16x32_bf16 v[32:35], v[152:155], v[168:171], v[44:47]
	v_mfma_f32_16x16x32_bf16 v[20:23], v[144:147], v[176:179], v[20:23]
	v_mfma_f32_16x16x32_bf16 v[16:19], v[152:155], v[176:179], v[16:19]
	v_mfma_f32_16x16x32_bf16 v[4:7], v[144:147], v[184:187], v[4:7]
	v_mfma_f32_16x16x32_bf16 v[0:3], v[152:155], v[184:187], v[0:3]
	v_mfma_f32_16x16x32_bf16 v[48:51], v[156:159], v[172:175], v[32:35]
	v_mfma_f32_16x16x32_bf16 v[20:23], v[148:151], v[180:183], v[20:23]
	v_mfma_f32_16x16x32_bf16 v[16:19], v[156:159], v[180:183], v[16:19]
	v_mfma_f32_16x16x32_bf16 v[4:7], v[148:151], v[188:191], v[4:7]
	v_mfma_f32_16x16x32_bf16 v[0:3], v[156:159], v[188:191], v[0:3]
	s_setprio 0
	s_barrier
	s_add_i32 s59, s59, 2
	s_add_u32 s10, s10, 0x100
	s_addc_u32 s11, s11, 0
	s_add_u32 s33, s33, 0x100
	s_addc_u32 s58, s58, 0
	s_cmp_gt_u32 s59, 13
	s_cbranch_scc0 .LBB0_256
	s_and_b64 vcc, exec, s[24:25]
	s_cbranch_vccz .LBB0_259
	s_barrier

.LBB0_610:
	v_bfe_u32 v133, v226, 4, 2
	s_lshl_b32 s6, s6, 5
	v_lshlrev_b32_e32 v11, 6, v226
	v_and_b32_e32 v193, 15, v226
	v_lshlrev_b32_e32 v9, 4, v133
	s_and_b32 s14, s6, 0x60
	v_and_b32_e32 v200, 0x3c0, v11
	v_lshl_or_b32 v132, s7, 6, v193
	v_lshl_or_b32 v194, v193, 6, v9
	s_lshl_b32 s7, s7, 13
	v_and_b32_e32 v199, 32, v125
	v_or_b32_e32 v11, v9, v200
	s_lshl_b32 s6, s14, 7
	v_bitop3_b32 v10, v194, s7, v199 bitop3:0xde
	v_bitop3_b32 v196, v9, v199, v200 bitop3:0x36
	v_bitop3_b32 v9, s6, v11, v199 bitop3:0xf6
	s_mov_b64 s[6:7], 0x80
	s_add_i32 m0, s16, 0x18000
	v_lshl_add_u64 v[6:7], v[6:7], 0, s[6:7]
	s_waitcnt vmcnt(2)
	s_barrier
	global_load_lds_dwordx4 v[6:7], off
	v_lshl_add_u64 v[4:5], v[4:5], 0, s[6:7]
	s_add_i32 m0, s16, 0x1a000
	s_add_i32 s20, s16, 0x8000
	s_add_i32 s21, s16, 0xa000
	global_load_lds_dwordx4 v[4:5], off
	v_lshl_add_u64 v[2:3], v[2:3], 0, s[6:7]
	s_mov_b32 m0, s20
	s_add_u32 s22, s2, 0x40080
	global_load_lds_dwordx4 v[2:3], off
	v_lshl_add_u64 v[0:1], v[0:1], 0, s[6:7]
	s_mov_b32 m0, s21
	s_addc_u32 s23, s3, 0
	global_load_lds_dwordx4 v[0:1], off
	s_add_i32 m0, s16, 0x1c000
	v_lshl_add_u64 v[0:1], s[22:23], 0, v[156:157]
	global_load_lds_dwordx4 v[0:1], off
	v_lshl_add_u64 v[0:1], s[22:23], 0, v[152:153]
	s_add_i32 m0, s16, 0x1e000
	v_lshrrev_b32_e32 v195, 7, v226
	global_load_lds_dwordx4 v[0:1], off
	v_lshlrev_b32_e32 v0, 15, v195
	v_lshlrev_b32_e32 v1, 11, v186
	v_readlane_b32 s48, v254, 0
	v_or3_b32 v0, v184, v0, v1
	v_readlane_b32 s50, v254, 2
	v_lshrrev_b32_e32 v197, 11, v8
	v_add_u32_e32 v160, v0, v185
	v_readlane_b32 s51, v254, 3
	s_add_u32 s10, s50, s10
	v_lshlrev_b32_e32 v0, 15, v197
	s_waitcnt vmcnt(6)
	s_addc_u32 s11, s51, s11
	v_or3_b32 v0, v184, v0, v1
	s_add_i32 s36, 0, 0x10000
	s_add_i32 s37, 0, 0x14000
	s_add_i32 s45, 0, 0x18000
	s_add_i32 s46, 0, 0x1c000
	v_mov_b32_e32 v161, v157
	v_add_u32_e32 v162, v0, v185
	v_mov_b32_e32 v163, v157
	s_add_i32 s30, s36, s12
	s_add_i32 s33, s37, s12
	s_add_i32 s35, s45, s12
	s_add_i32 s47, s46, s12
	s_mov_b64 s[8:9], 0x40080
	v_lshl_add_u64 v[128:129], s[10:11], 0, v[160:161]
	v_lshl_add_u64 v[130:131], s[10:11], 0, v[162:163]
	s_mov_b32 s22, -2
	v_add_u32_e32 v134, s36, v9
	v_add_u32_e32 v135, s37, v9
	v_add_u32_e32 v136, 0, v10
	s_add_i32 s23, s16, 0xc000
	s_add_i32 s29, s16, 0xe000
	s_add_i32 s31, s30, 0x2000
	s_add_i32 s34, s33, 0x2000
	v_add_u32_e32 v137, s45, v9
	v_add_u32_e32 v138, s46, v9
	s_add_i32 s41, s35, 0x2000
	s_add_i32 s48, s47, 0x2000
	s_barrier
	v_readlane_b32 s49, v254, 1
	ds_read_b128 v[140:143], v134
	ds_read_b128 v[144:147], v134 offset:1024
	ds_read_b128 v[148:151], v134 offset:2048
	ds_read_b128 v[164:167], v134 offset:3072
	ds_read_b128 v[168:171], v135
	ds_read_b128 v[172:175], v135 offset:1024
	ds_read_b128 v[176:179], v135 offset:2048
	ds_read_b128 v[206:209], v135 offset:3072
	s_add_u32 s10, s8, 0xfffc0080
	s_addc_u32 s11, s9, -1
	s_cmp_lg_u32 s22, 12
	s_cselect_b32 s10, s10, 0
	s_cselect_b32 s11, s11, 0
	s_add_u32 s12, s4, s10
	s_addc_u32 s13, s5, s11
	s_add_u32 s10, s2, s10
	s_addc_u32 s11, s3, s11
	s_mov_b32 m0, s23
	v_lshl_add_u64 v[180:181], v[128:129], 0, s[8:9]
	ds_read_b128 v[210:213], v136
	ds_read_b128 v[214:217], v136 offset:1024
	ds_read_b128 v[218:221], v136 offset:2048
	ds_read_b128 v[222:225], v136 offset:3072
	ds_read_b128 v[232:235], v136 offset:4096
	ds_read_b128 v[236:239], v136 offset:5120
	ds_read_b128 v[240:243], v136 offset:6144
	ds_read_b128 v[244:247], v136 offset:7168
	global_load_lds_dwordx4 v[180:181], off
	v_lshl_add_u64 v[180:181], v[130:131], 0, s[8:9]
	s_mov_b32 m0, s29
	s_nop 0
	global_load_lds_dwordx4 v[180:181], off
	s_waitcnt vmcnt(8)
	s_waitcnt lgkmcnt(0)
	s_barrier
	s_setprio 1
	v_mfma_f32_16x16x32_bf16 v[124:127], v[140:143], v[210:213], 0
	v_mfma_f32_16x16x32_bf16 v[120:123], v[148:151], v[210:213], 0
	v_mfma_f32_16x16x32_bf16 v[108:111], v[140:143], v[218:221], 0
	v_mfma_f32_16x16x32_bf16 v[104:107], v[148:151], v[218:221], 0
	v_mfma_f32_16x16x32_bf16 v[92:95], v[140:143], v[232:235], 0
	v_mfma_f32_16x16x32_bf16 v[88:91], v[148:151], v[232:235], 0
	v_mfma_f32_16x16x32_bf16 v[76:79], v[140:143], v[240:243], 0
	v_mfma_f32_16x16x32_bf16 v[72:75], v[148:151], v[240:243], 0
	v_mfma_f32_16x16x32_bf16 v[124:127], v[144:147], v[214:217], v[124:127]
	v_mfma_f32_16x16x32_bf16 v[120:123], v[164:167], v[214:217], v[120:123]
	v_mfma_f32_16x16x32_bf16 v[108:111], v[144:147], v[222:225], v[108:111]
	v_mfma_f32_16x16x32_bf16 v[104:107], v[164:167], v[222:225], v[104:107]
	v_mfma_f32_16x16x32_bf16 v[92:95], v[144:147], v[236:239], v[92:95]
	v_mfma_f32_16x16x32_bf16 v[88:91], v[164:167], v[236:239], v[88:91]
	v_mfma_f32_16x16x32_bf16 v[76:79], v[144:147], v[244:247], v[76:79]
	v_mfma_f32_16x16x32_bf16 v[72:75], v[164:167], v[244:247], v[72:75]
	s_setprio 0
	s_setprio 1
	v_mfma_f32_16x16x32_bf16 v[116:119], v[168:171], v[210:213], 0
	v_mfma_f32_16x16x32_bf16 v[112:115], v[176:179], v[210:213], 0
	v_mfma_f32_16x16x32_bf16 v[100:103], v[168:171], v[218:221], 0
	v_mfma_f32_16x16x32_bf16 v[96:99], v[176:179], v[218:221], 0
	v_mfma_f32_16x16x32_bf16 v[84:87], v[168:171], v[232:235], 0
	v_mfma_f32_16x16x32_bf16 v[80:83], v[176:179], v[232:235], 0
	v_mfma_f32_16x16x32_bf16 v[68:71], v[168:171], v[240:243], 0
	v_mfma_f32_16x16x32_bf16 v[64:67], v[176:179], v[240:243], 0
	v_mfma_f32_16x16x32_bf16 v[116:119], v[172:175], v[214:217], v[116:119]
	v_mfma_f32_16x16x32_bf16 v[112:115], v[206:209], v[214:217], v[112:115]
	v_mfma_f32_16x16x32_bf16 v[100:103], v[172:175], v[222:225], v[100:103]
	v_mfma_f32_16x16x32_bf16 v[96:99], v[206:209], v[222:225], v[96:99]
	v_mfma_f32_16x16x32_bf16 v[84:87], v[172:175], v[236:239], v[84:87]
	v_mfma_f32_16x16x32_bf16 v[80:83], v[206:209], v[236:239], v[80:83]
	v_mfma_f32_16x16x32_bf16 v[68:71], v[172:175], v[244:247], v[68:71]
	v_mfma_f32_16x16x32_bf16 v[64:67], v[206:209], v[244:247], v[64:67]
	s_setprio 0
	s_barrier
	s_mov_b32 m0, s30
	v_lshl_add_u64 v[180:181], s[10:11], 0, v[156:157]
	s_add_u32 s50, s10, 0x40000
	ds_read_b128 v[210:213], v136 offset:16384
	ds_read_b128 v[214:217], v136 offset:17408
	ds_read_b128 v[218:221], v136 offset:18432
	ds_read_b128 v[222:225], v136 offset:19456
	ds_read_b128 v[232:235], v136 offset:20480
	ds_read_b128 v[236:239], v136 offset:21504
	ds_read_b128 v[240:243], v136 offset:22528
	ds_read_b128 v[244:247], v136 offset:23552
	global_load_lds_dwordx4 v[180:181], off
	v_lshl_add_u64 v[202:203], s[10:11], 0, v[152:153]
	s_mov_b32 m0, s31
	s_addc_u32 s51, s11, 0
	global_load_lds_dwordx4 v[202:203], off
	v_lshl_add_u64 v[248:249], s[50:51], 0, v[156:157]
	s_mov_b32 m0, s33
	v_lshl_add_u64 v[250:251], s[12:13], 0, v[154:155]
	global_load_lds_dwordx4 v[248:249], off
	v_lshl_add_u64 v[248:249], s[50:51], 0, v[152:153]
	s_mov_b32 m0, s34
	s_nop 0
	global_load_lds_dwordx4 v[248:249], off
	v_lshl_add_u64 v[248:249], s[12:13], 0, v[158:159]
	s_mov_b32 m0, s16
	s_nop 0
	global_load_lds_dwordx4 v[248:249], off
	s_mov_b32 m0, s17
	s_nop 0
	global_load_lds_dwordx4 v[250:251], off
	s_waitcnt vmcnt(8)
	s_waitcnt lgkmcnt(0)
	s_barrier
	s_setprio 1
	v_mfma_f32_16x16x32_bf16 v[60:63], v[140:143], v[210:213], 0
	v_mfma_f32_16x16x32_bf16 v[56:59], v[148:151], v[210:213], 0
	v_mfma_f32_16x16x32_bf16 v[44:47], v[140:143], v[218:221], 0
	v_mfma_f32_16x16x32_bf16 v[40:43], v[148:151], v[218:221], 0
	v_mfma_f32_16x16x32_bf16 v[28:31], v[140:143], v[232:235], 0
	v_mfma_f32_16x16x32_bf16 v[24:27], v[148:151], v[232:235], 0
	v_mfma_f32_16x16x32_bf16 v[12:15], v[140:143], v[240:243], 0
	v_mfma_f32_16x16x32_bf16 v[8:11], v[148:151], v[240:243], 0
	v_mfma_f32_16x16x32_bf16 v[60:63], v[144:147], v[214:217], v[60:63]
	v_mfma_f32_16x16x32_bf16 v[56:59], v[164:167], v[214:217], v[56:59]
	v_mfma_f32_16x16x32_bf16 v[44:47], v[144:147], v[222:225], v[44:47]
	v_mfma_f32_16x16x32_bf16 v[40:43], v[164:167], v[222:225], v[40:43]
	v_mfma_f32_16x16x32_bf16 v[28:31], v[144:147], v[236:239], v[28:31]
	v_mfma_f32_16x16x32_bf16 v[24:27], v[164:167], v[236:239], v[24:27]
	v_mfma_f32_16x16x32_bf16 v[12:15], v[144:147], v[244:247], v[12:15]
	v_mfma_f32_16x16x32_bf16 v[8:11], v[164:167], v[244:247], v[8:11]
	s_setprio 0
	s_setprio 1
	v_mfma_f32_16x16x32_bf16 v[52:55], v[168:171], v[210:213], 0
	v_mfma_f32_16x16x32_bf16 v[48:51], v[176:179], v[210:213], 0
	v_mfma_f32_16x16x32_bf16 v[36:39], v[168:171], v[218:221], 0
	v_mfma_f32_16x16x32_bf16 v[32:35], v[176:179], v[218:221], 0
	v_mfma_f32_16x16x32_bf16 v[20:23], v[168:171], v[232:235], 0
	v_mfma_f32_16x16x32_bf16 v[16:19], v[176:179], v[232:235], 0
	v_mfma_f32_16x16x32_bf16 v[4:7], v[168:171], v[240:243], 0
	v_mfma_f32_16x16x32_bf16 v[0:3], v[176:179], v[240:243], 0
	v_mfma_f32_16x16x32_bf16 v[52:55], v[172:175], v[214:217], v[52:55]
	v_mfma_f32_16x16x32_bf16 v[48:51], v[206:209], v[214:217], v[48:51]
	v_mfma_f32_16x16x32_bf16 v[36:39], v[172:175], v[222:225], v[36:39]
	v_mfma_f32_16x16x32_bf16 v[32:35], v[206:209], v[222:225], v[32:35]
	v_mfma_f32_16x16x32_bf16 v[20:23], v[172:175], v[236:239], v[20:23]
	v_mfma_f32_16x16x32_bf16 v[16:19], v[206:209], v[236:239], v[16:19]
	v_mfma_f32_16x16x32_bf16 v[4:7], v[172:175], v[244:247], v[4:7]
	v_mfma_f32_16x16x32_bf16 v[0:3], v[206:209], v[244:247], v[0:3]
	s_setprio 0
	s_barrier
	ds_read_b128 v[140:143], v137
	ds_read_b128 v[144:147], v137 offset:1024
	ds_read_b128 v[148:151], v137 offset:2048
	ds_read_b128 v[164:167], v137 offset:3072
	ds_read_b128 v[168:171], v138
	ds_read_b128 v[172:175], v138 offset:1024
	ds_read_b128 v[176:179], v138 offset:2048
	ds_read_b128 v[206:209], v138 offset:3072
	s_add_u32 s12, s12, 0x40000
	s_addc_u32 s13, s13, 0
	s_mov_b32 m0, s18
	v_lshl_add_u64 v[252:253], s[12:13], 0, v[158:159]
	ds_read_b128 v[210:213], v136 offset:32768
	ds_read_b128 v[214:217], v136 offset:33792
	ds_read_b128 v[218:221], v136 offset:34816
	ds_read_b128 v[222:225], v136 offset:35840
	ds_read_b128 v[232:235], v136 offset:36864
	ds_read_b128 v[236:239], v136 offset:37888
	ds_read_b128 v[240:243], v136 offset:38912
	ds_read_b128 v[244:247], v136 offset:39936
	global_load_lds_dwordx4 v[252:253], off
	v_lshl_add_u64 v[252:253], s[12:13], 0, v[154:155]
	s_mov_b32 m0, s19
	s_nop 0
	global_load_lds_dwordx4 v[252:253], off
	s_waitcnt vmcnt(8)
	s_waitcnt lgkmcnt(0)
	s_barrier
	s_setprio 1
	v_mfma_f32_16x16x32_bf16 v[124:127], v[140:143], v[210:213], v[124:127]
	v_mfma_f32_16x16x32_bf16 v[120:123], v[148:151], v[210:213], v[120:123]
	v_mfma_f32_16x16x32_bf16 v[108:111], v[140:143], v[218:221], v[108:111]
	v_mfma_f32_16x16x32_bf16 v[104:107], v[148:151], v[218:221], v[104:107]
	v_mfma_f32_16x16x32_bf16 v[92:95], v[140:143], v[232:235], v[92:95]
	v_mfma_f32_16x16x32_bf16 v[88:91], v[148:151], v[232:235], v[88:91]
	v_mfma_f32_16x16x32_bf16 v[76:79], v[140:143], v[240:243], v[76:79]
	v_mfma_f32_16x16x32_bf16 v[72:75], v[148:151], v[240:243], v[72:75]
	v_mfma_f32_16x16x32_bf16 v[124:127], v[144:147], v[214:217], v[124:127]
	v_mfma_f32_16x16x32_bf16 v[120:123], v[164:167], v[214:217], v[120:123]
	v_mfma_f32_16x16x32_bf16 v[108:111], v[144:147], v[222:225], v[108:111]
	v_mfma_f32_16x16x32_bf16 v[104:107], v[164:167], v[222:225], v[104:107]
	v_mfma_f32_16x16x32_bf16 v[92:95], v[144:147], v[236:239], v[92:95]
	v_mfma_f32_16x16x32_bf16 v[88:91], v[164:167], v[236:239], v[88:91]
	v_mfma_f32_16x16x32_bf16 v[76:79], v[144:147], v[244:247], v[76:79]
	v_mfma_f32_16x16x32_bf16 v[72:75], v[164:167], v[244:247], v[72:75]
	s_setprio 0
	s_setprio 1
	v_mfma_f32_16x16x32_bf16 v[116:119], v[168:171], v[210:213], v[116:119]
	v_mfma_f32_16x16x32_bf16 v[112:115], v[176:179], v[210:213], v[112:115]
	v_mfma_f32_16x16x32_bf16 v[100:103], v[168:171], v[218:221], v[100:103]
	v_mfma_f32_16x16x32_bf16 v[96:99], v[176:179], v[218:221], v[96:99]
	v_mfma_f32_16x16x32_bf16 v[84:87], v[168:171], v[232:235], v[84:87]
	v_mfma_f32_16x16x32_bf16 v[80:83], v[176:179], v[232:235], v[80:83]
	v_mfma_f32_16x16x32_bf16 v[68:71], v[168:171], v[240:243], v[68:71]
	v_mfma_f32_16x16x32_bf16 v[64:67], v[176:179], v[240:243], v[64:67]
	v_mfma_f32_16x16x32_bf16 v[116:119], v[172:175], v[214:217], v[116:119]
	v_mfma_f32_16x16x32_bf16 v[112:115], v[206:209], v[214:217], v[112:115]
	v_mfma_f32_16x16x32_bf16 v[100:103], v[172:175], v[222:225], v[100:103]
	v_mfma_f32_16x16x32_bf16 v[96:99], v[206:209], v[222:225], v[96:99]
	v_mfma_f32_16x16x32_bf16 v[84:87], v[172:175], v[236:239], v[84:87]
	v_mfma_f32_16x16x32_bf16 v[80:83], v[206:209], v[236:239], v[80:83]
	v_mfma_f32_16x16x32_bf16 v[68:71], v[172:175], v[244:247], v[68:71]
	v_mfma_f32_16x16x32_bf16 v[64:67], v[206:209], v[244:247], v[64:67]
	s_setprio 0
	s_barrier
	s_mov_b32 m0, s35
	v_lshl_add_u64 v[180:181], v[180:181], 0, s[6:7]
	s_add_u32 s10, s10, 0x40080
	ds_read_b128 v[210:213], v136 offset:49152
	ds_read_b128 v[214:217], v136 offset:50176
	ds_read_b128 v[218:221], v136 offset:51200
	ds_read_b128 v[222:225], v136 offset:52224
	ds_read_b128 v[232:235], v136 offset:53248
	ds_read_b128 v[236:239], v136 offset:54272
	ds_read_b128 v[240:243], v136 offset:55296
	ds_read_b128 v[244:247], v136 offset:56320
	global_load_lds_dwordx4 v[180:181], off
	v_lshl_add_u64 v[180:181], v[202:203], 0, s[6:7]
	s_mov_b32 m0, s41
	s_addc_u32 s11, s11, 0
	global_load_lds_dwordx4 v[180:181], off
	v_lshl_add_u64 v[180:181], s[10:11], 0, v[156:157]
	s_mov_b32 m0, s47
	s_nop 0
	global_load_lds_dwordx4 v[180:181], off
	v_lshl_add_u64 v[180:181], s[10:11], 0, v[152:153]
	s_mov_b32 m0, s48
	s_nop 0
	global_load_lds_dwordx4 v[180:181], off
	v_lshl_add_u64 v[180:181], v[248:249], 0, s[6:7]
	s_mov_b32 m0, s20
	s_nop 0
	global_load_lds_dwordx4 v[180:181], off
	v_lshl_add_u64 v[180:181], v[250:251], 0, s[6:7]
	s_mov_b32 m0, s21
	s_nop 0
	global_load_lds_dwordx4 v[180:181], off
	s_waitcnt vmcnt(8)
	s_waitcnt lgkmcnt(0)
	s_barrier
	s_setprio 1
	v_mfma_f32_16x16x32_bf16 v[60:63], v[140:143], v[210:213], v[60:63]
	v_mfma_f32_16x16x32_bf16 v[56:59], v[148:151], v[210:213], v[56:59]
	v_mfma_f32_16x16x32_bf16 v[44:47], v[140:143], v[218:221], v[44:47]
	v_mfma_f32_16x16x32_bf16 v[40:43], v[148:151], v[218:221], v[40:43]
	v_mfma_f32_16x16x32_bf16 v[28:31], v[140:143], v[232:235], v[28:31]
	v_mfma_f32_16x16x32_bf16 v[24:27], v[148:151], v[232:235], v[24:27]
	v_mfma_f32_16x16x32_bf16 v[12:15], v[140:143], v[240:243], v[12:15]
	v_mfma_f32_16x16x32_bf16 v[8:11], v[148:151], v[240:243], v[8:11]
	v_mfma_f32_16x16x32_bf16 v[60:63], v[144:147], v[214:217], v[60:63]
	v_mfma_f32_16x16x32_bf16 v[56:59], v[164:167], v[214:217], v[56:59]
	v_mfma_f32_16x16x32_bf16 v[44:47], v[144:147], v[222:225], v[44:47]
	v_mfma_f32_16x16x32_bf16 v[40:43], v[164:167], v[222:225], v[40:43]
	v_mfma_f32_16x16x32_bf16 v[28:31], v[144:147], v[236:239], v[28:31]
	v_mfma_f32_16x16x32_bf16 v[24:27], v[164:167], v[236:239], v[24:27]
	v_mfma_f32_16x16x32_bf16 v[12:15], v[144:147], v[244:247], v[12:15]
	v_mfma_f32_16x16x32_bf16 v[8:11], v[164:167], v[244:247], v[8:11]
	s_setprio 0
	s_setprio 1
	v_mfma_f32_16x16x32_bf16 v[52:55], v[168:171], v[210:213], v[52:55]
	v_mfma_f32_16x16x32_bf16 v[48:51], v[176:179], v[210:213], v[48:51]
	v_mfma_f32_16x16x32_bf16 v[36:39], v[168:171], v[218:221], v[36:39]
	v_mfma_f32_16x16x32_bf16 v[32:35], v[176:179], v[218:221], v[32:35]
	v_mfma_f32_16x16x32_bf16 v[20:23], v[168:171], v[232:235], v[20:23]
	v_mfma_f32_16x16x32_bf16 v[16:19], v[176:179], v[232:235], v[16:19]
	v_mfma_f32_16x16x32_bf16 v[4:7], v[168:171], v[240:243], v[4:7]
	v_mfma_f32_16x16x32_bf16 v[0:3], v[176:179], v[240:243], v[0:3]
	v_mfma_f32_16x16x32_bf16 v[52:55], v[172:175], v[214:217], v[52:55]
	v_mfma_f32_16x16x32_bf16 v[48:51], v[206:209], v[214:217], v[48:51]
	v_mfma_f32_16x16x32_bf16 v[36:39], v[172:175], v[222:225], v[36:39]
	v_mfma_f32_16x16x32_bf16 v[32:35], v[206:209], v[222:225], v[32:35]
	v_mfma_f32_16x16x32_bf16 v[20:23], v[172:175], v[236:239], v[20:23]
	v_mfma_f32_16x16x32_bf16 v[16:19], v[206:209], v[236:239], v[16:19]
	v_mfma_f32_16x16x32_bf16 v[4:7], v[172:175], v[244:247], v[4:7]
	v_mfma_f32_16x16x32_bf16 v[0:3], v[206:209], v[244:247], v[0:3]
	s_setprio 0
	s_barrier
	s_add_i32 s22, s22, 2
	s_add_u32 s8, s8, 0x100
	s_addc_u32 s9, s9, 0
	s_cmp_gt_u32 s22, 13
.LBB0_611:
	ds_read_b128 v[140:143], v134
	ds_read_b128 v[144:147], v134 offset:1024
	ds_read_b128 v[148:151], v134 offset:2048
	ds_read_b128 v[164:167], v134 offset:3072
	ds_read_b128 v[168:171], v135
	ds_read_b128 v[172:175], v135 offset:1024
	ds_read_b128 v[176:179], v135 offset:2048
	ds_read_b128 v[206:209], v135 offset:3072
	s_add_u32 s10, s8, 0xfffc0080
	s_addc_u32 s11, s9, -1
	s_cmp_lg_u32 s22, 12
	s_cselect_b32 s10, s10, 0
	s_cselect_b32 s11, s11, 0
	s_add_u32 s12, s4, s10
	s_addc_u32 s13, s5, s11
	s_add_u32 s10, s2, s10
	s_addc_u32 s11, s3, s11
	s_mov_b32 m0, s23
	v_lshl_add_u64 v[180:181], v[128:129], 0, s[8:9]
	ds_read_b128 v[210:213], v136
	ds_read_b128 v[214:217], v136 offset:1024
	ds_read_b128 v[218:221], v136 offset:2048
	ds_read_b128 v[222:225], v136 offset:3072
	ds_read_b128 v[232:235], v136 offset:4096
	ds_read_b128 v[236:239], v136 offset:5120
	ds_read_b128 v[240:243], v136 offset:6144
	ds_read_b128 v[244:247], v136 offset:7168
	global_load_lds_dwordx4 v[180:181], off
	v_lshl_add_u64 v[180:181], v[130:131], 0, s[8:9]
	s_mov_b32 m0, s29
	s_nop 0
	global_load_lds_dwordx4 v[180:181], off
	s_waitcnt vmcnt(8)
	s_waitcnt lgkmcnt(0)
	s_barrier
	s_setprio 1
	v_mfma_f32_16x16x32_bf16 v[124:127], v[140:143], v[210:213], v[124:127]
	v_mfma_f32_16x16x32_bf16 v[120:123], v[148:151], v[210:213], v[120:123]
	v_mfma_f32_16x16x32_bf16 v[108:111], v[140:143], v[218:221], v[108:111]
	v_mfma_f32_16x16x32_bf16 v[104:107], v[148:151], v[218:221], v[104:107]
	v_mfma_f32_16x16x32_bf16 v[92:95], v[140:143], v[232:235], v[92:95]
	v_mfma_f32_16x16x32_bf16 v[88:91], v[148:151], v[232:235], v[88:91]
	v_mfma_f32_16x16x32_bf16 v[76:79], v[140:143], v[240:243], v[76:79]
	v_mfma_f32_16x16x32_bf16 v[72:75], v[148:151], v[240:243], v[72:75]
	v_mfma_f32_16x16x32_bf16 v[124:127], v[144:147], v[214:217], v[124:127]
	v_mfma_f32_16x16x32_bf16 v[120:123], v[164:167], v[214:217], v[120:123]
	v_mfma_f32_16x16x32_bf16 v[108:111], v[144:147], v[222:225], v[108:111]
	v_mfma_f32_16x16x32_bf16 v[104:107], v[164:167], v[222:225], v[104:107]
	v_mfma_f32_16x16x32_bf16 v[92:95], v[144:147], v[236:239], v[92:95]
	v_mfma_f32_16x16x32_bf16 v[88:91], v[164:167], v[236:239], v[88:91]
	v_mfma_f32_16x16x32_bf16 v[76:79], v[144:147], v[244:247], v[76:79]
	v_mfma_f32_16x16x32_bf16 v[72:75], v[164:167], v[244:247], v[72:75]
	s_setprio 0
	s_setprio 1
	v_mfma_f32_16x16x32_bf16 v[116:119], v[168:171], v[210:213], v[116:119]
	v_mfma_f32_16x16x32_bf16 v[112:115], v[176:179], v[210:213], v[112:115]
	v_mfma_f32_16x16x32_bf16 v[100:103], v[168:171], v[218:221], v[100:103]
	v_mfma_f32_16x16x32_bf16 v[96:99], v[176:179], v[218:221], v[96:99]
	v_mfma_f32_16x16x32_bf16 v[84:87], v[168:171], v[232:235], v[84:87]
	v_mfma_f32_16x16x32_bf16 v[80:83], v[176:179], v[232:235], v[80:83]
	v_mfma_f32_16x16x32_bf16 v[68:71], v[168:171], v[240:243], v[68:71]
	v_mfma_f32_16x16x32_bf16 v[64:67], v[176:179], v[240:243], v[64:67]
	v_mfma_f32_16x16x32_bf16 v[116:119], v[172:175], v[214:217], v[116:119]
	v_mfma_f32_16x16x32_bf16 v[112:115], v[206:209], v[214:217], v[112:115]
	v_mfma_f32_16x16x32_bf16 v[100:103], v[172:175], v[222:225], v[100:103]
	v_mfma_f32_16x16x32_bf16 v[96:99], v[206:209], v[222:225], v[96:99]
	v_mfma_f32_16x16x32_bf16 v[84:87], v[172:175], v[236:239], v[84:87]
	v_mfma_f32_16x16x32_bf16 v[80:83], v[206:209], v[236:239], v[80:83]
	v_mfma_f32_16x16x32_bf16 v[68:71], v[172:175], v[244:247], v[68:71]
	v_mfma_f32_16x16x32_bf16 v[64:67], v[206:209], v[244:247], v[64:67]
	s_setprio 0
	s_barrier
	s_mov_b32 m0, s30
	v_lshl_add_u64 v[180:181], s[10:11], 0, v[156:157]
	s_add_u32 s50, s10, 0x40000
	ds_read_b128 v[210:213], v136 offset:16384
	ds_read_b128 v[214:217], v136 offset:17408
	ds_read_b128 v[218:221], v136 offset:18432
	ds_read_b128 v[222:225], v136 offset:19456
	ds_read_b128 v[232:235], v136 offset:20480
	ds_read_b128 v[236:239], v136 offset:21504
	ds_read_b128 v[240:243], v136 offset:22528
	ds_read_b128 v[244:247], v136 offset:23552
	global_load_lds_dwordx4 v[180:181], off
	v_lshl_add_u64 v[202:203], s[10:11], 0, v[152:153]
	s_mov_b32 m0, s31
	s_addc_u32 s51, s11, 0
	global_load_lds_dwordx4 v[202:203], off
	v_lshl_add_u64 v[248:249], s[50:51], 0, v[156:157]
	s_mov_b32 m0, s33
	v_lshl_add_u64 v[250:251], s[12:13], 0, v[154:155]
	global_load_lds_dwordx4 v[248:249], off
	v_lshl_add_u64 v[248:249], s[50:51], 0, v[152:153]
	s_mov_b32 m0, s34
	s_nop 0
	global_load_lds_dwordx4 v[248:249], off
	v_lshl_add_u64 v[248:249], s[12:13], 0, v[158:159]
	s_mov_b32 m0, s16
	s_nop 0
	global_load_lds_dwordx4 v[248:249], off
	s_mov_b32 m0, s17
	s_nop 0
	global_load_lds_dwordx4 v[250:251], off
	s_waitcnt vmcnt(8)
	s_waitcnt lgkmcnt(0)
	s_barrier
	s_setprio 1
	v_mfma_f32_16x16x32_bf16 v[60:63], v[140:143], v[210:213], v[60:63]
	v_mfma_f32_16x16x32_bf16 v[56:59], v[148:151], v[210:213], v[56:59]
	v_mfma_f32_16x16x32_bf16 v[44:47], v[140:143], v[218:221], v[44:47]
	v_mfma_f32_16x16x32_bf16 v[40:43], v[148:151], v[218:221], v[40:43]
	v_mfma_f32_16x16x32_bf16 v[28:31], v[140:143], v[232:235], v[28:31]
	v_mfma_f32_16x16x32_bf16 v[24:27], v[148:151], v[232:235], v[24:27]
	v_mfma_f32_16x16x32_bf16 v[12:15], v[140:143], v[240:243], v[12:15]
	v_mfma_f32_16x16x32_bf16 v[8:11], v[148:151], v[240:243], v[8:11]
	v_mfma_f32_16x16x32_bf16 v[60:63], v[144:147], v[214:217], v[60:63]
	v_mfma_f32_16x16x32_bf16 v[56:59], v[164:167], v[214:217], v[56:59]
	v_mfma_f32_16x16x32_bf16 v[44:47], v[144:147], v[222:225], v[44:47]
	v_mfma_f32_16x16x32_bf16 v[40:43], v[164:167], v[222:225], v[40:43]
	v_mfma_f32_16x16x32_bf16 v[28:31], v[144:147], v[236:239], v[28:31]
	v_mfma_f32_16x16x32_bf16 v[24:27], v[164:167], v[236:239], v[24:27]
	v_mfma_f32_16x16x32_bf16 v[12:15], v[144:147], v[244:247], v[12:15]
	v_mfma_f32_16x16x32_bf16 v[8:11], v[164:167], v[244:247], v[8:11]
	s_setprio 0
	s_setprio 1
	v_mfma_f32_16x16x32_bf16 v[52:55], v[168:171], v[210:213], v[52:55]
	v_mfma_f32_16x16x32_bf16 v[48:51], v[176:179], v[210:213], v[48:51]
	v_mfma_f32_16x16x32_bf16 v[36:39], v[168:171], v[218:221], v[36:39]
	v_mfma_f32_16x16x32_bf16 v[32:35], v[176:179], v[218:221], v[32:35]
	v_mfma_f32_16x16x32_bf16 v[20:23], v[168:171], v[232:235], v[20:23]
	v_mfma_f32_16x16x32_bf16 v[16:19], v[176:179], v[232:235], v[16:19]
	v_mfma_f32_16x16x32_bf16 v[4:7], v[168:171], v[240:243], v[4:7]
	v_mfma_f32_16x16x32_bf16 v[0:3], v[176:179], v[240:243], v[0:3]
	v_mfma_f32_16x16x32_bf16 v[52:55], v[172:175], v[214:217], v[52:55]
	v_mfma_f32_16x16x32_bf16 v[48:51], v[206:209], v[214:217], v[48:51]
	v_mfma_f32_16x16x32_bf16 v[36:39], v[172:175], v[222:225], v[36:39]
	v_mfma_f32_16x16x32_bf16 v[32:35], v[206:209], v[222:225], v[32:35]
	v_mfma_f32_16x16x32_bf16 v[20:23], v[172:175], v[236:239], v[20:23]
	v_mfma_f32_16x16x32_bf16 v[16:19], v[206:209], v[236:239], v[16:19]
	v_mfma_f32_16x16x32_bf16 v[4:7], v[172:175], v[244:247], v[4:7]
	v_mfma_f32_16x16x32_bf16 v[0:3], v[206:209], v[244:247], v[0:3]
	s_setprio 0
	s_barrier
	ds_read_b128 v[140:143], v137
	ds_read_b128 v[144:147], v137 offset:1024
	ds_read_b128 v[148:151], v137 offset:2048
	ds_read_b128 v[164:167], v137 offset:3072
	ds_read_b128 v[168:171], v138
	ds_read_b128 v[172:175], v138 offset:1024
	ds_read_b128 v[176:179], v138 offset:2048
	ds_read_b128 v[206:209], v138 offset:3072
	s_add_u32 s12, s12, 0x40000
	s_addc_u32 s13, s13, 0
	s_mov_b32 m0, s18
	v_lshl_add_u64 v[252:253], s[12:13], 0, v[158:159]
	ds_read_b128 v[210:213], v136 offset:32768
	ds_read_b128 v[214:217], v136 offset:33792
	ds_read_b128 v[218:221], v136 offset:34816
	ds_read_b128 v[222:225], v136 offset:35840
	ds_read_b128 v[232:235], v136 offset:36864
	ds_read_b128 v[236:239], v136 offset:37888
	ds_read_b128 v[240:243], v136 offset:38912
	ds_read_b128 v[244:247], v136 offset:39936
	global_load_lds_dwordx4 v[252:253], off
	v_lshl_add_u64 v[252:253], s[12:13], 0, v[154:155]
	s_mov_b32 m0, s19
	s_nop 0
	global_load_lds_dwordx4 v[252:253], off
	s_waitcnt vmcnt(8)
	s_waitcnt lgkmcnt(0)
	s_barrier
	s_setprio 1
	v_mfma_f32_16x16x32_bf16 v[124:127], v[140:143], v[210:213], v[124:127]
	v_mfma_f32_16x16x32_bf16 v[120:123], v[148:151], v[210:213], v[120:123]
	v_mfma_f32_16x16x32_bf16 v[108:111], v[140:143], v[218:221], v[108:111]
	v_mfma_f32_16x16x32_bf16 v[104:107], v[148:151], v[218:221], v[104:107]
	v_mfma_f32_16x16x32_bf16 v[92:95], v[140:143], v[232:235], v[92:95]
	v_mfma_f32_16x16x32_bf16 v[88:91], v[148:151], v[232:235], v[88:91]
	v_mfma_f32_16x16x32_bf16 v[76:79], v[140:143], v[240:243], v[76:79]
	v_mfma_f32_16x16x32_bf16 v[72:75], v[148:151], v[240:243], v[72:75]
	v_mfma_f32_16x16x32_bf16 v[124:127], v[144:147], v[214:217], v[124:127]
	v_mfma_f32_16x16x32_bf16 v[120:123], v[164:167], v[214:217], v[120:123]
	v_mfma_f32_16x16x32_bf16 v[108:111], v[144:147], v[222:225], v[108:111]
	v_mfma_f32_16x16x32_bf16 v[104:107], v[164:167], v[222:225], v[104:107]
	v_mfma_f32_16x16x32_bf16 v[92:95], v[144:147], v[236:239], v[92:95]
	v_mfma_f32_16x16x32_bf16 v[88:91], v[164:167], v[236:239], v[88:91]
	v_mfma_f32_16x16x32_bf16 v[76:79], v[144:147], v[244:247], v[76:79]
	v_mfma_f32_16x16x32_bf16 v[72:75], v[164:167], v[244:247], v[72:75]
	s_setprio 0
	s_setprio 1
	v_mfma_f32_16x16x32_bf16 v[116:119], v[168:171], v[210:213], v[116:119]
	v_mfma_f32_16x16x32_bf16 v[112:115], v[176:179], v[210:213], v[112:115]
	v_mfma_f32_16x16x32_bf16 v[100:103], v[168:171], v[218:221], v[100:103]
	v_mfma_f32_16x16x32_bf16 v[96:99], v[176:179], v[218:221], v[96:99]
	v_mfma_f32_16x16x32_bf16 v[84:87], v[168:171], v[232:235], v[84:87]
	v_mfma_f32_16x16x32_bf16 v[80:83], v[176:179], v[232:235], v[80:83]
	v_mfma_f32_16x16x32_bf16 v[68:71], v[168:171], v[240:243], v[68:71]
	v_mfma_f32_16x16x32_bf16 v[64:67], v[176:179], v[240:243], v[64:67]
	v_mfma_f32_16x16x32_bf16 v[116:119], v[172:175], v[214:217], v[116:119]
	v_mfma_f32_16x16x32_bf16 v[112:115], v[206:209], v[214:217], v[112:115]
	v_mfma_f32_16x16x32_bf16 v[100:103], v[172:175], v[222:225], v[100:103]
	v_mfma_f32_16x16x32_bf16 v[96:99], v[206:209], v[222:225], v[96:99]
	v_mfma_f32_16x16x32_bf16 v[84:87], v[172:175], v[236:239], v[84:87]
	v_mfma_f32_16x16x32_bf16 v[80:83], v[206:209], v[236:239], v[80:83]
	v_mfma_f32_16x16x32_bf16 v[68:71], v[172:175], v[244:247], v[68:71]
	v_mfma_f32_16x16x32_bf16 v[64:67], v[206:209], v[244:247], v[64:67]
	s_setprio 0
	s_barrier
	s_mov_b32 m0, s35
	v_lshl_add_u64 v[180:181], v[180:181], 0, s[6:7]
	s_add_u32 s10, s10, 0x40080
	ds_read_b128 v[210:213], v136 offset:49152
	ds_read_b128 v[214:217], v136 offset:50176
	ds_read_b128 v[218:221], v136 offset:51200
	ds_read_b128 v[222:225], v136 offset:52224
	ds_read_b128 v[232:235], v136 offset:53248
	ds_read_b128 v[236:239], v136 offset:54272
	ds_read_b128 v[240:243], v136 offset:55296
	ds_read_b128 v[244:247], v136 offset:56320
	global_load_lds_dwordx4 v[180:181], off
	v_lshl_add_u64 v[180:181], v[202:203], 0, s[6:7]
	s_mov_b32 m0, s41
	s_addc_u32 s11, s11, 0
	global_load_lds_dwordx4 v[180:181], off
	v_lshl_add_u64 v[180:181], s[10:11], 0, v[156:157]
	s_mov_b32 m0, s47
	s_nop 0
	global_load_lds_dwordx4 v[180:181], off
	v_lshl_add_u64 v[180:181], s[10:11], 0, v[152:153]
	s_mov_b32 m0, s48
	s_nop 0
	global_load_lds_dwordx4 v[180:181], off
	v_lshl_add_u64 v[180:181], v[248:249], 0, s[6:7]
	s_mov_b32 m0, s20
	s_nop 0
	global_load_lds_dwordx4 v[180:181], off
	v_lshl_add_u64 v[180:181], v[250:251], 0, s[6:7]
	s_mov_b32 m0, s21
	s_nop 0
	global_load_lds_dwordx4 v[180:181], off
	s_waitcnt vmcnt(8)
	s_waitcnt lgkmcnt(0)
	s_barrier
	s_setprio 1
	v_mfma_f32_16x16x32_bf16 v[60:63], v[140:143], v[210:213], v[60:63]
	v_mfma_f32_16x16x32_bf16 v[56:59], v[148:151], v[210:213], v[56:59]
	v_mfma_f32_16x16x32_bf16 v[44:47], v[140:143], v[218:221], v[44:47]
	v_mfma_f32_16x16x32_bf16 v[40:43], v[148:151], v[218:221], v[40:43]
	v_mfma_f32_16x16x32_bf16 v[28:31], v[140:143], v[232:235], v[28:31]
	v_mfma_f32_16x16x32_bf16 v[24:27], v[148:151], v[232:235], v[24:27]
	v_mfma_f32_16x16x32_bf16 v[12:15], v[140:143], v[240:243], v[12:15]
	v_mfma_f32_16x16x32_bf16 v[8:11], v[148:151], v[240:243], v[8:11]
	v_mfma_f32_16x16x32_bf16 v[60:63], v[144:147], v[214:217], v[60:63]
	v_mfma_f32_16x16x32_bf16 v[56:59], v[164:167], v[214:217], v[56:59]
	v_mfma_f32_16x16x32_bf16 v[44:47], v[144:147], v[222:225], v[44:47]
	v_mfma_f32_16x16x32_bf16 v[40:43], v[164:167], v[222:225], v[40:43]
	v_mfma_f32_16x16x32_bf16 v[28:31], v[144:147], v[236:239], v[28:31]
	v_mfma_f32_16x16x32_bf16 v[24:27], v[164:167], v[236:239], v[24:27]
	v_mfma_f32_16x16x32_bf16 v[12:15], v[144:147], v[244:247], v[12:15]
	v_mfma_f32_16x16x32_bf16 v[8:11], v[164:167], v[244:247], v[8:11]
	s_setprio 0
	s_setprio 1
	v_mfma_f32_16x16x32_bf16 v[52:55], v[168:171], v[210:213], v[52:55]
	v_mfma_f32_16x16x32_bf16 v[48:51], v[176:179], v[210:213], v[48:51]
	v_mfma_f32_16x16x32_bf16 v[36:39], v[168:171], v[218:221], v[36:39]
	v_mfma_f32_16x16x32_bf16 v[32:35], v[176:179], v[218:221], v[32:35]
	v_mfma_f32_16x16x32_bf16 v[20:23], v[168:171], v[232:235], v[20:23]
	v_mfma_f32_16x16x32_bf16 v[16:19], v[176:179], v[232:235], v[16:19]
	v_mfma_f32_16x16x32_bf16 v[4:7], v[168:171], v[240:243], v[4:7]
	v_mfma_f32_16x16x32_bf16 v[0:3], v[176:179], v[240:243], v[0:3]
	v_mfma_f32_16x16x32_bf16 v[52:55], v[172:175], v[214:217], v[52:55]
	v_mfma_f32_16x16x32_bf16 v[48:51], v[206:209], v[214:217], v[48:51]
	v_mfma_f32_16x16x32_bf16 v[36:39], v[172:175], v[222:225], v[36:39]
	v_mfma_f32_16x16x32_bf16 v[32:35], v[206:209], v[222:225], v[32:35]
	v_mfma_f32_16x16x32_bf16 v[20:23], v[172:175], v[236:239], v[20:23]
	v_mfma_f32_16x16x32_bf16 v[16:19], v[206:209], v[236:239], v[16:19]
	v_mfma_f32_16x16x32_bf16 v[4:7], v[172:175], v[244:247], v[4:7]
	v_mfma_f32_16x16x32_bf16 v[0:3], v[206:209], v[244:247], v[0:3]
	s_setprio 0
	s_barrier
	s_add_i32 s22, s22, 2
	s_add_u32 s8, s8, 0x100
	s_addc_u32 s9, s9, 0
	s_cmp_gt_u32 s22, 13
	s_cbranch_scc0 .LBB0_611
	s_cmpk_lt_u32 s15, 0x100
	s_cbranch_scc0 .LBB0_614
	s_barrier

.LBB0_660:
	s_mov_b32 s63, s62
	s_add_i32 s62, s62, 1
	s_cmp_lt_u32 s63, 3
	s_mov_b64 s[0:1], s[18:19]
	s_cselect_b64 s[6:7], -1, 0
	s_add_i32 s18, s62, s58
	s_mov_b64 s[2:3], s[16:17]
	s_and_b64 s[16:17], s[6:7], exec
	s_mov_b32 s64, s34
	s_cselect_b32 s34, s40, s34
	s_mov_b32 s33, s30
	s_cselect_b32 s30, s18, s30
	s_ashr_i32 s35, s34, 31
	s_lshl_b64 s[16:17], s[34:35], 19
	s_add_u32 s18, s26, s16
	s_addc_u32 s19, s27, s17
	s_and_b64 s[16:17], s[6:7], exec
	s_cselect_b32 s35, s19, s1
	s_cselect_b32 s65, s18, s0
	s_ashr_i32 s31, s30, 31
	s_lshl_b64 s[16:17], s[30:31], 19
	s_add_u32 s16, s49, s16
	s_addc_u32 s17, s50, s17
	s_and_b64 s[6:7], s[6:7], exec
	s_cselect_b32 s31, s17, s3
	s_cselect_b32 s66, s16, s2
	s_add_u32 s0, s0, 0x40080
	s_addc_u32 s1, s1, 0
	s_add_u32 s67, s2, 0x100
	s_addc_u32 s68, s3, 0
	s_mov_b32 s69, -2
	ds_read_b128 v[128:131], v142
	ds_read_b128 v[132:135], v142 offset:1024
	ds_read_b128 v[148:151], v142 offset:2048
	ds_read_b128 v[164:167], v142 offset:3072
	ds_read_b128 v[168:171], v143
	ds_read_b128 v[172:175], v143 offset:1024
	ds_read_b128 v[176:179], v143 offset:2048
	ds_read_b128 v[200:203], v143 offset:3072
	s_add_u32 s2, s0, 0xfffc0080
	s_addc_u32 s3, s1, -1
	s_cmp_eq_u32 s69, 12
	s_cselect_b32 s7, s35, s3
	s_cselect_b32 s6, s65, s2
	s_cselect_b32 s3, s31, s68
	s_cselect_b32 s2, s66, s67
	v_lshl_add_u64 v[136:137], s[0:1], 0, v[160:161]
	s_add_i32 m0, s54, 0xc000
	ds_read_b128 v[206:209], v144
	ds_read_b128 v[210:213], v144 offset:1024
	ds_read_b128 v[214:217], v144 offset:2048
	ds_read_b128 v[218:221], v144 offset:3072
	ds_read_b128 v[222:225], v144 offset:4096
	ds_read_b128 v[232:235], v144 offset:5120
	ds_read_b128 v[236:239], v144 offset:6144
	ds_read_b128 v[240:243], v144 offset:7168
	global_load_lds_dwordx4 v[136:137], off
	v_lshl_add_u64 v[136:137], s[0:1], 0, v[162:163]
	s_add_i32 m0, s54, 0xe000
	s_nop 0
	global_load_lds_dwordx4 v[136:137], off
	s_waitcnt vmcnt(8)
	s_waitcnt lgkmcnt(0)
	s_barrier
	s_setprio 1
	v_mfma_f32_16x16x32_bf16 v[124:127], v[128:131], v[206:209], 0
	v_mfma_f32_16x16x32_bf16 v[120:123], v[148:151], v[206:209], 0
	v_mfma_f32_16x16x32_bf16 v[108:111], v[128:131], v[214:217], 0
	v_mfma_f32_16x16x32_bf16 v[104:107], v[148:151], v[214:217], 0
	v_mfma_f32_16x16x32_bf16 v[92:95], v[128:131], v[222:225], 0
	v_mfma_f32_16x16x32_bf16 v[88:91], v[148:151], v[222:225], 0
	v_mfma_f32_16x16x32_bf16 v[76:79], v[128:131], v[236:239], 0
	v_mfma_f32_16x16x32_bf16 v[72:75], v[148:151], v[236:239], 0
	v_mfma_f32_16x16x32_bf16 v[124:127], v[132:135], v[210:213], v[124:127]
	v_mfma_f32_16x16x32_bf16 v[120:123], v[164:167], v[210:213], v[120:123]
	v_mfma_f32_16x16x32_bf16 v[108:111], v[132:135], v[218:221], v[108:111]
	v_mfma_f32_16x16x32_bf16 v[104:107], v[164:167], v[218:221], v[104:107]
	v_mfma_f32_16x16x32_bf16 v[92:95], v[132:135], v[232:235], v[92:95]
	v_mfma_f32_16x16x32_bf16 v[88:91], v[164:167], v[232:235], v[88:91]
	v_mfma_f32_16x16x32_bf16 v[76:79], v[132:135], v[240:243], v[76:79]
	v_mfma_f32_16x16x32_bf16 v[72:75], v[164:167], v[240:243], v[72:75]
	s_setprio 0
	s_setprio 1
	v_mfma_f32_16x16x32_bf16 v[116:119], v[168:171], v[206:209], 0
	v_mfma_f32_16x16x32_bf16 v[112:115], v[176:179], v[206:209], 0
	v_mfma_f32_16x16x32_bf16 v[100:103], v[168:171], v[214:217], 0
	v_mfma_f32_16x16x32_bf16 v[96:99], v[176:179], v[214:217], 0
	v_mfma_f32_16x16x32_bf16 v[84:87], v[168:171], v[222:225], 0
	v_mfma_f32_16x16x32_bf16 v[80:83], v[176:179], v[222:225], 0
	v_mfma_f32_16x16x32_bf16 v[68:71], v[168:171], v[236:239], 0
	v_mfma_f32_16x16x32_bf16 v[64:67], v[176:179], v[236:239], 0
	v_mfma_f32_16x16x32_bf16 v[116:119], v[172:175], v[210:213], v[116:119]
	v_mfma_f32_16x16x32_bf16 v[112:115], v[200:203], v[210:213], v[112:115]
	v_mfma_f32_16x16x32_bf16 v[100:103], v[172:175], v[218:221], v[100:103]
	v_mfma_f32_16x16x32_bf16 v[96:99], v[200:203], v[218:221], v[96:99]
	v_mfma_f32_16x16x32_bf16 v[84:87], v[172:175], v[232:235], v[84:87]
	v_mfma_f32_16x16x32_bf16 v[80:83], v[200:203], v[232:235], v[80:83]
	v_mfma_f32_16x16x32_bf16 v[68:71], v[172:175], v[240:243], v[68:71]
	v_mfma_f32_16x16x32_bf16 v[64:67], v[200:203], v[240:243], v[64:67]
	s_setprio 0
	s_barrier
	s_add_i32 s70, s36, s51
	v_lshl_add_u64 v[136:137], s[2:3], 0, v[156:157]
	s_mov_b32 m0, s70
	ds_read_b128 v[206:209], v144 offset:16384
	ds_read_b128 v[210:213], v144 offset:17408
	ds_read_b128 v[214:217], v144 offset:18432
	ds_read_b128 v[218:221], v144 offset:19456
	ds_read_b128 v[222:225], v144 offset:20480
	ds_read_b128 v[232:235], v144 offset:21504
	ds_read_b128 v[236:239], v144 offset:22528
	ds_read_b128 v[240:243], v144 offset:23552
	global_load_lds_dwordx4 v[136:137], off
	s_add_i32 m0, s70, 0x2000
	s_add_u32 s70, s2, 0x40000
	v_lshl_add_u64 v[180:181], s[2:3], 0, v[152:153]
	s_addc_u32 s71, s3, 0
	s_add_i32 s72, s37, s51
	global_load_lds_dwordx4 v[180:181], off
	v_lshl_add_u64 v[244:245], s[70:71], 0, v[156:157]
	s_mov_b32 m0, s72
	v_lshl_add_u64 v[246:247], s[6:7], 0, v[154:155]
	global_load_lds_dwordx4 v[244:245], off
	v_lshl_add_u64 v[244:245], s[70:71], 0, v[152:153]
	s_add_i32 m0, s72, 0x2000
	s_nop 0
	global_load_lds_dwordx4 v[244:245], off
	v_lshl_add_u64 v[244:245], s[6:7], 0, v[158:159]
	s_mov_b32 m0, s54
	s_nop 0
	global_load_lds_dwordx4 v[244:245], off
	s_mov_b32 m0, s55
	s_nop 0
	global_load_lds_dwordx4 v[246:247], off
	s_waitcnt vmcnt(8)
	s_waitcnt lgkmcnt(0)
	s_barrier
	s_setprio 1
	v_mfma_f32_16x16x32_bf16 v[60:63], v[128:131], v[206:209], 0
	v_mfma_f32_16x16x32_bf16 v[56:59], v[148:151], v[206:209], 0
	v_mfma_f32_16x16x32_bf16 v[44:47], v[128:131], v[214:217], 0
	v_mfma_f32_16x16x32_bf16 v[40:43], v[148:151], v[214:217], 0
	v_mfma_f32_16x16x32_bf16 v[28:31], v[128:131], v[222:225], 0
	v_mfma_f32_16x16x32_bf16 v[24:27], v[148:151], v[222:225], 0
	v_mfma_f32_16x16x32_bf16 v[12:15], v[128:131], v[236:239], 0
	v_mfma_f32_16x16x32_bf16 v[8:11], v[148:151], v[236:239], 0
	v_mfma_f32_16x16x32_bf16 v[60:63], v[132:135], v[210:213], v[60:63]
	v_mfma_f32_16x16x32_bf16 v[56:59], v[164:167], v[210:213], v[56:59]
	v_mfma_f32_16x16x32_bf16 v[44:47], v[132:135], v[218:221], v[44:47]
	v_mfma_f32_16x16x32_bf16 v[40:43], v[164:167], v[218:221], v[40:43]
	v_mfma_f32_16x16x32_bf16 v[28:31], v[132:135], v[232:235], v[28:31]
	v_mfma_f32_16x16x32_bf16 v[24:27], v[164:167], v[232:235], v[24:27]
	v_mfma_f32_16x16x32_bf16 v[12:15], v[132:135], v[240:243], v[12:15]
	v_mfma_f32_16x16x32_bf16 v[8:11], v[164:167], v[240:243], v[8:11]
	s_setprio 0
	s_setprio 1
	v_mfma_f32_16x16x32_bf16 v[52:55], v[168:171], v[206:209], 0
	v_mfma_f32_16x16x32_bf16 v[48:51], v[176:179], v[206:209], 0
	v_mfma_f32_16x16x32_bf16 v[36:39], v[168:171], v[214:217], 0
	v_mfma_f32_16x16x32_bf16 v[32:35], v[176:179], v[214:217], 0
	v_mfma_f32_16x16x32_bf16 v[20:23], v[168:171], v[222:225], 0
	v_mfma_f32_16x16x32_bf16 v[16:19], v[176:179], v[222:225], 0
	v_mfma_f32_16x16x32_bf16 v[4:7], v[168:171], v[236:239], 0
	v_mfma_f32_16x16x32_bf16 v[0:3], v[176:179], v[236:239], 0
	v_mfma_f32_16x16x32_bf16 v[52:55], v[172:175], v[210:213], v[52:55]
	v_mfma_f32_16x16x32_bf16 v[48:51], v[200:203], v[210:213], v[48:51]
	v_mfma_f32_16x16x32_bf16 v[36:39], v[172:175], v[218:221], v[36:39]
	v_mfma_f32_16x16x32_bf16 v[32:35], v[200:203], v[218:221], v[32:35]
	v_mfma_f32_16x16x32_bf16 v[20:23], v[172:175], v[232:235], v[20:23]
	v_mfma_f32_16x16x32_bf16 v[16:19], v[200:203], v[232:235], v[16:19]
	v_mfma_f32_16x16x32_bf16 v[4:7], v[172:175], v[240:243], v[4:7]
	v_mfma_f32_16x16x32_bf16 v[0:3], v[200:203], v[240:243], v[0:3]
	s_setprio 0
	s_barrier
	v_add_u32_e32 v147, s45, v140
	ds_read_b128 v[128:131], v147
	ds_read_b128 v[132:135], v147 offset:1024
	ds_read_b128 v[148:151], v147 offset:2048
	ds_read_b128 v[164:167], v147 offset:3072
	v_add_u32_e32 v147, s46, v140
	ds_read_b128 v[168:171], v147
	ds_read_b128 v[172:175], v147 offset:1024
	ds_read_b128 v[176:179], v147 offset:2048
	ds_read_b128 v[200:203], v147 offset:3072
	s_add_u32 s6, s6, 0x40000
	s_addc_u32 s7, s7, 0
	s_mov_b32 m0, s56
	v_lshl_add_u64 v[248:249], s[6:7], 0, v[158:159]
	ds_read_b128 v[206:209], v144 offset:32768
	ds_read_b128 v[210:213], v144 offset:33792
	ds_read_b128 v[214:217], v144 offset:34816
	ds_read_b128 v[218:221], v144 offset:35840
	ds_read_b128 v[222:225], v144 offset:36864
	ds_read_b128 v[232:235], v144 offset:37888
	ds_read_b128 v[236:239], v144 offset:38912
	ds_read_b128 v[240:243], v144 offset:39936
	global_load_lds_dwordx4 v[248:249], off
	v_lshl_add_u64 v[248:249], s[6:7], 0, v[154:155]
	s_mov_b32 m0, s57
	s_nop 0
	global_load_lds_dwordx4 v[248:249], off
	s_waitcnt vmcnt(8)
	s_waitcnt lgkmcnt(0)
	s_barrier
	s_setprio 1
	v_mfma_f32_16x16x32_bf16 v[124:127], v[128:131], v[206:209], v[124:127]
	v_mfma_f32_16x16x32_bf16 v[120:123], v[148:151], v[206:209], v[120:123]
	v_mfma_f32_16x16x32_bf16 v[108:111], v[128:131], v[214:217], v[108:111]
	v_mfma_f32_16x16x32_bf16 v[104:107], v[148:151], v[214:217], v[104:107]
	v_mfma_f32_16x16x32_bf16 v[92:95], v[128:131], v[222:225], v[92:95]
	v_mfma_f32_16x16x32_bf16 v[88:91], v[148:151], v[222:225], v[88:91]
	v_mfma_f32_16x16x32_bf16 v[76:79], v[128:131], v[236:239], v[76:79]
	v_mfma_f32_16x16x32_bf16 v[72:75], v[148:151], v[236:239], v[72:75]
	v_mfma_f32_16x16x32_bf16 v[124:127], v[132:135], v[210:213], v[124:127]
	v_mfma_f32_16x16x32_bf16 v[120:123], v[164:167], v[210:213], v[120:123]
	v_mfma_f32_16x16x32_bf16 v[108:111], v[132:135], v[218:221], v[108:111]
	v_mfma_f32_16x16x32_bf16 v[104:107], v[164:167], v[218:221], v[104:107]
	v_mfma_f32_16x16x32_bf16 v[92:95], v[132:135], v[232:235], v[92:95]
	v_mfma_f32_16x16x32_bf16 v[88:91], v[164:167], v[232:235], v[88:91]
	v_mfma_f32_16x16x32_bf16 v[76:79], v[132:135], v[240:243], v[76:79]
	v_mfma_f32_16x16x32_bf16 v[72:75], v[164:167], v[240:243], v[72:75]
	s_setprio 0
	s_setprio 1
	v_mfma_f32_16x16x32_bf16 v[116:119], v[168:171], v[206:209], v[116:119]
	v_mfma_f32_16x16x32_bf16 v[112:115], v[176:179], v[206:209], v[112:115]
	v_mfma_f32_16x16x32_bf16 v[100:103], v[168:171], v[214:217], v[100:103]
	v_mfma_f32_16x16x32_bf16 v[96:99], v[176:179], v[214:217], v[96:99]
	v_mfma_f32_16x16x32_bf16 v[84:87], v[168:171], v[222:225], v[84:87]
	v_mfma_f32_16x16x32_bf16 v[80:83], v[176:179], v[222:225], v[80:83]
	v_mfma_f32_16x16x32_bf16 v[68:71], v[168:171], v[236:239], v[68:71]
	v_mfma_f32_16x16x32_bf16 v[64:67], v[176:179], v[236:239], v[64:67]
	v_mfma_f32_16x16x32_bf16 v[116:119], v[172:175], v[210:213], v[116:119]
	v_mfma_f32_16x16x32_bf16 v[112:115], v[200:203], v[210:213], v[112:115]
	v_mfma_f32_16x16x32_bf16 v[100:103], v[172:175], v[218:221], v[100:103]
	v_mfma_f32_16x16x32_bf16 v[96:99], v[200:203], v[218:221], v[96:99]
	v_mfma_f32_16x16x32_bf16 v[84:87], v[172:175], v[232:235], v[84:87]
	v_mfma_f32_16x16x32_bf16 v[80:83], v[200:203], v[232:235], v[80:83]
	v_mfma_f32_16x16x32_bf16 v[68:71], v[172:175], v[240:243], v[68:71]
	v_mfma_f32_16x16x32_bf16 v[64:67], v[200:203], v[240:243], v[64:67]
	s_setprio 0
	s_barrier
	s_add_i32 s6, s45, s51
	v_lshl_add_u64 v[136:137], v[136:137], 0, s[22:23]
	s_mov_b32 m0, s6
	ds_read_b128 v[206:209], v144 offset:49152
	ds_read_b128 v[210:213], v144 offset:50176
	ds_read_b128 v[214:217], v144 offset:51200
	ds_read_b128 v[218:221], v144 offset:52224
	ds_read_b128 v[222:225], v144 offset:53248
	ds_read_b128 v[232:235], v144 offset:54272
	ds_read_b128 v[236:239], v144 offset:55296
	ds_read_b128 v[240:243], v144 offset:56320
	global_load_lds_dwordx4 v[136:137], off
	s_add_i32 m0, s6, 0x2000
	s_add_u32 s2, s2, 0x40080
	v_lshl_add_u64 v[136:137], v[180:181], 0, s[22:23]
	s_addc_u32 s3, s3, 0
	s_add_i32 s6, s46, s51
	global_load_lds_dwordx4 v[136:137], off
	v_lshl_add_u64 v[136:137], s[2:3], 0, v[156:157]
	s_mov_b32 m0, s6
	s_nop 0
	global_load_lds_dwordx4 v[136:137], off
	v_lshl_add_u64 v[136:137], s[2:3], 0, v[152:153]
	s_add_i32 m0, s6, 0x2000
	s_nop 0
	global_load_lds_dwordx4 v[136:137], off
	v_lshl_add_u64 v[136:137], v[244:245], 0, s[22:23]
	s_mov_b32 m0, s59
	s_nop 0
	global_load_lds_dwordx4 v[136:137], off
	v_lshl_add_u64 v[136:137], v[246:247], 0, s[22:23]
	s_mov_b32 m0, s60
	s_nop 0
	global_load_lds_dwordx4 v[136:137], off
	s_waitcnt vmcnt(8)
	s_waitcnt lgkmcnt(0)
	s_barrier
	s_setprio 1
	v_mfma_f32_16x16x32_bf16 v[60:63], v[128:131], v[206:209], v[60:63]
	v_mfma_f32_16x16x32_bf16 v[56:59], v[148:151], v[206:209], v[56:59]
	v_mfma_f32_16x16x32_bf16 v[44:47], v[128:131], v[214:217], v[44:47]
	v_mfma_f32_16x16x32_bf16 v[40:43], v[148:151], v[214:217], v[40:43]
	v_mfma_f32_16x16x32_bf16 v[28:31], v[128:131], v[222:225], v[28:31]
	v_mfma_f32_16x16x32_bf16 v[24:27], v[148:151], v[222:225], v[24:27]
	v_mfma_f32_16x16x32_bf16 v[12:15], v[128:131], v[236:239], v[12:15]
	v_mfma_f32_16x16x32_bf16 v[8:11], v[148:151], v[236:239], v[8:11]
	v_mfma_f32_16x16x32_bf16 v[60:63], v[132:135], v[210:213], v[60:63]
	v_mfma_f32_16x16x32_bf16 v[56:59], v[164:167], v[210:213], v[56:59]
	v_mfma_f32_16x16x32_bf16 v[44:47], v[132:135], v[218:221], v[44:47]
	v_mfma_f32_16x16x32_bf16 v[40:43], v[164:167], v[218:221], v[40:43]
	v_mfma_f32_16x16x32_bf16 v[28:31], v[132:135], v[232:235], v[28:31]
	v_mfma_f32_16x16x32_bf16 v[24:27], v[164:167], v[232:235], v[24:27]
	v_mfma_f32_16x16x32_bf16 v[12:15], v[132:135], v[240:243], v[12:15]
	v_mfma_f32_16x16x32_bf16 v[8:11], v[164:167], v[240:243], v[8:11]
	s_setprio 0
	s_setprio 1
	v_mfma_f32_16x16x32_bf16 v[52:55], v[168:171], v[206:209], v[52:55]
	v_mfma_f32_16x16x32_bf16 v[48:51], v[176:179], v[206:209], v[48:51]
	v_mfma_f32_16x16x32_bf16 v[36:39], v[168:171], v[214:217], v[36:39]
	v_mfma_f32_16x16x32_bf16 v[32:35], v[176:179], v[214:217], v[32:35]
	v_mfma_f32_16x16x32_bf16 v[20:23], v[168:171], v[222:225], v[20:23]
	v_mfma_f32_16x16x32_bf16 v[16:19], v[176:179], v[222:225], v[16:19]
	v_mfma_f32_16x16x32_bf16 v[4:7], v[168:171], v[236:239], v[4:7]
	v_mfma_f32_16x16x32_bf16 v[0:3], v[176:179], v[236:239], v[0:3]
	v_mfma_f32_16x16x32_bf16 v[52:55], v[172:175], v[210:213], v[52:55]
	v_mfma_f32_16x16x32_bf16 v[48:51], v[200:203], v[210:213], v[48:51]
	v_mfma_f32_16x16x32_bf16 v[36:39], v[172:175], v[218:221], v[36:39]
	v_mfma_f32_16x16x32_bf16 v[32:35], v[200:203], v[218:221], v[32:35]
	v_mfma_f32_16x16x32_bf16 v[20:23], v[172:175], v[232:235], v[20:23]
	v_mfma_f32_16x16x32_bf16 v[16:19], v[200:203], v[232:235], v[16:19]
	v_mfma_f32_16x16x32_bf16 v[4:7], v[172:175], v[240:243], v[4:7]
	v_mfma_f32_16x16x32_bf16 v[0:3], v[200:203], v[240:243], v[0:3]
	s_setprio 0
	s_barrier
	s_add_i32 s69, s69, 2
	s_add_u32 s0, s0, 0x100
	s_addc_u32 s1, s1, 0
	s_add_u32 s67, s67, 0x100
	s_addc_u32 s68, s68, 0
	s_cmp_gt_u32 s69, 13
.LBB0_661:
	ds_read_b128 v[128:131], v142
	ds_read_b128 v[132:135], v142 offset:1024
	ds_read_b128 v[148:151], v142 offset:2048
	ds_read_b128 v[164:167], v142 offset:3072
	ds_read_b128 v[168:171], v143
	ds_read_b128 v[172:175], v143 offset:1024
	ds_read_b128 v[176:179], v143 offset:2048
	ds_read_b128 v[200:203], v143 offset:3072
	s_add_u32 s2, s0, 0xfffc0080
	s_addc_u32 s3, s1, -1
	s_cmp_eq_u32 s69, 12
	s_cselect_b32 s7, s35, s3
	s_cselect_b32 s6, s65, s2
	s_cselect_b32 s3, s31, s68
	s_cselect_b32 s2, s66, s67
	v_lshl_add_u64 v[136:137], s[0:1], 0, v[160:161]
	s_add_i32 m0, s54, 0xc000
	ds_read_b128 v[206:209], v144
	ds_read_b128 v[210:213], v144 offset:1024
	ds_read_b128 v[214:217], v144 offset:2048
	ds_read_b128 v[218:221], v144 offset:3072
	ds_read_b128 v[222:225], v144 offset:4096
	ds_read_b128 v[232:235], v144 offset:5120
	ds_read_b128 v[236:239], v144 offset:6144
	ds_read_b128 v[240:243], v144 offset:7168
	global_load_lds_dwordx4 v[136:137], off
	v_lshl_add_u64 v[136:137], s[0:1], 0, v[162:163]
	s_add_i32 m0, s54, 0xe000
	s_nop 0
	global_load_lds_dwordx4 v[136:137], off
	s_waitcnt vmcnt(8)
	s_waitcnt lgkmcnt(0)
	s_barrier
	s_setprio 1
	v_mfma_f32_16x16x32_bf16 v[124:127], v[128:131], v[206:209], v[124:127]
	v_mfma_f32_16x16x32_bf16 v[120:123], v[148:151], v[206:209], v[120:123]
	v_mfma_f32_16x16x32_bf16 v[108:111], v[128:131], v[214:217], v[108:111]
	v_mfma_f32_16x16x32_bf16 v[104:107], v[148:151], v[214:217], v[104:107]
	v_mfma_f32_16x16x32_bf16 v[92:95], v[128:131], v[222:225], v[92:95]
	v_mfma_f32_16x16x32_bf16 v[88:91], v[148:151], v[222:225], v[88:91]
	v_mfma_f32_16x16x32_bf16 v[76:79], v[128:131], v[236:239], v[76:79]
	v_mfma_f32_16x16x32_bf16 v[72:75], v[148:151], v[236:239], v[72:75]
	v_mfma_f32_16x16x32_bf16 v[124:127], v[132:135], v[210:213], v[124:127]
	v_mfma_f32_16x16x32_bf16 v[120:123], v[164:167], v[210:213], v[120:123]
	v_mfma_f32_16x16x32_bf16 v[108:111], v[132:135], v[218:221], v[108:111]
	v_mfma_f32_16x16x32_bf16 v[104:107], v[164:167], v[218:221], v[104:107]
	v_mfma_f32_16x16x32_bf16 v[92:95], v[132:135], v[232:235], v[92:95]
	v_mfma_f32_16x16x32_bf16 v[88:91], v[164:167], v[232:235], v[88:91]
	v_mfma_f32_16x16x32_bf16 v[76:79], v[132:135], v[240:243], v[76:79]
	v_mfma_f32_16x16x32_bf16 v[72:75], v[164:167], v[240:243], v[72:75]
	s_setprio 0
	s_setprio 1
	v_mfma_f32_16x16x32_bf16 v[116:119], v[168:171], v[206:209], v[116:119]
	v_mfma_f32_16x16x32_bf16 v[112:115], v[176:179], v[206:209], v[112:115]
	v_mfma_f32_16x16x32_bf16 v[100:103], v[168:171], v[214:217], v[100:103]
	v_mfma_f32_16x16x32_bf16 v[96:99], v[176:179], v[214:217], v[96:99]
	v_mfma_f32_16x16x32_bf16 v[84:87], v[168:171], v[222:225], v[84:87]
	v_mfma_f32_16x16x32_bf16 v[80:83], v[176:179], v[222:225], v[80:83]
	v_mfma_f32_16x16x32_bf16 v[68:71], v[168:171], v[236:239], v[68:71]
	v_mfma_f32_16x16x32_bf16 v[64:67], v[176:179], v[236:239], v[64:67]
	v_mfma_f32_16x16x32_bf16 v[116:119], v[172:175], v[210:213], v[116:119]
	v_mfma_f32_16x16x32_bf16 v[112:115], v[200:203], v[210:213], v[112:115]
	v_mfma_f32_16x16x32_bf16 v[100:103], v[172:175], v[218:221], v[100:103]
	v_mfma_f32_16x16x32_bf16 v[96:99], v[200:203], v[218:221], v[96:99]
	v_mfma_f32_16x16x32_bf16 v[84:87], v[172:175], v[232:235], v[84:87]
	v_mfma_f32_16x16x32_bf16 v[80:83], v[200:203], v[232:235], v[80:83]
	v_mfma_f32_16x16x32_bf16 v[68:71], v[172:175], v[240:243], v[68:71]
	v_mfma_f32_16x16x32_bf16 v[64:67], v[200:203], v[240:243], v[64:67]
	s_setprio 0
	s_barrier
	s_add_i32 s70, s36, s51
	v_lshl_add_u64 v[136:137], s[2:3], 0, v[156:157]
	s_mov_b32 m0, s70
	ds_read_b128 v[206:209], v144 offset:16384
	ds_read_b128 v[210:213], v144 offset:17408
	ds_read_b128 v[214:217], v144 offset:18432
	ds_read_b128 v[218:221], v144 offset:19456
	ds_read_b128 v[222:225], v144 offset:20480
	ds_read_b128 v[232:235], v144 offset:21504
	ds_read_b128 v[236:239], v144 offset:22528
	ds_read_b128 v[240:243], v144 offset:23552
	global_load_lds_dwordx4 v[136:137], off
	s_add_i32 m0, s70, 0x2000
	s_add_u32 s70, s2, 0x40000
	v_lshl_add_u64 v[180:181], s[2:3], 0, v[152:153]
	s_addc_u32 s71, s3, 0
	s_add_i32 s72, s37, s51
	global_load_lds_dwordx4 v[180:181], off
	v_lshl_add_u64 v[244:245], s[70:71], 0, v[156:157]
	s_mov_b32 m0, s72
	v_lshl_add_u64 v[246:247], s[6:7], 0, v[154:155]
	global_load_lds_dwordx4 v[244:245], off
	v_lshl_add_u64 v[244:245], s[70:71], 0, v[152:153]
	s_add_i32 m0, s72, 0x2000
	s_nop 0
	global_load_lds_dwordx4 v[244:245], off
	v_lshl_add_u64 v[244:245], s[6:7], 0, v[158:159]
	s_mov_b32 m0, s54
	s_nop 0
	global_load_lds_dwordx4 v[244:245], off
	s_mov_b32 m0, s55
	s_nop 0
	global_load_lds_dwordx4 v[246:247], off
	s_waitcnt vmcnt(8)
	s_waitcnt lgkmcnt(0)
	s_barrier
	s_setprio 1
	v_mfma_f32_16x16x32_bf16 v[60:63], v[128:131], v[206:209], v[60:63]
	v_mfma_f32_16x16x32_bf16 v[56:59], v[148:151], v[206:209], v[56:59]
	v_mfma_f32_16x16x32_bf16 v[44:47], v[128:131], v[214:217], v[44:47]
	v_mfma_f32_16x16x32_bf16 v[40:43], v[148:151], v[214:217], v[40:43]
	v_mfma_f32_16x16x32_bf16 v[28:31], v[128:131], v[222:225], v[28:31]
	v_mfma_f32_16x16x32_bf16 v[24:27], v[148:151], v[222:225], v[24:27]
	v_mfma_f32_16x16x32_bf16 v[12:15], v[128:131], v[236:239], v[12:15]
	v_mfma_f32_16x16x32_bf16 v[8:11], v[148:151], v[236:239], v[8:11]
	v_mfma_f32_16x16x32_bf16 v[60:63], v[132:135], v[210:213], v[60:63]
	v_mfma_f32_16x16x32_bf16 v[56:59], v[164:167], v[210:213], v[56:59]
	v_mfma_f32_16x16x32_bf16 v[44:47], v[132:135], v[218:221], v[44:47]
	v_mfma_f32_16x16x32_bf16 v[40:43], v[164:167], v[218:221], v[40:43]
	v_mfma_f32_16x16x32_bf16 v[28:31], v[132:135], v[232:235], v[28:31]
	v_mfma_f32_16x16x32_bf16 v[24:27], v[164:167], v[232:235], v[24:27]
	v_mfma_f32_16x16x32_bf16 v[12:15], v[132:135], v[240:243], v[12:15]
	v_mfma_f32_16x16x32_bf16 v[8:11], v[164:167], v[240:243], v[8:11]
	s_setprio 0
	s_setprio 1
	v_mfma_f32_16x16x32_bf16 v[52:55], v[168:171], v[206:209], v[52:55]
	v_mfma_f32_16x16x32_bf16 v[48:51], v[176:179], v[206:209], v[48:51]
	v_mfma_f32_16x16x32_bf16 v[36:39], v[168:171], v[214:217], v[36:39]
	v_mfma_f32_16x16x32_bf16 v[32:35], v[176:179], v[214:217], v[32:35]
	v_mfma_f32_16x16x32_bf16 v[20:23], v[168:171], v[222:225], v[20:23]
	v_mfma_f32_16x16x32_bf16 v[16:19], v[176:179], v[222:225], v[16:19]
	v_mfma_f32_16x16x32_bf16 v[4:7], v[168:171], v[236:239], v[4:7]
	v_mfma_f32_16x16x32_bf16 v[0:3], v[176:179], v[236:239], v[0:3]
	v_mfma_f32_16x16x32_bf16 v[52:55], v[172:175], v[210:213], v[52:55]
	v_mfma_f32_16x16x32_bf16 v[48:51], v[200:203], v[210:213], v[48:51]
	v_mfma_f32_16x16x32_bf16 v[36:39], v[172:175], v[218:221], v[36:39]
	v_mfma_f32_16x16x32_bf16 v[32:35], v[200:203], v[218:221], v[32:35]
	v_mfma_f32_16x16x32_bf16 v[20:23], v[172:175], v[232:235], v[20:23]
	v_mfma_f32_16x16x32_bf16 v[16:19], v[200:203], v[232:235], v[16:19]
	v_mfma_f32_16x16x32_bf16 v[4:7], v[172:175], v[240:243], v[4:7]
	v_mfma_f32_16x16x32_bf16 v[0:3], v[200:203], v[240:243], v[0:3]
	s_setprio 0
	s_barrier
	v_add_u32_e32 v147, s45, v140
	ds_read_b128 v[128:131], v147
	ds_read_b128 v[132:135], v147 offset:1024
	ds_read_b128 v[148:151], v147 offset:2048
	ds_read_b128 v[164:167], v147 offset:3072
	v_add_u32_e32 v147, s46, v140
	ds_read_b128 v[168:171], v147
	ds_read_b128 v[172:175], v147 offset:1024
	ds_read_b128 v[176:179], v147 offset:2048
	ds_read_b128 v[200:203], v147 offset:3072
	s_add_u32 s6, s6, 0x40000
	s_addc_u32 s7, s7, 0
	s_mov_b32 m0, s56
	v_lshl_add_u64 v[248:249], s[6:7], 0, v[158:159]
	ds_read_b128 v[206:209], v144 offset:32768
	ds_read_b128 v[210:213], v144 offset:33792
	ds_read_b128 v[214:217], v144 offset:34816
	ds_read_b128 v[218:221], v144 offset:35840
	ds_read_b128 v[222:225], v144 offset:36864
	ds_read_b128 v[232:235], v144 offset:37888
	ds_read_b128 v[236:239], v144 offset:38912
	ds_read_b128 v[240:243], v144 offset:39936
	global_load_lds_dwordx4 v[248:249], off
	v_lshl_add_u64 v[248:249], s[6:7], 0, v[154:155]
	s_mov_b32 m0, s57
	s_nop 0
	global_load_lds_dwordx4 v[248:249], off
	s_waitcnt vmcnt(8)
	s_waitcnt lgkmcnt(0)
	s_barrier
	s_setprio 1
	v_mfma_f32_16x16x32_bf16 v[124:127], v[128:131], v[206:209], v[124:127]
	v_mfma_f32_16x16x32_bf16 v[120:123], v[148:151], v[206:209], v[120:123]
	v_mfma_f32_16x16x32_bf16 v[108:111], v[128:131], v[214:217], v[108:111]
	v_mfma_f32_16x16x32_bf16 v[104:107], v[148:151], v[214:217], v[104:107]
	v_mfma_f32_16x16x32_bf16 v[92:95], v[128:131], v[222:225], v[92:95]
	v_mfma_f32_16x16x32_bf16 v[88:91], v[148:151], v[222:225], v[88:91]
	v_mfma_f32_16x16x32_bf16 v[76:79], v[128:131], v[236:239], v[76:79]
	v_mfma_f32_16x16x32_bf16 v[72:75], v[148:151], v[236:239], v[72:75]
	v_mfma_f32_16x16x32_bf16 v[124:127], v[132:135], v[210:213], v[124:127]
	v_mfma_f32_16x16x32_bf16 v[120:123], v[164:167], v[210:213], v[120:123]
	v_mfma_f32_16x16x32_bf16 v[108:111], v[132:135], v[218:221], v[108:111]
	v_mfma_f32_16x16x32_bf16 v[104:107], v[164:167], v[218:221], v[104:107]
	v_mfma_f32_16x16x32_bf16 v[92:95], v[132:135], v[232:235], v[92:95]
	v_mfma_f32_16x16x32_bf16 v[88:91], v[164:167], v[232:235], v[88:91]
	v_mfma_f32_16x16x32_bf16 v[76:79], v[132:135], v[240:243], v[76:79]
	v_mfma_f32_16x16x32_bf16 v[72:75], v[164:167], v[240:243], v[72:75]
	s_setprio 0
	s_setprio 1
	v_mfma_f32_16x16x32_bf16 v[116:119], v[168:171], v[206:209], v[116:119]
	v_mfma_f32_16x16x32_bf16 v[112:115], v[176:179], v[206:209], v[112:115]
	v_mfma_f32_16x16x32_bf16 v[100:103], v[168:171], v[214:217], v[100:103]
	v_mfma_f32_16x16x32_bf16 v[96:99], v[176:179], v[214:217], v[96:99]
	v_mfma_f32_16x16x32_bf16 v[84:87], v[168:171], v[222:225], v[84:87]
	v_mfma_f32_16x16x32_bf16 v[80:83], v[176:179], v[222:225], v[80:83]
	v_mfma_f32_16x16x32_bf16 v[68:71], v[168:171], v[236:239], v[68:71]
	v_mfma_f32_16x16x32_bf16 v[64:67], v[176:179], v[236:239], v[64:67]
	v_mfma_f32_16x16x32_bf16 v[116:119], v[172:175], v[210:213], v[116:119]
	v_mfma_f32_16x16x32_bf16 v[112:115], v[200:203], v[210:213], v[112:115]
	v_mfma_f32_16x16x32_bf16 v[100:103], v[172:175], v[218:221], v[100:103]
	v_mfma_f32_16x16x32_bf16 v[96:99], v[200:203], v[218:221], v[96:99]
	v_mfma_f32_16x16x32_bf16 v[84:87], v[172:175], v[232:235], v[84:87]
	v_mfma_f32_16x16x32_bf16 v[80:83], v[200:203], v[232:235], v[80:83]
	v_mfma_f32_16x16x32_bf16 v[68:71], v[172:175], v[240:243], v[68:71]
	v_mfma_f32_16x16x32_bf16 v[64:67], v[200:203], v[240:243], v[64:67]
	s_setprio 0
	s_barrier
	s_add_i32 s6, s45, s51
	v_lshl_add_u64 v[136:137], v[136:137], 0, s[22:23]
	s_mov_b32 m0, s6
	ds_read_b128 v[206:209], v144 offset:49152
	ds_read_b128 v[210:213], v144 offset:50176
	ds_read_b128 v[214:217], v144 offset:51200
	ds_read_b128 v[218:221], v144 offset:52224
	ds_read_b128 v[222:225], v144 offset:53248
	ds_read_b128 v[232:235], v144 offset:54272
	ds_read_b128 v[236:239], v144 offset:55296
	ds_read_b128 v[240:243], v144 offset:56320
	global_load_lds_dwordx4 v[136:137], off
	s_add_i32 m0, s6, 0x2000
	s_add_u32 s2, s2, 0x40080
	v_lshl_add_u64 v[136:137], v[180:181], 0, s[22:23]
	s_addc_u32 s3, s3, 0
	s_add_i32 s6, s46, s51
	global_load_lds_dwordx4 v[136:137], off
	v_lshl_add_u64 v[136:137], s[2:3], 0, v[156:157]
	s_mov_b32 m0, s6
	s_nop 0
	global_load_lds_dwordx4 v[136:137], off
	v_lshl_add_u64 v[136:137], s[2:3], 0, v[152:153]
	s_add_i32 m0, s6, 0x2000
	s_nop 0
	global_load_lds_dwordx4 v[136:137], off
	v_lshl_add_u64 v[136:137], v[244:245], 0, s[22:23]
	s_mov_b32 m0, s59
	s_nop 0
	global_load_lds_dwordx4 v[136:137], off
	v_lshl_add_u64 v[136:137], v[246:247], 0, s[22:23]
	s_mov_b32 m0, s60
	s_nop 0
	global_load_lds_dwordx4 v[136:137], off
	s_waitcnt vmcnt(8)
	s_waitcnt lgkmcnt(0)
	s_barrier
	s_setprio 1
	v_mfma_f32_16x16x32_bf16 v[60:63], v[128:131], v[206:209], v[60:63]
	v_mfma_f32_16x16x32_bf16 v[56:59], v[148:151], v[206:209], v[56:59]
	v_mfma_f32_16x16x32_bf16 v[44:47], v[128:131], v[214:217], v[44:47]
	v_mfma_f32_16x16x32_bf16 v[40:43], v[148:151], v[214:217], v[40:43]
	v_mfma_f32_16x16x32_bf16 v[28:31], v[128:131], v[222:225], v[28:31]
	v_mfma_f32_16x16x32_bf16 v[24:27], v[148:151], v[222:225], v[24:27]
	v_mfma_f32_16x16x32_bf16 v[12:15], v[128:131], v[236:239], v[12:15]
	v_mfma_f32_16x16x32_bf16 v[8:11], v[148:151], v[236:239], v[8:11]
	v_mfma_f32_16x16x32_bf16 v[60:63], v[132:135], v[210:213], v[60:63]
	v_mfma_f32_16x16x32_bf16 v[56:59], v[164:167], v[210:213], v[56:59]
	v_mfma_f32_16x16x32_bf16 v[44:47], v[132:135], v[218:221], v[44:47]
	v_mfma_f32_16x16x32_bf16 v[40:43], v[164:167], v[218:221], v[40:43]
	v_mfma_f32_16x16x32_bf16 v[28:31], v[132:135], v[232:235], v[28:31]
	v_mfma_f32_16x16x32_bf16 v[24:27], v[164:167], v[232:235], v[24:27]
	v_mfma_f32_16x16x32_bf16 v[12:15], v[132:135], v[240:243], v[12:15]
	v_mfma_f32_16x16x32_bf16 v[8:11], v[164:167], v[240:243], v[8:11]
	s_setprio 0
	s_setprio 1
	v_mfma_f32_16x16x32_bf16 v[52:55], v[168:171], v[206:209], v[52:55]
	v_mfma_f32_16x16x32_bf16 v[48:51], v[176:179], v[206:209], v[48:51]
	v_mfma_f32_16x16x32_bf16 v[36:39], v[168:171], v[214:217], v[36:39]
	v_mfma_f32_16x16x32_bf16 v[32:35], v[176:179], v[214:217], v[32:35]
	v_mfma_f32_16x16x32_bf16 v[20:23], v[168:171], v[222:225], v[20:23]
	v_mfma_f32_16x16x32_bf16 v[16:19], v[176:179], v[222:225], v[16:19]
	v_mfma_f32_16x16x32_bf16 v[4:7], v[168:171], v[236:239], v[4:7]
	v_mfma_f32_16x16x32_bf16 v[0:3], v[176:179], v[236:239], v[0:3]
	v_mfma_f32_16x16x32_bf16 v[52:55], v[172:175], v[210:213], v[52:55]
	v_mfma_f32_16x16x32_bf16 v[48:51], v[200:203], v[210:213], v[48:51]
	v_mfma_f32_16x16x32_bf16 v[36:39], v[172:175], v[218:221], v[36:39]
	v_mfma_f32_16x16x32_bf16 v[32:35], v[200:203], v[218:221], v[32:35]
	v_mfma_f32_16x16x32_bf16 v[20:23], v[172:175], v[232:235], v[20:23]
	v_mfma_f32_16x16x32_bf16 v[16:19], v[200:203], v[232:235], v[16:19]
	v_mfma_f32_16x16x32_bf16 v[4:7], v[172:175], v[240:243], v[4:7]
	v_mfma_f32_16x16x32_bf16 v[0:3], v[200:203], v[240:243], v[0:3]
	s_setprio 0
	s_barrier
	s_add_i32 s69, s69, 2
	s_add_u32 s0, s0, 0x100
	s_addc_u32 s1, s1, 0
	s_add_u32 s67, s67, 0x100
	s_addc_u32 s68, s68, 0
	s_cmp_gt_u32 s69, 13
	s_cbranch_scc0 .LBB0_661
	s_and_b64 vcc, exec, s[28:29]
	s_cbranch_vccz .LBB0_664
	s_barrier

.LBB0_683:
	v_lshl_or_b32 v140, s7, 6, v193
	s_lshl_b32 s7, s7, 13
	s_lshl_b32 s6, s6, 5
	v_bitop3_b32 v8, v194, s7, v138 bitop3:0xde
	s_and_b32 s23, s6, 0x60
	s_mov_b64 s[6:7], 0x80
	s_add_i32 m0, s19, 0x18000
	v_lshl_add_u64 v[6:7], v[6:7], 0, s[6:7]
	s_waitcnt vmcnt(2)
	s_barrier
	global_load_lds_dwordx4 v[6:7], off
	v_lshl_add_u64 v[4:5], v[4:5], 0, s[6:7]
	s_add_i32 m0, s19, 0x1a000
	s_add_i32 s28, s19, 0x8000
	s_add_i32 s29, s19, 0xa000
	global_load_lds_dwordx4 v[4:5], off
	v_lshl_add_u64 v[2:3], v[2:3], 0, s[6:7]
	s_mov_b32 m0, s28
	s_add_u32 s14, s0, 0x100080
	global_load_lds_dwordx4 v[2:3], off
	v_lshl_add_u64 v[0:1], v[0:1], 0, s[6:7]
	s_mov_b32 m0, s29
	s_addc_u32 s15, s1, 0
	global_load_lds_dwordx4 v[0:1], off
	s_add_i32 m0, s19, 0x1c000
	v_lshl_add_u64 v[0:1], s[14:15], 0, v[132:133]
	global_load_lds_dwordx4 v[0:1], off
	v_lshl_add_u64 v[0:1], s[14:15], 0, v[128:129]
	s_add_i32 m0, s19, 0x1e000
	s_add_i32 s12, s44, s53
	global_load_lds_dwordx4 v[0:1], off
	s_lshl_b64 s[12:13], s[12:13], 21
	v_lshlrev_b32_e32 v0, 17, v195
	v_lshlrev_b32_e32 v2, 13, v186
	v_or3_b32 v0, v184, v0, v2
	s_add_u32 s12, s96, s12
	v_add_u32_e32 v0, v0, v185
	v_mov_b32_e32 v1, v133
	s_addc_u32 s13, s97, s13
	v_lshl_add_u64 v[136:137], s[12:13], 0, v[0:1]
	v_lshlrev_b32_e32 v0, 17, v197
	v_lshl_or_b32 v9, s23, 7, v196
	s_waitcnt vmcnt(6)
	v_or3_b32 v0, v184, v0, v2
	v_add_u32_e32 v0, v0, v185
	v_add_u32_e32 v141, s36, v9
	s_add_i32 s34, s36, s16
	s_add_i32 s36, s37, s16
	v_add_u32_e32 v144, s45, v9
	s_add_i32 s41, s45, s16
	s_add_i32 s45, s46, s16
	v_lshl_add_u64 v[138:139], s[12:13], 0, v[0:1]
	s_mov_b32 s30, -2
	s_mov_b64 s[12:13], 0x7600080
	v_add_u32_e32 v142, s37, v9
	v_add_u32_e32 v143, 0, v8
	s_add_i32 s31, s19, 0xc000
	s_add_i32 s33, s19, 0xe000
	s_add_i32 s35, s34, 0x2000
	s_add_i32 s37, s36, 0x2000
	v_add_u32_e32 v145, s46, v9
	s_add_i32 s44, s41, 0x2000
	s_add_i32 s46, s45, 0x2000
	s_barrier
	ds_read_b128 v[146:149], v141
	ds_read_b128 v[150:153], v141 offset:1024
	ds_read_b128 v[154:157], v141 offset:2048
	ds_read_b128 v[158:161], v141 offset:3072
	ds_read_b128 v[162:165], v142
	ds_read_b128 v[166:169], v142 offset:1024
	ds_read_b128 v[170:173], v142 offset:2048
	ds_read_b128 v[174:177], v142 offset:3072
	s_add_u32 s14, s12, 0xf8a00080
	s_addc_u32 s15, s13, -1
	s_cmp_lg_u32 s30, 60
	s_cselect_b32 s14, s14, 0
	s_cselect_b32 s15, s15, 0
	s_add_u32 s16, s2, s14
	s_addc_u32 s17, s3, s15
	s_add_u32 s14, s0, s14
	s_addc_u32 s15, s1, s15
	s_mov_b32 m0, s31
	v_lshl_add_u64 v[218:219], v[136:137], 0, s[12:13]
	ds_read_b128 v[178:181], v143
	ds_read_b128 v[184:187], v143 offset:1024
	ds_read_b128 v[188:191], v143 offset:2048
	ds_read_b128 v[194:197], v143 offset:3072
	ds_read_b128 v[200:203], v143 offset:4096
	ds_read_b128 v[206:209], v143 offset:5120
	ds_read_b128 v[210:213], v143 offset:6144
	ds_read_b128 v[214:217], v143 offset:7168
	global_load_lds_dwordx4 v[218:219], off
	v_lshl_add_u64 v[218:219], v[138:139], 0, s[12:13]
	s_mov_b32 m0, s33
	s_nop 0
	global_load_lds_dwordx4 v[218:219], off
	s_waitcnt vmcnt(8)
	s_waitcnt lgkmcnt(0)
	s_barrier
	s_setprio 1
	v_mfma_f32_16x16x32_bf16 v[124:127], v[146:149], v[178:181], 0
	v_mfma_f32_16x16x32_bf16 v[120:123], v[154:157], v[178:181], 0
	v_mfma_f32_16x16x32_bf16 v[108:111], v[146:149], v[188:191], 0
	v_mfma_f32_16x16x32_bf16 v[104:107], v[154:157], v[188:191], 0
	v_mfma_f32_16x16x32_bf16 v[92:95], v[146:149], v[200:203], 0
	v_mfma_f32_16x16x32_bf16 v[88:91], v[154:157], v[200:203], 0
	v_mfma_f32_16x16x32_bf16 v[76:79], v[146:149], v[210:213], 0
	v_mfma_f32_16x16x32_bf16 v[72:75], v[154:157], v[210:213], 0
	v_mfma_f32_16x16x32_bf16 v[124:127], v[150:153], v[184:187], v[124:127]
	v_mfma_f32_16x16x32_bf16 v[120:123], v[158:161], v[184:187], v[120:123]
	v_mfma_f32_16x16x32_bf16 v[108:111], v[150:153], v[194:197], v[108:111]
	v_mfma_f32_16x16x32_bf16 v[104:107], v[158:161], v[194:197], v[104:107]
	v_mfma_f32_16x16x32_bf16 v[92:95], v[150:153], v[206:209], v[92:95]
	v_mfma_f32_16x16x32_bf16 v[88:91], v[158:161], v[206:209], v[88:91]
	v_mfma_f32_16x16x32_bf16 v[76:79], v[150:153], v[214:217], v[76:79]
	v_mfma_f32_16x16x32_bf16 v[72:75], v[158:161], v[214:217], v[72:75]
	s_setprio 0
	s_setprio 1
	v_mfma_f32_16x16x32_bf16 v[116:119], v[162:165], v[178:181], 0
	v_mfma_f32_16x16x32_bf16 v[112:115], v[170:173], v[178:181], 0
	v_mfma_f32_16x16x32_bf16 v[100:103], v[162:165], v[188:191], 0
	v_mfma_f32_16x16x32_bf16 v[96:99], v[170:173], v[188:191], 0
	v_mfma_f32_16x16x32_bf16 v[84:87], v[162:165], v[200:203], 0
	v_mfma_f32_16x16x32_bf16 v[80:83], v[170:173], v[200:203], 0
	v_mfma_f32_16x16x32_bf16 v[68:71], v[162:165], v[210:213], 0
	v_mfma_f32_16x16x32_bf16 v[64:67], v[170:173], v[210:213], 0
	v_mfma_f32_16x16x32_bf16 v[116:119], v[166:169], v[184:187], v[116:119]
	v_mfma_f32_16x16x32_bf16 v[112:115], v[174:177], v[184:187], v[112:115]
	v_mfma_f32_16x16x32_bf16 v[100:103], v[166:169], v[194:197], v[100:103]
	v_mfma_f32_16x16x32_bf16 v[96:99], v[174:177], v[194:197], v[96:99]
	v_mfma_f32_16x16x32_bf16 v[84:87], v[166:169], v[206:209], v[84:87]
	v_mfma_f32_16x16x32_bf16 v[80:83], v[174:177], v[206:209], v[80:83]
	v_mfma_f32_16x16x32_bf16 v[68:71], v[166:169], v[214:217], v[68:71]
	v_mfma_f32_16x16x32_bf16 v[64:67], v[174:177], v[214:217], v[64:67]
	s_setprio 0
	s_barrier
	s_mov_b32 m0, s34
	v_lshl_add_u64 v[218:219], s[14:15], 0, v[132:133]
	s_add_u32 s48, s14, 0x100000
	ds_read_b128 v[178:181], v143 offset:16384
	ds_read_b128 v[184:187], v143 offset:17408
	ds_read_b128 v[188:191], v143 offset:18432
	ds_read_b128 v[194:197], v143 offset:19456
	ds_read_b128 v[200:203], v143 offset:20480
	ds_read_b128 v[206:209], v143 offset:21504
	ds_read_b128 v[210:213], v143 offset:22528
	ds_read_b128 v[214:217], v143 offset:23552
	global_load_lds_dwordx4 v[218:219], off
	v_lshl_add_u64 v[220:221], s[14:15], 0, v[128:129]
	s_mov_b32 m0, s35
	s_addc_u32 s49, s15, 0
	global_load_lds_dwordx4 v[220:221], off
	v_lshl_add_u64 v[222:223], s[48:49], 0, v[132:133]
	s_mov_b32 m0, s36
	v_lshl_add_u64 v[224:225], s[16:17], 0, v[130:131]
	global_load_lds_dwordx4 v[222:223], off
	v_lshl_add_u64 v[222:223], s[48:49], 0, v[128:129]
	s_mov_b32 m0, s37
	s_nop 0
	global_load_lds_dwordx4 v[222:223], off
	v_lshl_add_u64 v[222:223], s[16:17], 0, v[134:135]
	s_mov_b32 m0, s19
	s_nop 0
	global_load_lds_dwordx4 v[222:223], off
	s_mov_b32 m0, s20
	s_nop 0
	global_load_lds_dwordx4 v[224:225], off
	s_waitcnt vmcnt(8)
	s_waitcnt lgkmcnt(0)
	s_barrier
	s_setprio 1
	v_mfma_f32_16x16x32_bf16 v[60:63], v[146:149], v[178:181], 0
	v_mfma_f32_16x16x32_bf16 v[56:59], v[154:157], v[178:181], 0
	v_mfma_f32_16x16x32_bf16 v[44:47], v[146:149], v[188:191], 0
	v_mfma_f32_16x16x32_bf16 v[40:43], v[154:157], v[188:191], 0
	v_mfma_f32_16x16x32_bf16 v[28:31], v[146:149], v[200:203], 0
	v_mfma_f32_16x16x32_bf16 v[24:27], v[154:157], v[200:203], 0
	v_mfma_f32_16x16x32_bf16 v[12:15], v[146:149], v[210:213], 0
	v_mfma_f32_16x16x32_bf16 v[8:11], v[154:157], v[210:213], 0
	v_mfma_f32_16x16x32_bf16 v[60:63], v[150:153], v[184:187], v[60:63]
	v_mfma_f32_16x16x32_bf16 v[56:59], v[158:161], v[184:187], v[56:59]
	v_mfma_f32_16x16x32_bf16 v[44:47], v[150:153], v[194:197], v[44:47]
	v_mfma_f32_16x16x32_bf16 v[40:43], v[158:161], v[194:197], v[40:43]
	v_mfma_f32_16x16x32_bf16 v[28:31], v[150:153], v[206:209], v[28:31]
	v_mfma_f32_16x16x32_bf16 v[24:27], v[158:161], v[206:209], v[24:27]
	v_mfma_f32_16x16x32_bf16 v[12:15], v[150:153], v[214:217], v[12:15]
	v_mfma_f32_16x16x32_bf16 v[8:11], v[158:161], v[214:217], v[8:11]
	s_setprio 0
	s_setprio 1
	v_mfma_f32_16x16x32_bf16 v[52:55], v[162:165], v[178:181], 0
	v_mfma_f32_16x16x32_bf16 v[48:51], v[170:173], v[178:181], 0
	v_mfma_f32_16x16x32_bf16 v[36:39], v[162:165], v[188:191], 0
	v_mfma_f32_16x16x32_bf16 v[32:35], v[170:173], v[188:191], 0
	v_mfma_f32_16x16x32_bf16 v[20:23], v[162:165], v[200:203], 0
	v_mfma_f32_16x16x32_bf16 v[16:19], v[170:173], v[200:203], 0
	v_mfma_f32_16x16x32_bf16 v[4:7], v[162:165], v[210:213], 0
	v_mfma_f32_16x16x32_bf16 v[0:3], v[170:173], v[210:213], 0
	v_mfma_f32_16x16x32_bf16 v[52:55], v[166:169], v[184:187], v[52:55]
	v_mfma_f32_16x16x32_bf16 v[48:51], v[174:177], v[184:187], v[48:51]
	v_mfma_f32_16x16x32_bf16 v[36:39], v[166:169], v[194:197], v[36:39]
	v_mfma_f32_16x16x32_bf16 v[32:35], v[174:177], v[194:197], v[32:35]
	v_mfma_f32_16x16x32_bf16 v[20:23], v[166:169], v[206:209], v[20:23]
	v_mfma_f32_16x16x32_bf16 v[16:19], v[174:177], v[206:209], v[16:19]
	v_mfma_f32_16x16x32_bf16 v[4:7], v[166:169], v[214:217], v[4:7]
	v_mfma_f32_16x16x32_bf16 v[0:3], v[174:177], v[214:217], v[0:3]
	s_setprio 0
	s_barrier
	ds_read_b128 v[146:149], v144
	ds_read_b128 v[150:153], v144 offset:1024
	ds_read_b128 v[154:157], v144 offset:2048
	ds_read_b128 v[158:161], v144 offset:3072
	ds_read_b128 v[162:165], v145
	ds_read_b128 v[166:169], v145 offset:1024
	ds_read_b128 v[170:173], v145 offset:2048
	ds_read_b128 v[174:177], v145 offset:3072
	s_add_u32 s16, s16, 0x100000
	s_addc_u32 s17, s17, 0
	s_mov_b32 m0, s21
	v_lshl_add_u64 v[232:233], s[16:17], 0, v[134:135]
	ds_read_b128 v[178:181], v143 offset:32768
	ds_read_b128 v[184:187], v143 offset:33792
	ds_read_b128 v[188:191], v143 offset:34816
	ds_read_b128 v[194:197], v143 offset:35840
	ds_read_b128 v[200:203], v143 offset:36864
	ds_read_b128 v[206:209], v143 offset:37888
	ds_read_b128 v[210:213], v143 offset:38912
	ds_read_b128 v[214:217], v143 offset:39936
	global_load_lds_dwordx4 v[232:233], off
	v_lshl_add_u64 v[232:233], s[16:17], 0, v[130:131]
	s_mov_b32 m0, s22
	s_nop 0
	global_load_lds_dwordx4 v[232:233], off
	s_waitcnt vmcnt(8)
	s_waitcnt lgkmcnt(0)
	s_barrier
	s_setprio 1
	v_mfma_f32_16x16x32_bf16 v[124:127], v[146:149], v[178:181], v[124:127]
	v_mfma_f32_16x16x32_bf16 v[120:123], v[154:157], v[178:181], v[120:123]
	v_mfma_f32_16x16x32_bf16 v[108:111], v[146:149], v[188:191], v[108:111]
	v_mfma_f32_16x16x32_bf16 v[104:107], v[154:157], v[188:191], v[104:107]
	v_mfma_f32_16x16x32_bf16 v[92:95], v[146:149], v[200:203], v[92:95]
	v_mfma_f32_16x16x32_bf16 v[88:91], v[154:157], v[200:203], v[88:91]
	v_mfma_f32_16x16x32_bf16 v[76:79], v[146:149], v[210:213], v[76:79]
	v_mfma_f32_16x16x32_bf16 v[72:75], v[154:157], v[210:213], v[72:75]
	v_mfma_f32_16x16x32_bf16 v[124:127], v[150:153], v[184:187], v[124:127]
	v_mfma_f32_16x16x32_bf16 v[120:123], v[158:161], v[184:187], v[120:123]
	v_mfma_f32_16x16x32_bf16 v[108:111], v[150:153], v[194:197], v[108:111]
	v_mfma_f32_16x16x32_bf16 v[104:107], v[158:161], v[194:197], v[104:107]
	v_mfma_f32_16x16x32_bf16 v[92:95], v[150:153], v[206:209], v[92:95]
	v_mfma_f32_16x16x32_bf16 v[88:91], v[158:161], v[206:209], v[88:91]
	v_mfma_f32_16x16x32_bf16 v[76:79], v[150:153], v[214:217], v[76:79]
	v_mfma_f32_16x16x32_bf16 v[72:75], v[158:161], v[214:217], v[72:75]
	s_setprio 0
	s_setprio 1
	v_mfma_f32_16x16x32_bf16 v[116:119], v[162:165], v[178:181], v[116:119]
	v_mfma_f32_16x16x32_bf16 v[112:115], v[170:173], v[178:181], v[112:115]
	v_mfma_f32_16x16x32_bf16 v[100:103], v[162:165], v[188:191], v[100:103]
	v_mfma_f32_16x16x32_bf16 v[96:99], v[170:173], v[188:191], v[96:99]
	v_mfma_f32_16x16x32_bf16 v[84:87], v[162:165], v[200:203], v[84:87]
	v_mfma_f32_16x16x32_bf16 v[80:83], v[170:173], v[200:203], v[80:83]
	v_mfma_f32_16x16x32_bf16 v[68:71], v[162:165], v[210:213], v[68:71]
	v_mfma_f32_16x16x32_bf16 v[64:67], v[170:173], v[210:213], v[64:67]
	v_mfma_f32_16x16x32_bf16 v[116:119], v[166:169], v[184:187], v[116:119]
	v_mfma_f32_16x16x32_bf16 v[112:115], v[174:177], v[184:187], v[112:115]
	v_mfma_f32_16x16x32_bf16 v[100:103], v[166:169], v[194:197], v[100:103]
	v_mfma_f32_16x16x32_bf16 v[96:99], v[174:177], v[194:197], v[96:99]
	v_mfma_f32_16x16x32_bf16 v[84:87], v[166:169], v[206:209], v[84:87]
	v_mfma_f32_16x16x32_bf16 v[80:83], v[174:177], v[206:209], v[80:83]
	v_mfma_f32_16x16x32_bf16 v[68:71], v[166:169], v[214:217], v[68:71]
	v_mfma_f32_16x16x32_bf16 v[64:67], v[174:177], v[214:217], v[64:67]
	s_setprio 0
	s_barrier
	s_mov_b32 m0, s41
	v_lshl_add_u64 v[218:219], v[218:219], 0, s[6:7]
	s_add_u32 s14, s14, 0x100080
	ds_read_b128 v[178:181], v143 offset:49152
	ds_read_b128 v[184:187], v143 offset:50176
	ds_read_b128 v[188:191], v143 offset:51200
	ds_read_b128 v[194:197], v143 offset:52224
	ds_read_b128 v[200:203], v143 offset:53248
	ds_read_b128 v[206:209], v143 offset:54272
	ds_read_b128 v[210:213], v143 offset:55296
	ds_read_b128 v[214:217], v143 offset:56320
	global_load_lds_dwordx4 v[218:219], off
	v_lshl_add_u64 v[218:219], v[220:221], 0, s[6:7]
	s_mov_b32 m0, s44
	s_addc_u32 s15, s15, 0
	global_load_lds_dwordx4 v[218:219], off
	v_lshl_add_u64 v[218:219], s[14:15], 0, v[132:133]
	s_mov_b32 m0, s45
	s_nop 0
	global_load_lds_dwordx4 v[218:219], off
	v_lshl_add_u64 v[218:219], s[14:15], 0, v[128:129]
	s_mov_b32 m0, s46
	s_nop 0
	global_load_lds_dwordx4 v[218:219], off
	v_lshl_add_u64 v[218:219], v[222:223], 0, s[6:7]
	s_mov_b32 m0, s28
	s_nop 0
	global_load_lds_dwordx4 v[218:219], off
	v_lshl_add_u64 v[218:219], v[224:225], 0, s[6:7]
	s_mov_b32 m0, s29
	s_nop 0
	global_load_lds_dwordx4 v[218:219], off
	s_waitcnt vmcnt(8)
	s_waitcnt lgkmcnt(0)
	s_barrier
	s_setprio 1
	v_mfma_f32_16x16x32_bf16 v[60:63], v[146:149], v[178:181], v[60:63]
	v_mfma_f32_16x16x32_bf16 v[56:59], v[154:157], v[178:181], v[56:59]
	v_mfma_f32_16x16x32_bf16 v[44:47], v[146:149], v[188:191], v[44:47]
	v_mfma_f32_16x16x32_bf16 v[40:43], v[154:157], v[188:191], v[40:43]
	v_mfma_f32_16x16x32_bf16 v[28:31], v[146:149], v[200:203], v[28:31]
	v_mfma_f32_16x16x32_bf16 v[24:27], v[154:157], v[200:203], v[24:27]
	v_mfma_f32_16x16x32_bf16 v[12:15], v[146:149], v[210:213], v[12:15]
	v_mfma_f32_16x16x32_bf16 v[8:11], v[154:157], v[210:213], v[8:11]
	v_mfma_f32_16x16x32_bf16 v[60:63], v[150:153], v[184:187], v[60:63]
	v_mfma_f32_16x16x32_bf16 v[56:59], v[158:161], v[184:187], v[56:59]
	v_mfma_f32_16x16x32_bf16 v[44:47], v[150:153], v[194:197], v[44:47]
	v_mfma_f32_16x16x32_bf16 v[40:43], v[158:161], v[194:197], v[40:43]
	v_mfma_f32_16x16x32_bf16 v[28:31], v[150:153], v[206:209], v[28:31]
	v_mfma_f32_16x16x32_bf16 v[24:27], v[158:161], v[206:209], v[24:27]
	v_mfma_f32_16x16x32_bf16 v[12:15], v[150:153], v[214:217], v[12:15]
	v_mfma_f32_16x16x32_bf16 v[8:11], v[158:161], v[214:217], v[8:11]
	s_setprio 0
	s_setprio 1
	v_mfma_f32_16x16x32_bf16 v[52:55], v[162:165], v[178:181], v[52:55]
	v_mfma_f32_16x16x32_bf16 v[48:51], v[170:173], v[178:181], v[48:51]
	v_mfma_f32_16x16x32_bf16 v[36:39], v[162:165], v[188:191], v[36:39]
	v_mfma_f32_16x16x32_bf16 v[32:35], v[170:173], v[188:191], v[32:35]
	v_mfma_f32_16x16x32_bf16 v[20:23], v[162:165], v[200:203], v[20:23]
	v_mfma_f32_16x16x32_bf16 v[16:19], v[170:173], v[200:203], v[16:19]
	v_mfma_f32_16x16x32_bf16 v[4:7], v[162:165], v[210:213], v[4:7]
	v_mfma_f32_16x16x32_bf16 v[0:3], v[170:173], v[210:213], v[0:3]
	v_mfma_f32_16x16x32_bf16 v[52:55], v[166:169], v[184:187], v[52:55]
	v_mfma_f32_16x16x32_bf16 v[48:51], v[174:177], v[184:187], v[48:51]
	v_mfma_f32_16x16x32_bf16 v[36:39], v[166:169], v[194:197], v[36:39]
	v_mfma_f32_16x16x32_bf16 v[32:35], v[174:177], v[194:197], v[32:35]
	v_mfma_f32_16x16x32_bf16 v[20:23], v[166:169], v[206:209], v[20:23]
	v_mfma_f32_16x16x32_bf16 v[16:19], v[174:177], v[206:209], v[16:19]
	v_mfma_f32_16x16x32_bf16 v[4:7], v[166:169], v[214:217], v[4:7]
	v_mfma_f32_16x16x32_bf16 v[0:3], v[174:177], v[214:217], v[0:3]
	s_setprio 0
	s_barrier
	s_add_i32 s30, s30, 2
	s_add_u32 s12, s12, 0x100
	s_addc_u32 s13, s13, 0
	s_cmp_gt_u32 s30, 61
.LBB0_684:
	ds_read_b128 v[146:149], v141
	ds_read_b128 v[150:153], v141 offset:1024
	ds_read_b128 v[154:157], v141 offset:2048
	ds_read_b128 v[158:161], v141 offset:3072
	ds_read_b128 v[162:165], v142
	ds_read_b128 v[166:169], v142 offset:1024
	ds_read_b128 v[170:173], v142 offset:2048
	ds_read_b128 v[174:177], v142 offset:3072
	s_add_u32 s14, s12, 0xf8a00080
	s_addc_u32 s15, s13, -1
	s_cmp_lg_u32 s30, 60
	s_cselect_b32 s14, s14, 0
	s_cselect_b32 s15, s15, 0
	s_add_u32 s16, s2, s14
	s_addc_u32 s17, s3, s15
	s_add_u32 s14, s0, s14
	s_addc_u32 s15, s1, s15
	s_mov_b32 m0, s31
	v_lshl_add_u64 v[218:219], v[136:137], 0, s[12:13]
	ds_read_b128 v[178:181], v143
	ds_read_b128 v[184:187], v143 offset:1024
	ds_read_b128 v[188:191], v143 offset:2048
	ds_read_b128 v[194:197], v143 offset:3072
	ds_read_b128 v[200:203], v143 offset:4096
	ds_read_b128 v[206:209], v143 offset:5120
	ds_read_b128 v[210:213], v143 offset:6144
	ds_read_b128 v[214:217], v143 offset:7168
	global_load_lds_dwordx4 v[218:219], off
	v_lshl_add_u64 v[218:219], v[138:139], 0, s[12:13]
	s_mov_b32 m0, s33
	s_nop 0
	global_load_lds_dwordx4 v[218:219], off
	s_waitcnt vmcnt(8)
	s_waitcnt lgkmcnt(0)
	s_barrier
	s_setprio 1
	v_mfma_f32_16x16x32_bf16 v[124:127], v[146:149], v[178:181], v[124:127]
	v_mfma_f32_16x16x32_bf16 v[120:123], v[154:157], v[178:181], v[120:123]
	v_mfma_f32_16x16x32_bf16 v[108:111], v[146:149], v[188:191], v[108:111]
	v_mfma_f32_16x16x32_bf16 v[104:107], v[154:157], v[188:191], v[104:107]
	v_mfma_f32_16x16x32_bf16 v[92:95], v[146:149], v[200:203], v[92:95]
	v_mfma_f32_16x16x32_bf16 v[88:91], v[154:157], v[200:203], v[88:91]
	v_mfma_f32_16x16x32_bf16 v[76:79], v[146:149], v[210:213], v[76:79]
	v_mfma_f32_16x16x32_bf16 v[72:75], v[154:157], v[210:213], v[72:75]
	v_mfma_f32_16x16x32_bf16 v[124:127], v[150:153], v[184:187], v[124:127]
	v_mfma_f32_16x16x32_bf16 v[120:123], v[158:161], v[184:187], v[120:123]
	v_mfma_f32_16x16x32_bf16 v[108:111], v[150:153], v[194:197], v[108:111]
	v_mfma_f32_16x16x32_bf16 v[104:107], v[158:161], v[194:197], v[104:107]
	v_mfma_f32_16x16x32_bf16 v[92:95], v[150:153], v[206:209], v[92:95]
	v_mfma_f32_16x16x32_bf16 v[88:91], v[158:161], v[206:209], v[88:91]
	v_mfma_f32_16x16x32_bf16 v[76:79], v[150:153], v[214:217], v[76:79]
	v_mfma_f32_16x16x32_bf16 v[72:75], v[158:161], v[214:217], v[72:75]
	s_setprio 0
	s_setprio 1
	v_mfma_f32_16x16x32_bf16 v[116:119], v[162:165], v[178:181], v[116:119]
	v_mfma_f32_16x16x32_bf16 v[112:115], v[170:173], v[178:181], v[112:115]
	v_mfma_f32_16x16x32_bf16 v[100:103], v[162:165], v[188:191], v[100:103]
	v_mfma_f32_16x16x32_bf16 v[96:99], v[170:173], v[188:191], v[96:99]
	v_mfma_f32_16x16x32_bf16 v[84:87], v[162:165], v[200:203], v[84:87]
	v_mfma_f32_16x16x32_bf16 v[80:83], v[170:173], v[200:203], v[80:83]
	v_mfma_f32_16x16x32_bf16 v[68:71], v[162:165], v[210:213], v[68:71]
	v_mfma_f32_16x16x32_bf16 v[64:67], v[170:173], v[210:213], v[64:67]
	v_mfma_f32_16x16x32_bf16 v[116:119], v[166:169], v[184:187], v[116:119]
	v_mfma_f32_16x16x32_bf16 v[112:115], v[174:177], v[184:187], v[112:115]
	v_mfma_f32_16x16x32_bf16 v[100:103], v[166:169], v[194:197], v[100:103]
	v_mfma_f32_16x16x32_bf16 v[96:99], v[174:177], v[194:197], v[96:99]
	v_mfma_f32_16x16x32_bf16 v[84:87], v[166:169], v[206:209], v[84:87]
	v_mfma_f32_16x16x32_bf16 v[80:83], v[174:177], v[206:209], v[80:83]
	v_mfma_f32_16x16x32_bf16 v[68:71], v[166:169], v[214:217], v[68:71]
	v_mfma_f32_16x16x32_bf16 v[64:67], v[174:177], v[214:217], v[64:67]
	s_setprio 0
	s_barrier
	s_mov_b32 m0, s34
	v_lshl_add_u64 v[218:219], s[14:15], 0, v[132:133]
	s_add_u32 s48, s14, 0x100000
	ds_read_b128 v[178:181], v143 offset:16384
	ds_read_b128 v[184:187], v143 offset:17408
	ds_read_b128 v[188:191], v143 offset:18432
	ds_read_b128 v[194:197], v143 offset:19456
	ds_read_b128 v[200:203], v143 offset:20480
	ds_read_b128 v[206:209], v143 offset:21504
	ds_read_b128 v[210:213], v143 offset:22528
	ds_read_b128 v[214:217], v143 offset:23552
	global_load_lds_dwordx4 v[218:219], off
	v_lshl_add_u64 v[220:221], s[14:15], 0, v[128:129]
	s_mov_b32 m0, s35
	s_addc_u32 s49, s15, 0
	global_load_lds_dwordx4 v[220:221], off
	v_lshl_add_u64 v[222:223], s[48:49], 0, v[132:133]
	s_mov_b32 m0, s36
	v_lshl_add_u64 v[224:225], s[16:17], 0, v[130:131]
	global_load_lds_dwordx4 v[222:223], off
	v_lshl_add_u64 v[222:223], s[48:49], 0, v[128:129]
	s_mov_b32 m0, s37
	s_nop 0
	global_load_lds_dwordx4 v[222:223], off
	v_lshl_add_u64 v[222:223], s[16:17], 0, v[134:135]
	s_mov_b32 m0, s19
	s_nop 0
	global_load_lds_dwordx4 v[222:223], off
	s_mov_b32 m0, s20
	s_nop 0
	global_load_lds_dwordx4 v[224:225], off
	s_waitcnt vmcnt(8)
	s_waitcnt lgkmcnt(0)
	s_barrier
	s_setprio 1
	v_mfma_f32_16x16x32_bf16 v[60:63], v[146:149], v[178:181], v[60:63]
	v_mfma_f32_16x16x32_bf16 v[56:59], v[154:157], v[178:181], v[56:59]
	v_mfma_f32_16x16x32_bf16 v[44:47], v[146:149], v[188:191], v[44:47]
	v_mfma_f32_16x16x32_bf16 v[40:43], v[154:157], v[188:191], v[40:43]
	v_mfma_f32_16x16x32_bf16 v[28:31], v[146:149], v[200:203], v[28:31]
	v_mfma_f32_16x16x32_bf16 v[24:27], v[154:157], v[200:203], v[24:27]
	v_mfma_f32_16x16x32_bf16 v[12:15], v[146:149], v[210:213], v[12:15]
	v_mfma_f32_16x16x32_bf16 v[8:11], v[154:157], v[210:213], v[8:11]
	v_mfma_f32_16x16x32_bf16 v[60:63], v[150:153], v[184:187], v[60:63]
	v_mfma_f32_16x16x32_bf16 v[56:59], v[158:161], v[184:187], v[56:59]
	v_mfma_f32_16x16x32_bf16 v[44:47], v[150:153], v[194:197], v[44:47]
	v_mfma_f32_16x16x32_bf16 v[40:43], v[158:161], v[194:197], v[40:43]
	v_mfma_f32_16x16x32_bf16 v[28:31], v[150:153], v[206:209], v[28:31]
	v_mfma_f32_16x16x32_bf16 v[24:27], v[158:161], v[206:209], v[24:27]
	v_mfma_f32_16x16x32_bf16 v[12:15], v[150:153], v[214:217], v[12:15]
	v_mfma_f32_16x16x32_bf16 v[8:11], v[158:161], v[214:217], v[8:11]
	s_setprio 0
	s_setprio 1
	v_mfma_f32_16x16x32_bf16 v[52:55], v[162:165], v[178:181], v[52:55]
	v_mfma_f32_16x16x32_bf16 v[48:51], v[170:173], v[178:181], v[48:51]
	v_mfma_f32_16x16x32_bf16 v[36:39], v[162:165], v[188:191], v[36:39]
	v_mfma_f32_16x16x32_bf16 v[32:35], v[170:173], v[188:191], v[32:35]
	v_mfma_f32_16x16x32_bf16 v[20:23], v[162:165], v[200:203], v[20:23]
	v_mfma_f32_16x16x32_bf16 v[16:19], v[170:173], v[200:203], v[16:19]
	v_mfma_f32_16x16x32_bf16 v[4:7], v[162:165], v[210:213], v[4:7]
	v_mfma_f32_16x16x32_bf16 v[0:3], v[170:173], v[210:213], v[0:3]
	v_mfma_f32_16x16x32_bf16 v[52:55], v[166:169], v[184:187], v[52:55]
	v_mfma_f32_16x16x32_bf16 v[48:51], v[174:177], v[184:187], v[48:51]
	v_mfma_f32_16x16x32_bf16 v[36:39], v[166:169], v[194:197], v[36:39]
	v_mfma_f32_16x16x32_bf16 v[32:35], v[174:177], v[194:197], v[32:35]
	v_mfma_f32_16x16x32_bf16 v[20:23], v[166:169], v[206:209], v[20:23]
	v_mfma_f32_16x16x32_bf16 v[16:19], v[174:177], v[206:209], v[16:19]
	v_mfma_f32_16x16x32_bf16 v[4:7], v[166:169], v[214:217], v[4:7]
	v_mfma_f32_16x16x32_bf16 v[0:3], v[174:177], v[214:217], v[0:3]
	s_setprio 0
	s_barrier
	ds_read_b128 v[146:149], v144
	ds_read_b128 v[150:153], v144 offset:1024
	ds_read_b128 v[154:157], v144 offset:2048
	ds_read_b128 v[158:161], v144 offset:3072
	ds_read_b128 v[162:165], v145
	ds_read_b128 v[166:169], v145 offset:1024
	ds_read_b128 v[170:173], v145 offset:2048
	ds_read_b128 v[174:177], v145 offset:3072
	s_add_u32 s16, s16, 0x100000
	s_addc_u32 s17, s17, 0
	s_mov_b32 m0, s21
	v_lshl_add_u64 v[232:233], s[16:17], 0, v[134:135]
	ds_read_b128 v[178:181], v143 offset:32768
	ds_read_b128 v[184:187], v143 offset:33792
	ds_read_b128 v[188:191], v143 offset:34816
	ds_read_b128 v[194:197], v143 offset:35840
	ds_read_b128 v[200:203], v143 offset:36864
	ds_read_b128 v[206:209], v143 offset:37888
	ds_read_b128 v[210:213], v143 offset:38912
	ds_read_b128 v[214:217], v143 offset:39936
	global_load_lds_dwordx4 v[232:233], off
	v_lshl_add_u64 v[232:233], s[16:17], 0, v[130:131]
	s_mov_b32 m0, s22
	s_nop 0
	global_load_lds_dwordx4 v[232:233], off
	s_waitcnt vmcnt(8)
	s_waitcnt lgkmcnt(0)
	s_barrier
	s_setprio 1
	v_mfma_f32_16x16x32_bf16 v[124:127], v[146:149], v[178:181], v[124:127]
	v_mfma_f32_16x16x32_bf16 v[120:123], v[154:157], v[178:181], v[120:123]
	v_mfma_f32_16x16x32_bf16 v[108:111], v[146:149], v[188:191], v[108:111]
	v_mfma_f32_16x16x32_bf16 v[104:107], v[154:157], v[188:191], v[104:107]
	v_mfma_f32_16x16x32_bf16 v[92:95], v[146:149], v[200:203], v[92:95]
	v_mfma_f32_16x16x32_bf16 v[88:91], v[154:157], v[200:203], v[88:91]
	v_mfma_f32_16x16x32_bf16 v[76:79], v[146:149], v[210:213], v[76:79]
	v_mfma_f32_16x16x32_bf16 v[72:75], v[154:157], v[210:213], v[72:75]
	v_mfma_f32_16x16x32_bf16 v[124:127], v[150:153], v[184:187], v[124:127]
	v_mfma_f32_16x16x32_bf16 v[120:123], v[158:161], v[184:187], v[120:123]
	v_mfma_f32_16x16x32_bf16 v[108:111], v[150:153], v[194:197], v[108:111]
	v_mfma_f32_16x16x32_bf16 v[104:107], v[158:161], v[194:197], v[104:107]
	v_mfma_f32_16x16x32_bf16 v[92:95], v[150:153], v[206:209], v[92:95]
	v_mfma_f32_16x16x32_bf16 v[88:91], v[158:161], v[206:209], v[88:91]
	v_mfma_f32_16x16x32_bf16 v[76:79], v[150:153], v[214:217], v[76:79]
	v_mfma_f32_16x16x32_bf16 v[72:75], v[158:161], v[214:217], v[72:75]
	s_setprio 0
	s_setprio 1
	v_mfma_f32_16x16x32_bf16 v[116:119], v[162:165], v[178:181], v[116:119]
	v_mfma_f32_16x16x32_bf16 v[112:115], v[170:173], v[178:181], v[112:115]
	v_mfma_f32_16x16x32_bf16 v[100:103], v[162:165], v[188:191], v[100:103]
	v_mfma_f32_16x16x32_bf16 v[96:99], v[170:173], v[188:191], v[96:99]
	v_mfma_f32_16x16x32_bf16 v[84:87], v[162:165], v[200:203], v[84:87]
	v_mfma_f32_16x16x32_bf16 v[80:83], v[170:173], v[200:203], v[80:83]
	v_mfma_f32_16x16x32_bf16 v[68:71], v[162:165], v[210:213], v[68:71]
	v_mfma_f32_16x16x32_bf16 v[64:67], v[170:173], v[210:213], v[64:67]
	v_mfma_f32_16x16x32_bf16 v[116:119], v[166:169], v[184:187], v[116:119]
	v_mfma_f32_16x16x32_bf16 v[112:115], v[174:177], v[184:187], v[112:115]
	v_mfma_f32_16x16x32_bf16 v[100:103], v[166:169], v[194:197], v[100:103]
	v_mfma_f32_16x16x32_bf16 v[96:99], v[174:177], v[194:197], v[96:99]
	v_mfma_f32_16x16x32_bf16 v[84:87], v[166:169], v[206:209], v[84:87]
	v_mfma_f32_16x16x32_bf16 v[80:83], v[174:177], v[206:209], v[80:83]
	v_mfma_f32_16x16x32_bf16 v[68:71], v[166:169], v[214:217], v[68:71]
	v_mfma_f32_16x16x32_bf16 v[64:67], v[174:177], v[214:217], v[64:67]
	s_setprio 0
	s_barrier
	s_mov_b32 m0, s41
	v_lshl_add_u64 v[218:219], v[218:219], 0, s[6:7]
	s_add_u32 s14, s14, 0x100080
	ds_read_b128 v[178:181], v143 offset:49152
	ds_read_b128 v[184:187], v143 offset:50176
	ds_read_b128 v[188:191], v143 offset:51200
	ds_read_b128 v[194:197], v143 offset:52224
	ds_read_b128 v[200:203], v143 offset:53248
	ds_read_b128 v[206:209], v143 offset:54272
	ds_read_b128 v[210:213], v143 offset:55296
	ds_read_b128 v[214:217], v143 offset:56320
	global_load_lds_dwordx4 v[218:219], off
	v_lshl_add_u64 v[218:219], v[220:221], 0, s[6:7]
	s_mov_b32 m0, s44
	s_addc_u32 s15, s15, 0
	global_load_lds_dwordx4 v[218:219], off
	v_lshl_add_u64 v[218:219], s[14:15], 0, v[132:133]
	s_mov_b32 m0, s45
	s_nop 0
	global_load_lds_dwordx4 v[218:219], off
	v_lshl_add_u64 v[218:219], s[14:15], 0, v[128:129]
	s_mov_b32 m0, s46
	s_nop 0
	global_load_lds_dwordx4 v[218:219], off
	v_lshl_add_u64 v[218:219], v[222:223], 0, s[6:7]
	s_mov_b32 m0, s28
	s_nop 0
	global_load_lds_dwordx4 v[218:219], off
	v_lshl_add_u64 v[218:219], v[224:225], 0, s[6:7]
	s_mov_b32 m0, s29
	s_nop 0
	global_load_lds_dwordx4 v[218:219], off
	s_waitcnt vmcnt(8)
	s_waitcnt lgkmcnt(0)
	s_barrier
	s_setprio 1
	v_mfma_f32_16x16x32_bf16 v[60:63], v[146:149], v[178:181], v[60:63]
	v_mfma_f32_16x16x32_bf16 v[56:59], v[154:157], v[178:181], v[56:59]
	v_mfma_f32_16x16x32_bf16 v[44:47], v[146:149], v[188:191], v[44:47]
	v_mfma_f32_16x16x32_bf16 v[40:43], v[154:157], v[188:191], v[40:43]
	v_mfma_f32_16x16x32_bf16 v[28:31], v[146:149], v[200:203], v[28:31]
	v_mfma_f32_16x16x32_bf16 v[24:27], v[154:157], v[200:203], v[24:27]
	v_mfma_f32_16x16x32_bf16 v[12:15], v[146:149], v[210:213], v[12:15]
	v_mfma_f32_16x16x32_bf16 v[8:11], v[154:157], v[210:213], v[8:11]
	v_mfma_f32_16x16x32_bf16 v[60:63], v[150:153], v[184:187], v[60:63]
	v_mfma_f32_16x16x32_bf16 v[56:59], v[158:161], v[184:187], v[56:59]
	v_mfma_f32_16x16x32_bf16 v[44:47], v[150:153], v[194:197], v[44:47]
	v_mfma_f32_16x16x32_bf16 v[40:43], v[158:161], v[194:197], v[40:43]
	v_mfma_f32_16x16x32_bf16 v[28:31], v[150:153], v[206:209], v[28:31]
	v_mfma_f32_16x16x32_bf16 v[24:27], v[158:161], v[206:209], v[24:27]
	v_mfma_f32_16x16x32_bf16 v[12:15], v[150:153], v[214:217], v[12:15]
	v_mfma_f32_16x16x32_bf16 v[8:11], v[158:161], v[214:217], v[8:11]
	s_setprio 0
	s_setprio 1
	v_mfma_f32_16x16x32_bf16 v[52:55], v[162:165], v[178:181], v[52:55]
	v_mfma_f32_16x16x32_bf16 v[48:51], v[170:173], v[178:181], v[48:51]
	v_mfma_f32_16x16x32_bf16 v[36:39], v[162:165], v[188:191], v[36:39]
	v_mfma_f32_16x16x32_bf16 v[32:35], v[170:173], v[188:191], v[32:35]
	v_mfma_f32_16x16x32_bf16 v[20:23], v[162:165], v[200:203], v[20:23]
	v_mfma_f32_16x16x32_bf16 v[16:19], v[170:173], v[200:203], v[16:19]
	v_mfma_f32_16x16x32_bf16 v[4:7], v[162:165], v[210:213], v[4:7]
	v_mfma_f32_16x16x32_bf16 v[0:3], v[170:173], v[210:213], v[0:3]
	v_mfma_f32_16x16x32_bf16 v[52:55], v[166:169], v[184:187], v[52:55]
	v_mfma_f32_16x16x32_bf16 v[48:51], v[174:177], v[184:187], v[48:51]
	v_mfma_f32_16x16x32_bf16 v[36:39], v[166:169], v[194:197], v[36:39]
	v_mfma_f32_16x16x32_bf16 v[32:35], v[174:177], v[194:197], v[32:35]
	v_mfma_f32_16x16x32_bf16 v[20:23], v[166:169], v[206:209], v[20:23]
	v_mfma_f32_16x16x32_bf16 v[16:19], v[174:177], v[206:209], v[16:19]
	v_mfma_f32_16x16x32_bf16 v[4:7], v[166:169], v[214:217], v[4:7]
	v_mfma_f32_16x16x32_bf16 v[0:3], v[174:177], v[214:217], v[0:3]
	s_setprio 0
	s_barrier
	s_add_i32 s30, s30, 2
	s_add_u32 s12, s12, 0x100
	s_addc_u32 s13, s13, 0
	s_cmp_gt_u32 s30, 61
	s_cbranch_scc0 .LBB0_684
	s_cmpk_lt_u32 s18, 0x100
	s_cbranch_scc0 .LBB0_687
	s_barrier

.LBB0_767:
	s_ashr_i32 s31, s30, 31
	s_lshl_b64 s[34:35], s[30:31], 19
	s_add_u32 s34, s41, s34
	s_addc_u32 s35, s46, s35
	s_and_b64 s[36:37], s[8:9], exec
	s_cselect_b32 s1, s35, s11
	s_cselect_b32 s3, s34, s10
	s_ashr_i32 s29, s28, 31
	s_lshl_b64 s[36:37], s[28:29], 19
	s_add_u32 s36, s47, s36
	s_addc_u32 s37, s48, s37
	s_and_b64 s[44:45], s[8:9], exec
	s_cselect_b32 s29, s37, s13
	s_cselect_b32 s31, s36, s12
	s_add_u32 s10, s10, 0x40080
	s_addc_u32 s11, s11, 0
	s_add_u32 s33, s12, 0x100
	s_addc_u32 s67, s13, 0
	s_mov_b32 s68, -2
	ds_read_b128 v[32:35], v232
	ds_read_b128 v[36:39], v232 offset:1024
	ds_read_b128 v[40:43], v232 offset:2048
	ds_read_b128 v[44:47], v232 offset:3072
	ds_read_b128 v[48:51], v233
	ds_read_b128 v[56:59], v233 offset:1024
	ds_read_b128 v[64:67], v233 offset:2048
	ds_read_b128 v[68:71], v233 offset:3072
	s_add_u32 s12, s10, 0xfffc0080
	s_addc_u32 s13, s11, -1
	s_cmp_eq_u32 s68, 12
	s_cselect_b32 s45, s1, s13
	s_cselect_b32 s44, s3, s12
	s_cselect_b32 s13, s29, s67
	s_cselect_b32 s12, s31, s33
	v_lshl_add_u64 v[218:219], s[10:11], 0, v[208:209]
	s_add_i32 m0, s50, 0xc000
	ds_read_b128 v[160:163], v234
	ds_read_b128 v[164:167], v234 offset:1024
	ds_read_b128 v[168:171], v234 offset:2048
	ds_read_b128 v[172:175], v234 offset:3072
	ds_read_b128 v[176:179], v234 offset:4096
	ds_read_b128 v[180:183], v234 offset:5120
	ds_read_b128 v[184:187], v234 offset:6144
	ds_read_b128 v[188:191], v234 offset:7168
	global_load_lds_dwordx4 v[218:219], off
	v_lshl_add_u64 v[218:219], s[10:11], 0, v[210:211]
	s_add_i32 m0, s50, 0xe000
	s_nop 0
	global_load_lds_dwordx4 v[218:219], off
	s_waitcnt vmcnt(8)
	s_waitcnt lgkmcnt(0)
	s_barrier
	s_setprio 1
	v_mfma_f32_16x16x32_bf16 v[156:159], v[32:35], v[160:163], 0
	v_mfma_f32_16x16x32_bf16 v[152:155], v[40:43], v[160:163], 0
	v_mfma_f32_16x16x32_bf16 v[140:143], v[32:35], v[168:171], 0
	v_mfma_f32_16x16x32_bf16 v[136:139], v[40:43], v[168:171], 0
	v_mfma_f32_16x16x32_bf16 v[124:127], v[32:35], v[176:179], 0
	v_mfma_f32_16x16x32_bf16 v[120:123], v[40:43], v[176:179], 0
	v_mfma_f32_16x16x32_bf16 v[108:111], v[32:35], v[184:187], 0
	v_mfma_f32_16x16x32_bf16 v[104:107], v[40:43], v[184:187], 0
	v_mfma_f32_16x16x32_bf16 v[156:159], v[36:39], v[164:167], v[156:159]
	v_mfma_f32_16x16x32_bf16 v[152:155], v[44:47], v[164:167], v[152:155]
	v_mfma_f32_16x16x32_bf16 v[140:143], v[36:39], v[172:175], v[140:143]
	v_mfma_f32_16x16x32_bf16 v[136:139], v[44:47], v[172:175], v[136:139]
	v_mfma_f32_16x16x32_bf16 v[124:127], v[36:39], v[180:183], v[124:127]
	v_mfma_f32_16x16x32_bf16 v[120:123], v[44:47], v[180:183], v[120:123]
	v_mfma_f32_16x16x32_bf16 v[108:111], v[36:39], v[188:191], v[108:111]
	v_mfma_f32_16x16x32_bf16 v[104:107], v[44:47], v[188:191], v[104:107]
	s_setprio 0
	s_setprio 1
	v_mfma_f32_16x16x32_bf16 v[148:151], v[48:51], v[160:163], 0
	v_mfma_f32_16x16x32_bf16 v[144:147], v[64:67], v[160:163], 0
	v_mfma_f32_16x16x32_bf16 v[132:135], v[48:51], v[168:171], 0
	v_mfma_f32_16x16x32_bf16 v[128:131], v[64:67], v[168:171], 0
	v_mfma_f32_16x16x32_bf16 v[116:119], v[48:51], v[176:179], 0
	v_mfma_f32_16x16x32_bf16 v[112:115], v[64:67], v[176:179], 0
	v_mfma_f32_16x16x32_bf16 v[100:103], v[48:51], v[184:187], 0
	v_mfma_f32_16x16x32_bf16 v[96:99], v[64:67], v[184:187], 0
	v_mfma_f32_16x16x32_bf16 v[148:151], v[56:59], v[164:167], v[148:151]
	v_mfma_f32_16x16x32_bf16 v[144:147], v[68:71], v[164:167], v[144:147]
	v_mfma_f32_16x16x32_bf16 v[132:135], v[56:59], v[172:175], v[132:135]
	v_mfma_f32_16x16x32_bf16 v[128:131], v[68:71], v[172:175], v[128:131]
	v_mfma_f32_16x16x32_bf16 v[116:119], v[56:59], v[180:183], v[116:119]
	v_mfma_f32_16x16x32_bf16 v[112:115], v[68:71], v[180:183], v[112:115]
	v_mfma_f32_16x16x32_bf16 v[100:103], v[56:59], v[188:191], v[100:103]
	v_mfma_f32_16x16x32_bf16 v[96:99], v[68:71], v[188:191], v[96:99]
	s_setprio 0
	s_barrier
	s_add_i32 s69, s63, s49
	v_lshl_add_u64 v[222:223], s[12:13], 0, v[196:197]
	s_mov_b32 m0, s69
	ds_read_b128 v[160:163], v234 offset:16384
	ds_read_b128 v[164:167], v234 offset:17408
	ds_read_b128 v[168:171], v234 offset:18432
	ds_read_b128 v[172:175], v234 offset:19456
	ds_read_b128 v[176:179], v234 offset:20480
	ds_read_b128 v[180:183], v234 offset:21504
	ds_read_b128 v[184:187], v234 offset:22528
	ds_read_b128 v[188:191], v234 offset:23552
	global_load_lds_dwordx4 v[222:223], off
	s_add_i32 m0, s69, 0x2000
	s_add_u32 s70, s12, 0x40000
	v_lshl_add_u64 v[224:225], s[12:13], 0, v[200:201]
	s_addc_u32 s71, s13, 0
	s_add_i32 s69, s64, s49
	global_load_lds_dwordx4 v[224:225], off
	v_lshl_add_u64 v[218:219], s[70:71], 0, v[196:197]
	s_mov_b32 m0, s69
	v_lshl_add_u64 v[240:241], s[44:45], 0, v[194:195]
	global_load_lds_dwordx4 v[218:219], off
	v_lshl_add_u64 v[218:219], s[70:71], 0, v[200:201]
	s_add_i32 m0, s69, 0x2000
	v_lshl_add_u64 v[242:243], s[44:45], 0, v[198:199]
	global_load_lds_dwordx4 v[218:219], off
	s_mov_b32 m0, s50
	s_nop 0
	global_load_lds_dwordx4 v[240:241], off
	s_mov_b32 m0, s51
	s_nop 0
	global_load_lds_dwordx4 v[242:243], off
	s_waitcnt vmcnt(8)
	s_waitcnt lgkmcnt(0)
	s_barrier
	s_setprio 1
	v_mfma_f32_16x16x32_bf16 v[92:95], v[32:35], v[160:163], 0
	v_mfma_f32_16x16x32_bf16 v[88:91], v[40:43], v[160:163], 0
	v_mfma_f32_16x16x32_bf16 v[76:79], v[32:35], v[168:171], 0
	v_mfma_f32_16x16x32_bf16 v[72:75], v[40:43], v[168:171], 0
	v_mfma_f32_16x16x32_bf16 v[28:31], v[32:35], v[176:179], 0
	v_mfma_f32_16x16x32_bf16 v[24:27], v[40:43], v[176:179], 0
	v_mfma_f32_16x16x32_bf16 v[12:15], v[32:35], v[184:187], 0
	v_mfma_f32_16x16x32_bf16 v[8:11], v[40:43], v[184:187], 0
	v_mfma_f32_16x16x32_bf16 v[92:95], v[36:39], v[164:167], v[92:95]
	v_mfma_f32_16x16x32_bf16 v[88:91], v[44:47], v[164:167], v[88:91]
	v_mfma_f32_16x16x32_bf16 v[76:79], v[36:39], v[172:175], v[76:79]
	v_mfma_f32_16x16x32_bf16 v[72:75], v[44:47], v[172:175], v[72:75]
	v_mfma_f32_16x16x32_bf16 v[28:31], v[36:39], v[180:183], v[28:31]
	v_mfma_f32_16x16x32_bf16 v[24:27], v[44:47], v[180:183], v[24:27]
	v_mfma_f32_16x16x32_bf16 v[12:15], v[36:39], v[188:191], v[12:15]
	v_mfma_f32_16x16x32_bf16 v[8:11], v[44:47], v[188:191], v[8:11]
	s_setprio 0
	s_setprio 1
	v_mfma_f32_16x16x32_bf16 v[20:23], v[48:51], v[176:179], 0
	v_mfma_f32_16x16x32_bf16 v[16:19], v[64:67], v[176:179], 0
	v_mfma_f32_16x16x32_bf16 v[4:7], v[48:51], v[184:187], 0
	v_mfma_f32_16x16x32_bf16 v[0:3], v[64:67], v[184:187], 0
	v_mfma_f32_16x16x32_bf16 v[32:35], v[48:51], v[160:163], 0
	v_mfma_f32_16x16x32_bf16 v[36:39], v[64:67], v[160:163], 0
	v_mfma_f32_16x16x32_bf16 v[40:43], v[48:51], v[168:171], 0
	v_mfma_f32_16x16x32_bf16 v[44:47], v[64:67], v[168:171], 0
	v_mfma_f32_16x16x32_bf16 v[20:23], v[56:59], v[180:183], v[20:23]
	v_mfma_f32_16x16x32_bf16 v[16:19], v[68:71], v[180:183], v[16:19]
	v_mfma_f32_16x16x32_bf16 v[4:7], v[56:59], v[188:191], v[4:7]
	v_mfma_f32_16x16x32_bf16 v[0:3], v[68:71], v[188:191], v[0:3]
	v_mfma_f32_16x16x32_bf16 v[32:35], v[56:59], v[164:167], v[32:35]
	v_mfma_f32_16x16x32_bf16 v[36:39], v[68:71], v[164:167], v[36:39]
	v_mfma_f32_16x16x32_bf16 v[40:43], v[56:59], v[172:175], v[40:43]
	v_mfma_f32_16x16x32_bf16 v[44:47], v[68:71], v[172:175], v[44:47]
	s_setprio 0
	s_barrier
	s_add_i32 s69, 0, 0x18000
	s_add_i32 s70, 0, 0x1c000
	v_add_u32_e32 v60, s69, v231
	v_add_u32_e32 v80, s70, v231
	ds_read_b128 v[48:51], v60
	ds_read_b128 v[52:55], v60 offset:1024
	ds_read_b128 v[56:59], v60 offset:2048
	ds_read_b128 v[60:63], v60 offset:3072
	ds_read_b128 v[64:67], v80
	ds_read_b128 v[68:71], v80 offset:1024
	ds_read_b128 v[160:163], v80 offset:2048
	ds_read_b128 v[164:167], v80 offset:3072
	s_add_u32 s44, s44, 0x40000
	s_addc_u32 s45, s45, 0
	s_mov_b32 m0, s54
	v_lshl_add_u64 v[218:219], s[44:45], 0, v[194:195]
	ds_read_b128 v[80:83], v234 offset:32768
	ds_read_b128 v[84:87], v234 offset:33792
	ds_read_b128 v[168:171], v234 offset:34816
	ds_read_b128 v[172:175], v234 offset:35840
	ds_read_b128 v[176:179], v234 offset:36864
	ds_read_b128 v[180:183], v234 offset:37888
	ds_read_b128 v[184:187], v234 offset:38912
	ds_read_b128 v[188:191], v234 offset:39936
	global_load_lds_dwordx4 v[218:219], off
	v_lshl_add_u64 v[218:219], s[44:45], 0, v[198:199]
	s_mov_b32 m0, s55
	s_nop 0
	global_load_lds_dwordx4 v[218:219], off
	s_waitcnt vmcnt(8)
	s_waitcnt lgkmcnt(0)
	s_barrier
	s_setprio 1
	v_mfma_f32_16x16x32_bf16 v[156:159], v[48:51], v[80:83], v[156:159]
	v_mfma_f32_16x16x32_bf16 v[152:155], v[56:59], v[80:83], v[152:155]
	v_mfma_f32_16x16x32_bf16 v[140:143], v[48:51], v[168:171], v[140:143]
	v_mfma_f32_16x16x32_bf16 v[136:139], v[56:59], v[168:171], v[136:139]
	v_mfma_f32_16x16x32_bf16 v[124:127], v[48:51], v[176:179], v[124:127]
	v_mfma_f32_16x16x32_bf16 v[120:123], v[56:59], v[176:179], v[120:123]
	v_mfma_f32_16x16x32_bf16 v[108:111], v[48:51], v[184:187], v[108:111]
	v_mfma_f32_16x16x32_bf16 v[104:107], v[56:59], v[184:187], v[104:107]
	v_mfma_f32_16x16x32_bf16 v[156:159], v[52:55], v[84:87], v[156:159]
	v_mfma_f32_16x16x32_bf16 v[152:155], v[60:63], v[84:87], v[152:155]
	v_mfma_f32_16x16x32_bf16 v[140:143], v[52:55], v[172:175], v[140:143]
	v_mfma_f32_16x16x32_bf16 v[136:139], v[60:63], v[172:175], v[136:139]
	v_mfma_f32_16x16x32_bf16 v[124:127], v[52:55], v[180:183], v[124:127]
	v_mfma_f32_16x16x32_bf16 v[120:123], v[60:63], v[180:183], v[120:123]
	v_mfma_f32_16x16x32_bf16 v[108:111], v[52:55], v[188:191], v[108:111]
	v_mfma_f32_16x16x32_bf16 v[104:107], v[60:63], v[188:191], v[104:107]
	s_setprio 0
	s_setprio 1
	v_mfma_f32_16x16x32_bf16 v[148:151], v[64:67], v[80:83], v[148:151]
	v_mfma_f32_16x16x32_bf16 v[80:83], v[160:163], v[80:83], v[144:147]
	v_mfma_f32_16x16x32_bf16 v[144:147], v[164:167], v[84:87], v[80:83]
	v_mfma_f32_16x16x32_bf16 v[80:83], v[64:67], v[168:171], v[132:135]
	v_mfma_f32_16x16x32_bf16 v[132:135], v[68:71], v[172:175], v[80:83]
	v_mfma_f32_16x16x32_bf16 v[80:83], v[160:163], v[168:171], v[128:131]
	v_mfma_f32_16x16x32_bf16 v[128:131], v[164:167], v[172:175], v[80:83]
	v_mfma_f32_16x16x32_bf16 v[80:83], v[64:67], v[176:179], v[116:119]
	v_mfma_f32_16x16x32_bf16 v[116:119], v[68:71], v[180:183], v[80:83]
	v_mfma_f32_16x16x32_bf16 v[80:83], v[160:163], v[176:179], v[112:115]
	v_mfma_f32_16x16x32_bf16 v[112:115], v[164:167], v[180:183], v[80:83]
	v_mfma_f32_16x16x32_bf16 v[80:83], v[64:67], v[184:187], v[100:103]
	v_mfma_f32_16x16x32_bf16 v[100:103], v[68:71], v[188:191], v[80:83]
	v_mfma_f32_16x16x32_bf16 v[80:83], v[160:163], v[184:187], v[96:99]
	v_mfma_f32_16x16x32_bf16 v[148:151], v[68:71], v[84:87], v[148:151]
	v_mfma_f32_16x16x32_bf16 v[96:99], v[164:167], v[188:191], v[80:83]
	s_setprio 0
	s_barrier
	s_add_i32 s44, s69, s49
	v_lshl_add_u64 v[84:85], v[222:223], 0, s[24:25]
	s_mov_b32 m0, s44
	s_nop 0
	ds_read_b128 v[80:83], v234 offset:49152
	ds_read_b128 v[168:171], v234 offset:50176
	ds_read_b128 v[172:175], v234 offset:51200
	ds_read_b128 v[176:179], v234 offset:52224
	ds_read_b128 v[180:183], v234 offset:53248
	ds_read_b128 v[184:187], v234 offset:54272
	ds_read_b128 v[188:191], v234 offset:55296
	ds_read_b128 v[218:221], v234 offset:56320
	global_load_lds_dwordx4 v[84:85], off
	s_add_i32 m0, s44, 0x2000
	s_add_u32 s12, s12, 0x40080
	v_lshl_add_u64 v[84:85], v[224:225], 0, s[24:25]
	s_addc_u32 s13, s13, 0
	s_add_i32 s44, s70, s49
	global_load_lds_dwordx4 v[84:85], off
	v_lshl_add_u64 v[84:85], s[12:13], 0, v[196:197]
	s_mov_b32 m0, s44
	s_nop 0
	global_load_lds_dwordx4 v[84:85], off
	v_lshl_add_u64 v[84:85], s[12:13], 0, v[200:201]
	s_add_i32 m0, s44, 0x2000
	s_nop 0
	global_load_lds_dwordx4 v[84:85], off
	v_lshl_add_u64 v[84:85], v[240:241], 0, s[24:25]
	s_mov_b32 m0, s58
	s_nop 0
	global_load_lds_dwordx4 v[84:85], off
	v_lshl_add_u64 v[84:85], v[242:243], 0, s[24:25]
	s_mov_b32 m0, s59
	s_nop 0
	global_load_lds_dwordx4 v[84:85], off
	s_waitcnt vmcnt(8)
	s_waitcnt lgkmcnt(0)
	s_barrier
	s_setprio 1
	v_mfma_f32_16x16x32_bf16 v[84:87], v[48:51], v[80:83], v[92:95]
	v_mfma_f32_16x16x32_bf16 v[92:95], v[52:55], v[168:171], v[84:87]
	v_mfma_f32_16x16x32_bf16 v[84:87], v[56:59], v[80:83], v[88:91]
	v_mfma_f32_16x16x32_bf16 v[76:79], v[48:51], v[172:175], v[76:79]
	v_mfma_f32_16x16x32_bf16 v[72:75], v[56:59], v[172:175], v[72:75]
	v_mfma_f32_16x16x32_bf16 v[28:31], v[48:51], v[180:183], v[28:31]
	v_mfma_f32_16x16x32_bf16 v[24:27], v[56:59], v[180:183], v[24:27]
	v_mfma_f32_16x16x32_bf16 v[12:15], v[48:51], v[188:191], v[12:15]
	v_mfma_f32_16x16x32_bf16 v[8:11], v[56:59], v[188:191], v[8:11]
	v_mfma_f32_16x16x32_bf16 v[88:91], v[60:63], v[168:171], v[84:87]
	v_mfma_f32_16x16x32_bf16 v[76:79], v[52:55], v[176:179], v[76:79]
	v_mfma_f32_16x16x32_bf16 v[72:75], v[60:63], v[176:179], v[72:75]
	v_mfma_f32_16x16x32_bf16 v[28:31], v[52:55], v[184:187], v[28:31]
	v_mfma_f32_16x16x32_bf16 v[24:27], v[60:63], v[184:187], v[24:27]
	v_mfma_f32_16x16x32_bf16 v[12:15], v[52:55], v[218:221], v[12:15]
	v_mfma_f32_16x16x32_bf16 v[8:11], v[60:63], v[218:221], v[8:11]
	s_setprio 0
	s_setprio 1
	v_mfma_f32_16x16x32_bf16 v[32:35], v[64:67], v[80:83], v[32:35]
	v_mfma_f32_16x16x32_bf16 v[84:87], v[68:71], v[168:171], v[32:35]
	v_mfma_f32_16x16x32_bf16 v[32:35], v[160:163], v[80:83], v[36:39]
	v_mfma_f32_16x16x32_bf16 v[80:83], v[164:167], v[168:171], v[32:35]
	v_mfma_f32_16x16x32_bf16 v[32:35], v[64:67], v[172:175], v[40:43]
	v_mfma_f32_16x16x32_bf16 v[60:63], v[68:71], v[176:179], v[32:35]
	v_mfma_f32_16x16x32_bf16 v[32:35], v[160:163], v[172:175], v[44:47]
	v_mfma_f32_16x16x32_bf16 v[20:23], v[64:67], v[180:183], v[20:23]
	v_mfma_f32_16x16x32_bf16 v[16:19], v[160:163], v[180:183], v[16:19]
	v_mfma_f32_16x16x32_bf16 v[4:7], v[64:67], v[188:191], v[4:7]
	v_mfma_f32_16x16x32_bf16 v[0:3], v[160:163], v[188:191], v[0:3]
	v_mfma_f32_16x16x32_bf16 v[52:55], v[164:167], v[176:179], v[32:35]
	v_mfma_f32_16x16x32_bf16 v[20:23], v[68:71], v[184:187], v[20:23]
	v_mfma_f32_16x16x32_bf16 v[16:19], v[164:167], v[184:187], v[16:19]
	v_mfma_f32_16x16x32_bf16 v[4:7], v[68:71], v[218:221], v[4:7]
	v_mfma_f32_16x16x32_bf16 v[0:3], v[164:167], v[218:221], v[0:3]
	s_setprio 0
	s_barrier
	s_add_i32 s68, s68, 2
	s_add_u32 s10, s10, 0x100
	s_addc_u32 s11, s11, 0
	s_add_u32 s33, s33, 0x100
	s_addc_u32 s67, s67, 0
	s_cmp_gt_u32 s68, 13
.LBB0_768:
	ds_read_b128 v[32:35], v232
	ds_read_b128 v[36:39], v232 offset:1024
	ds_read_b128 v[40:43], v232 offset:2048
	ds_read_b128 v[44:47], v232 offset:3072
	ds_read_b128 v[48:51], v233
	ds_read_b128 v[56:59], v233 offset:1024
	ds_read_b128 v[64:67], v233 offset:2048
	ds_read_b128 v[68:71], v233 offset:3072
	s_add_u32 s12, s10, 0xfffc0080
	s_addc_u32 s13, s11, -1
	s_cmp_eq_u32 s68, 12
	s_cselect_b32 s45, s1, s13
	s_cselect_b32 s44, s3, s12
	s_cselect_b32 s13, s29, s67
	s_cselect_b32 s12, s31, s33
	v_lshl_add_u64 v[218:219], s[10:11], 0, v[208:209]
	s_add_i32 m0, s50, 0xc000
	ds_read_b128 v[160:163], v234
	ds_read_b128 v[164:167], v234 offset:1024
	ds_read_b128 v[168:171], v234 offset:2048
	ds_read_b128 v[172:175], v234 offset:3072
	ds_read_b128 v[176:179], v234 offset:4096
	ds_read_b128 v[180:183], v234 offset:5120
	ds_read_b128 v[184:187], v234 offset:6144
	ds_read_b128 v[188:191], v234 offset:7168
	global_load_lds_dwordx4 v[218:219], off
	v_lshl_add_u64 v[218:219], s[10:11], 0, v[210:211]
	s_add_i32 m0, s50, 0xe000
	s_nop 0
	global_load_lds_dwordx4 v[218:219], off
	s_waitcnt vmcnt(8)
	s_waitcnt lgkmcnt(0)
	s_barrier
	s_setprio 1
	v_mfma_f32_16x16x32_bf16 v[156:159], v[32:35], v[160:163], v[156:159]
	v_mfma_f32_16x16x32_bf16 v[152:155], v[40:43], v[160:163], v[152:155]
	v_mfma_f32_16x16x32_bf16 v[140:143], v[32:35], v[168:171], v[140:143]
	v_mfma_f32_16x16x32_bf16 v[136:139], v[40:43], v[168:171], v[136:139]
	v_mfma_f32_16x16x32_bf16 v[124:127], v[32:35], v[176:179], v[124:127]
	v_mfma_f32_16x16x32_bf16 v[120:123], v[40:43], v[176:179], v[120:123]
	v_mfma_f32_16x16x32_bf16 v[108:111], v[32:35], v[184:187], v[108:111]
	v_mfma_f32_16x16x32_bf16 v[104:107], v[40:43], v[184:187], v[104:107]
	v_mfma_f32_16x16x32_bf16 v[156:159], v[36:39], v[164:167], v[156:159]
	v_mfma_f32_16x16x32_bf16 v[152:155], v[44:47], v[164:167], v[152:155]
	v_mfma_f32_16x16x32_bf16 v[140:143], v[36:39], v[172:175], v[140:143]
	v_mfma_f32_16x16x32_bf16 v[136:139], v[44:47], v[172:175], v[136:139]
	v_mfma_f32_16x16x32_bf16 v[124:127], v[36:39], v[180:183], v[124:127]
	v_mfma_f32_16x16x32_bf16 v[120:123], v[44:47], v[180:183], v[120:123]
	v_mfma_f32_16x16x32_bf16 v[108:111], v[36:39], v[188:191], v[108:111]
	v_mfma_f32_16x16x32_bf16 v[104:107], v[44:47], v[188:191], v[104:107]
	s_setprio 0
	s_setprio 1
	v_mfma_f32_16x16x32_bf16 v[148:151], v[48:51], v[160:163], v[148:151]
	v_mfma_f32_16x16x32_bf16 v[144:147], v[64:67], v[160:163], v[144:147]
	v_mfma_f32_16x16x32_bf16 v[132:135], v[48:51], v[168:171], v[132:135]
	v_mfma_f32_16x16x32_bf16 v[128:131], v[64:67], v[168:171], v[128:131]
	v_mfma_f32_16x16x32_bf16 v[116:119], v[48:51], v[176:179], v[116:119]
	v_mfma_f32_16x16x32_bf16 v[112:115], v[64:67], v[176:179], v[112:115]
	v_mfma_f32_16x16x32_bf16 v[100:103], v[48:51], v[184:187], v[100:103]
	v_mfma_f32_16x16x32_bf16 v[96:99], v[64:67], v[184:187], v[96:99]
	v_mfma_f32_16x16x32_bf16 v[148:151], v[56:59], v[164:167], v[148:151]
	v_mfma_f32_16x16x32_bf16 v[144:147], v[68:71], v[164:167], v[144:147]
	v_mfma_f32_16x16x32_bf16 v[132:135], v[56:59], v[172:175], v[132:135]
	v_mfma_f32_16x16x32_bf16 v[128:131], v[68:71], v[172:175], v[128:131]
	v_mfma_f32_16x16x32_bf16 v[116:119], v[56:59], v[180:183], v[116:119]
	v_mfma_f32_16x16x32_bf16 v[112:115], v[68:71], v[180:183], v[112:115]
	v_mfma_f32_16x16x32_bf16 v[100:103], v[56:59], v[188:191], v[100:103]
	v_mfma_f32_16x16x32_bf16 v[96:99], v[68:71], v[188:191], v[96:99]
	s_setprio 0
	s_barrier
	s_add_i32 s69, s63, s49
	v_lshl_add_u64 v[222:223], s[12:13], 0, v[196:197]
	s_mov_b32 m0, s69
	ds_read_b128 v[160:163], v234 offset:16384
	ds_read_b128 v[164:167], v234 offset:17408
	ds_read_b128 v[168:171], v234 offset:18432
	ds_read_b128 v[172:175], v234 offset:19456
	ds_read_b128 v[176:179], v234 offset:20480
	ds_read_b128 v[180:183], v234 offset:21504
	ds_read_b128 v[184:187], v234 offset:22528
	ds_read_b128 v[188:191], v234 offset:23552
	global_load_lds_dwordx4 v[222:223], off
	s_add_i32 m0, s69, 0x2000
	s_add_u32 s70, s12, 0x40000
	v_lshl_add_u64 v[224:225], s[12:13], 0, v[200:201]
	s_addc_u32 s71, s13, 0
	s_add_i32 s69, s64, s49
	global_load_lds_dwordx4 v[224:225], off
	v_lshl_add_u64 v[218:219], s[70:71], 0, v[196:197]
	s_mov_b32 m0, s69
	v_lshl_add_u64 v[240:241], s[44:45], 0, v[194:195]
	global_load_lds_dwordx4 v[218:219], off
	v_lshl_add_u64 v[218:219], s[70:71], 0, v[200:201]
	s_add_i32 m0, s69, 0x2000
	v_lshl_add_u64 v[242:243], s[44:45], 0, v[198:199]
	global_load_lds_dwordx4 v[218:219], off
	s_mov_b32 m0, s50
	s_nop 0
	global_load_lds_dwordx4 v[240:241], off
	s_mov_b32 m0, s51
	s_nop 0
	global_load_lds_dwordx4 v[242:243], off
	s_waitcnt vmcnt(8)
	s_waitcnt lgkmcnt(0)
	s_barrier
	s_setprio 1
	v_mfma_f32_16x16x32_bf16 v[92:95], v[32:35], v[160:163], v[92:95]
	v_mfma_f32_16x16x32_bf16 v[88:91], v[40:43], v[160:163], v[88:91]
	v_mfma_f32_16x16x32_bf16 v[76:79], v[32:35], v[168:171], v[76:79]
	v_mfma_f32_16x16x32_bf16 v[72:75], v[40:43], v[168:171], v[72:75]
	v_mfma_f32_16x16x32_bf16 v[28:31], v[32:35], v[176:179], v[28:31]
	v_mfma_f32_16x16x32_bf16 v[24:27], v[40:43], v[176:179], v[24:27]
	v_mfma_f32_16x16x32_bf16 v[12:15], v[32:35], v[184:187], v[12:15]
	v_mfma_f32_16x16x32_bf16 v[8:11], v[40:43], v[184:187], v[8:11]
	v_mfma_f32_16x16x32_bf16 v[92:95], v[36:39], v[164:167], v[92:95]
	v_mfma_f32_16x16x32_bf16 v[88:91], v[44:47], v[164:167], v[88:91]
	v_mfma_f32_16x16x32_bf16 v[76:79], v[36:39], v[172:175], v[76:79]
	v_mfma_f32_16x16x32_bf16 v[72:75], v[44:47], v[172:175], v[72:75]
	v_mfma_f32_16x16x32_bf16 v[28:31], v[36:39], v[180:183], v[28:31]
	v_mfma_f32_16x16x32_bf16 v[24:27], v[44:47], v[180:183], v[24:27]
	v_mfma_f32_16x16x32_bf16 v[12:15], v[36:39], v[188:191], v[12:15]
	v_mfma_f32_16x16x32_bf16 v[8:11], v[44:47], v[188:191], v[8:11]
	s_setprio 0
	s_setprio 1
	v_mfma_f32_16x16x32_bf16 v[20:23], v[48:51], v[176:179], v[20:23]
	v_mfma_f32_16x16x32_bf16 v[16:19], v[64:67], v[176:179], v[16:19]
	v_mfma_f32_16x16x32_bf16 v[4:7], v[48:51], v[184:187], v[4:7]
	v_mfma_f32_16x16x32_bf16 v[0:3], v[64:67], v[184:187], v[0:3]
	v_mfma_f32_16x16x32_bf16 v[32:35], v[48:51], v[160:163], v[84:87]
	v_mfma_f32_16x16x32_bf16 v[36:39], v[64:67], v[160:163], v[80:83]
	v_mfma_f32_16x16x32_bf16 v[40:43], v[48:51], v[168:171], v[60:63]
	v_mfma_f32_16x16x32_bf16 v[44:47], v[64:67], v[168:171], v[52:55]
	v_mfma_f32_16x16x32_bf16 v[20:23], v[56:59], v[180:183], v[20:23]
	v_mfma_f32_16x16x32_bf16 v[16:19], v[68:71], v[180:183], v[16:19]
	v_mfma_f32_16x16x32_bf16 v[4:7], v[56:59], v[188:191], v[4:7]
	v_mfma_f32_16x16x32_bf16 v[0:3], v[68:71], v[188:191], v[0:3]
	v_mfma_f32_16x16x32_bf16 v[32:35], v[56:59], v[164:167], v[32:35]
	v_mfma_f32_16x16x32_bf16 v[36:39], v[68:71], v[164:167], v[36:39]
	v_mfma_f32_16x16x32_bf16 v[40:43], v[56:59], v[172:175], v[40:43]
	v_mfma_f32_16x16x32_bf16 v[44:47], v[68:71], v[172:175], v[44:47]
	s_setprio 0
	s_barrier
	s_add_i32 s69, 0, 0x18000
	s_add_i32 s70, 0, 0x1c000
	v_add_u32_e32 v60, s69, v231
	v_add_u32_e32 v80, s70, v231
	ds_read_b128 v[48:51], v60
	ds_read_b128 v[52:55], v60 offset:1024
	ds_read_b128 v[56:59], v60 offset:2048
	ds_read_b128 v[60:63], v60 offset:3072
	ds_read_b128 v[64:67], v80
	ds_read_b128 v[68:71], v80 offset:1024
	ds_read_b128 v[160:163], v80 offset:2048
	ds_read_b128 v[164:167], v80 offset:3072
	s_add_u32 s44, s44, 0x40000
	s_addc_u32 s45, s45, 0
	s_mov_b32 m0, s54
	v_lshl_add_u64 v[218:219], s[44:45], 0, v[194:195]
	ds_read_b128 v[80:83], v234 offset:32768
	ds_read_b128 v[84:87], v234 offset:33792
	ds_read_b128 v[168:171], v234 offset:34816
	ds_read_b128 v[172:175], v234 offset:35840
	ds_read_b128 v[176:179], v234 offset:36864
	ds_read_b128 v[180:183], v234 offset:37888
	ds_read_b128 v[184:187], v234 offset:38912
	ds_read_b128 v[188:191], v234 offset:39936
	global_load_lds_dwordx4 v[218:219], off
	v_lshl_add_u64 v[218:219], s[44:45], 0, v[198:199]
	s_mov_b32 m0, s55
	s_nop 0
	global_load_lds_dwordx4 v[218:219], off
	s_waitcnt vmcnt(8)
	s_waitcnt lgkmcnt(0)
	s_barrier
	s_setprio 1
	v_mfma_f32_16x16x32_bf16 v[156:159], v[48:51], v[80:83], v[156:159]
	v_mfma_f32_16x16x32_bf16 v[152:155], v[56:59], v[80:83], v[152:155]
	v_mfma_f32_16x16x32_bf16 v[140:143], v[48:51], v[168:171], v[140:143]
	v_mfma_f32_16x16x32_bf16 v[136:139], v[56:59], v[168:171], v[136:139]
	v_mfma_f32_16x16x32_bf16 v[124:127], v[48:51], v[176:179], v[124:127]
	v_mfma_f32_16x16x32_bf16 v[120:123], v[56:59], v[176:179], v[120:123]
	v_mfma_f32_16x16x32_bf16 v[108:111], v[48:51], v[184:187], v[108:111]
	v_mfma_f32_16x16x32_bf16 v[104:107], v[56:59], v[184:187], v[104:107]
	v_mfma_f32_16x16x32_bf16 v[156:159], v[52:55], v[84:87], v[156:159]
	v_mfma_f32_16x16x32_bf16 v[152:155], v[60:63], v[84:87], v[152:155]
	v_mfma_f32_16x16x32_bf16 v[140:143], v[52:55], v[172:175], v[140:143]
	v_mfma_f32_16x16x32_bf16 v[136:139], v[60:63], v[172:175], v[136:139]
	v_mfma_f32_16x16x32_bf16 v[124:127], v[52:55], v[180:183], v[124:127]
	v_mfma_f32_16x16x32_bf16 v[120:123], v[60:63], v[180:183], v[120:123]
	v_mfma_f32_16x16x32_bf16 v[108:111], v[52:55], v[188:191], v[108:111]
	v_mfma_f32_16x16x32_bf16 v[104:107], v[60:63], v[188:191], v[104:107]
	s_setprio 0
	s_setprio 1
	v_mfma_f32_16x16x32_bf16 v[148:151], v[64:67], v[80:83], v[148:151]
	v_mfma_f32_16x16x32_bf16 v[80:83], v[160:163], v[80:83], v[144:147]
	v_mfma_f32_16x16x32_bf16 v[144:147], v[164:167], v[84:87], v[80:83]
	v_mfma_f32_16x16x32_bf16 v[80:83], v[64:67], v[168:171], v[132:135]
	v_mfma_f32_16x16x32_bf16 v[132:135], v[68:71], v[172:175], v[80:83]
	v_mfma_f32_16x16x32_bf16 v[80:83], v[160:163], v[168:171], v[128:131]
	v_mfma_f32_16x16x32_bf16 v[128:131], v[164:167], v[172:175], v[80:83]
	v_mfma_f32_16x16x32_bf16 v[80:83], v[64:67], v[176:179], v[116:119]
	v_mfma_f32_16x16x32_bf16 v[116:119], v[68:71], v[180:183], v[80:83]
	v_mfma_f32_16x16x32_bf16 v[80:83], v[160:163], v[176:179], v[112:115]
	v_mfma_f32_16x16x32_bf16 v[112:115], v[164:167], v[180:183], v[80:83]
	v_mfma_f32_16x16x32_bf16 v[80:83], v[64:67], v[184:187], v[100:103]
	v_mfma_f32_16x16x32_bf16 v[100:103], v[68:71], v[188:191], v[80:83]
	v_mfma_f32_16x16x32_bf16 v[80:83], v[160:163], v[184:187], v[96:99]
	v_mfma_f32_16x16x32_bf16 v[148:151], v[68:71], v[84:87], v[148:151]
	v_mfma_f32_16x16x32_bf16 v[96:99], v[164:167], v[188:191], v[80:83]
	s_setprio 0
	s_barrier
	s_add_i32 s44, s69, s49
	v_lshl_add_u64 v[84:85], v[222:223], 0, s[24:25]
	s_mov_b32 m0, s44
	s_nop 0
	ds_read_b128 v[80:83], v234 offset:49152
	ds_read_b128 v[168:171], v234 offset:50176
	ds_read_b128 v[172:175], v234 offset:51200
	ds_read_b128 v[176:179], v234 offset:52224
	ds_read_b128 v[180:183], v234 offset:53248
	ds_read_b128 v[184:187], v234 offset:54272
	ds_read_b128 v[188:191], v234 offset:55296
	ds_read_b128 v[218:221], v234 offset:56320
	global_load_lds_dwordx4 v[84:85], off
	s_add_i32 m0, s44, 0x2000
	s_add_u32 s12, s12, 0x40080
	v_lshl_add_u64 v[84:85], v[224:225], 0, s[24:25]
	s_addc_u32 s13, s13, 0
	s_add_i32 s44, s70, s49
	global_load_lds_dwordx4 v[84:85], off
	v_lshl_add_u64 v[84:85], s[12:13], 0, v[196:197]
	s_mov_b32 m0, s44
	s_nop 0
	global_load_lds_dwordx4 v[84:85], off
	v_lshl_add_u64 v[84:85], s[12:13], 0, v[200:201]
	s_add_i32 m0, s44, 0x2000
	s_nop 0
	global_load_lds_dwordx4 v[84:85], off
	v_lshl_add_u64 v[84:85], v[240:241], 0, s[24:25]
	s_mov_b32 m0, s58
	s_nop 0
	global_load_lds_dwordx4 v[84:85], off
	v_lshl_add_u64 v[84:85], v[242:243], 0, s[24:25]
	s_mov_b32 m0, s59
	s_nop 0
	global_load_lds_dwordx4 v[84:85], off
	s_waitcnt vmcnt(8)
	s_waitcnt lgkmcnt(0)
	s_barrier
	s_setprio 1
	v_mfma_f32_16x16x32_bf16 v[84:87], v[48:51], v[80:83], v[92:95]
	v_mfma_f32_16x16x32_bf16 v[92:95], v[52:55], v[168:171], v[84:87]
	v_mfma_f32_16x16x32_bf16 v[84:87], v[56:59], v[80:83], v[88:91]
	v_mfma_f32_16x16x32_bf16 v[76:79], v[48:51], v[172:175], v[76:79]
	v_mfma_f32_16x16x32_bf16 v[72:75], v[56:59], v[172:175], v[72:75]
	v_mfma_f32_16x16x32_bf16 v[28:31], v[48:51], v[180:183], v[28:31]
	v_mfma_f32_16x16x32_bf16 v[24:27], v[56:59], v[180:183], v[24:27]
	v_mfma_f32_16x16x32_bf16 v[12:15], v[48:51], v[188:191], v[12:15]
	v_mfma_f32_16x16x32_bf16 v[8:11], v[56:59], v[188:191], v[8:11]
	v_mfma_f32_16x16x32_bf16 v[88:91], v[60:63], v[168:171], v[84:87]
	v_mfma_f32_16x16x32_bf16 v[76:79], v[52:55], v[176:179], v[76:79]
	v_mfma_f32_16x16x32_bf16 v[72:75], v[60:63], v[176:179], v[72:75]
	v_mfma_f32_16x16x32_bf16 v[28:31], v[52:55], v[184:187], v[28:31]
	v_mfma_f32_16x16x32_bf16 v[24:27], v[60:63], v[184:187], v[24:27]
	v_mfma_f32_16x16x32_bf16 v[12:15], v[52:55], v[218:221], v[12:15]
	v_mfma_f32_16x16x32_bf16 v[8:11], v[60:63], v[218:221], v[8:11]
	s_setprio 0
	s_setprio 1
	v_mfma_f32_16x16x32_bf16 v[32:35], v[64:67], v[80:83], v[32:35]
	v_mfma_f32_16x16x32_bf16 v[84:87], v[68:71], v[168:171], v[32:35]
	v_mfma_f32_16x16x32_bf16 v[32:35], v[160:163], v[80:83], v[36:39]
	v_mfma_f32_16x16x32_bf16 v[80:83], v[164:167], v[168:171], v[32:35]
	v_mfma_f32_16x16x32_bf16 v[32:35], v[64:67], v[172:175], v[40:43]
	v_mfma_f32_16x16x32_bf16 v[60:63], v[68:71], v[176:179], v[32:35]
	v_mfma_f32_16x16x32_bf16 v[32:35], v[160:163], v[172:175], v[44:47]
	v_mfma_f32_16x16x32_bf16 v[20:23], v[64:67], v[180:183], v[20:23]
	v_mfma_f32_16x16x32_bf16 v[16:19], v[160:163], v[180:183], v[16:19]
	v_mfma_f32_16x16x32_bf16 v[4:7], v[64:67], v[188:191], v[4:7]
	v_mfma_f32_16x16x32_bf16 v[0:3], v[160:163], v[188:191], v[0:3]
	v_mfma_f32_16x16x32_bf16 v[52:55], v[164:167], v[176:179], v[32:35]
	v_mfma_f32_16x16x32_bf16 v[20:23], v[68:71], v[184:187], v[20:23]
	v_mfma_f32_16x16x32_bf16 v[16:19], v[164:167], v[184:187], v[16:19]
	v_mfma_f32_16x16x32_bf16 v[4:7], v[68:71], v[218:221], v[4:7]
	v_mfma_f32_16x16x32_bf16 v[0:3], v[164:167], v[218:221], v[0:3]
	s_setprio 0
	s_barrier
	s_add_i32 s68, s68, 2
	s_add_u32 s10, s10, 0x100
	s_addc_u32 s11, s11, 0
	s_add_u32 s33, s33, 0x100
	s_addc_u32 s67, s67, 0
	s_cmp_gt_u32 s68, 13
	s_cbranch_scc0 .LBB0_768
	s_and_b64 vcc, exec, s[26:27]
	s_cbranch_vccz .LBB0_771
	s_barrier

.LBB0_952:
	v_bfe_u32 v199, v226, 4, 2
	s_lshl_b32 s6, s6, 5
	v_lshlrev_b32_e32 v11, 6, v226
	v_and_b32_e32 v191, 15, v226
	v_lshlrev_b32_e32 v9, 4, v199
	s_and_b32 s19, s6, 0x60
	v_and_b32_e32 v197, 0x3c0, v11
	v_lshl_or_b32 v132, s7, 6, v191
	v_lshl_or_b32 v10, v191, 6, v9
	s_lshl_b32 s7, s7, 13
	v_and_b32_e32 v196, 32, v160
	v_or_b32_e32 v9, v9, v197
	s_lshl_b32 s6, s19, 7
	v_bitop3_b32 v10, v10, s7, v196 bitop3:0xde
	v_bitop3_b32 v9, s6, v9, v196 bitop3:0xf6
	s_mov_b64 s[6:7], 0x80
	s_add_i32 m0, s15, 0x18000
	v_lshl_add_u64 v[6:7], v[6:7], 0, s[6:7]
	s_waitcnt vmcnt(2)
	s_barrier
	global_load_lds_dwordx4 v[6:7], off
	v_lshl_add_u64 v[4:5], v[4:5], 0, s[6:7]
	s_add_i32 m0, s15, 0x1a000
	s_add_i32 s20, s15, 0x8000
	s_add_i32 s21, s15, 0xa000
	global_load_lds_dwordx4 v[4:5], off
	v_lshl_add_u64 v[2:3], v[2:3], 0, s[6:7]
	s_mov_b32 m0, s20
	s_add_u32 s22, s0, 0x40080
	global_load_lds_dwordx4 v[2:3], off
	v_lshl_add_u64 v[0:1], v[0:1], 0, s[6:7]
	s_mov_b32 m0, s21
	s_addc_u32 s23, s1, 0
	global_load_lds_dwordx4 v[0:1], off
	s_add_i32 m0, s15, 0x1c000
	v_lshl_add_u64 v[0:1], s[22:23], 0, v[156:157]
	global_load_lds_dwordx4 v[0:1], off
	v_lshl_add_u64 v[0:1], s[22:23], 0, v[152:153]
	s_add_i32 m0, s15, 0x1e000
	s_lshl_b32 s10, s41, 4
	global_load_lds_dwordx4 v[0:1], off
	s_lshl_b32 s13, s53, 1
	v_lshrrev_b32_e32 v192, 7, v226
	v_readlane_b32 s24, v254, 0
	s_or_b32 s10, s10, s13
	v_lshlrev_b32_e32 v0, 15, v192
	v_lshlrev_b32_e32 v1, 11, v185
	v_readlane_b32 s26, v254, 2
	v_readlane_b32 s27, v254, 3
	s_lshl_b64 s[10:11], s[10:11], 19
	v_or3_b32 v0, v183, v0, v1
	s_mov_b64 s[22:23], s[26:27]
	v_lshrrev_b32_e32 v193, 11, v8
	v_add_u32_e32 v160, v0, v184
	s_add_u32 s10, s22, s10
	v_lshlrev_b32_e32 v0, 15, v193
	s_waitcnt vmcnt(6)
	v_readlane_b32 s25, v254, 1
	s_addc_u32 s11, s23, s11
	v_or3_b32 v0, v183, v0, v1
	s_add_i32 s48, 0, 0x10000
	s_add_i32 s49, 0, 0x14000
	s_add_i32 s51, 0, 0x18000
	s_add_i32 s53, 0, 0x1c000
	v_mov_b32_e32 v161, v157
	v_add_u32_e32 v162, v0, v184
	v_mov_b32_e32 v163, v157
	s_add_i32 s25, s48, s12
	s_add_i32 s27, s49, s12
	s_add_i32 s29, s51, s12
	s_add_i32 s31, s53, s12
	s_mov_b64 s[8:9], 0x40080
	v_lshl_add_u64 v[128:129], s[10:11], 0, v[160:161]
	v_lshl_add_u64 v[130:131], s[10:11], 0, v[162:163]
	s_mov_b32 s22, -2
	v_add_u32_e32 v133, s48, v9
	v_add_u32_e32 v134, s49, v9
	v_add_u32_e32 v135, 0, v10
	s_add_i32 s23, s15, 0xc000
	s_add_i32 s24, s15, 0xe000
	s_add_i32 s26, s25, 0x2000
	s_add_i32 s28, s27, 0x2000
	v_add_u32_e32 v136, s51, v9
	v_add_u32_e32 v137, s53, v9
	s_add_i32 s30, s29, 0x2000
	s_add_i32 s34, s31, 0x2000
	s_barrier
	ds_read_b128 v[138:141], v133
	ds_read_b128 v[142:145], v133 offset:1024
	ds_read_b128 v[146:149], v133 offset:2048
	ds_read_b128 v[164:167], v133 offset:3072
	ds_read_b128 v[168:171], v134
	ds_read_b128 v[172:175], v134 offset:1024
	ds_read_b128 v[176:179], v134 offset:2048
	ds_read_b128 v[200:203], v134 offset:3072
	s_add_u32 s10, s8, 0xfffc0080
	s_addc_u32 s11, s9, -1
	s_cmp_lg_u32 s22, 12
	s_cselect_b32 s10, s10, 0
	s_cselect_b32 s11, s11, 0
	s_add_u32 s12, s4, s10
	s_addc_u32 s13, s5, s11
	s_add_u32 s10, s0, s10
	s_addc_u32 s11, s1, s11
	s_mov_b32 m0, s23
	v_lshl_add_u64 v[150:151], v[128:129], 0, s[8:9]
	ds_read_b128 v[204:207], v135
	ds_read_b128 v[208:211], v135 offset:1024
	ds_read_b128 v[212:215], v135 offset:2048
	ds_read_b128 v[216:219], v135 offset:3072
	ds_read_b128 v[220:223], v135 offset:4096
	ds_read_b128 v[228:231], v135 offset:5120
	ds_read_b128 v[232:235], v135 offset:6144
	ds_read_b128 v[236:239], v135 offset:7168
	global_load_lds_dwordx4 v[150:151], off
	v_lshl_add_u64 v[150:151], v[130:131], 0, s[8:9]
	s_mov_b32 m0, s24
	s_nop 0
	global_load_lds_dwordx4 v[150:151], off
	s_waitcnt vmcnt(8)
	s_waitcnt lgkmcnt(0)
	s_barrier
	s_setprio 1
	v_mfma_f32_16x16x32_bf16 v[124:127], v[138:141], v[204:207], 0
	v_mfma_f32_16x16x32_bf16 v[120:123], v[146:149], v[204:207], 0
	v_mfma_f32_16x16x32_bf16 v[108:111], v[138:141], v[212:215], 0
	v_mfma_f32_16x16x32_bf16 v[104:107], v[146:149], v[212:215], 0
	v_mfma_f32_16x16x32_bf16 v[92:95], v[138:141], v[220:223], 0
	v_mfma_f32_16x16x32_bf16 v[88:91], v[146:149], v[220:223], 0
	v_mfma_f32_16x16x32_bf16 v[76:79], v[138:141], v[232:235], 0
	v_mfma_f32_16x16x32_bf16 v[72:75], v[146:149], v[232:235], 0
	v_mfma_f32_16x16x32_bf16 v[124:127], v[142:145], v[208:211], v[124:127]
	v_mfma_f32_16x16x32_bf16 v[120:123], v[164:167], v[208:211], v[120:123]
	v_mfma_f32_16x16x32_bf16 v[108:111], v[142:145], v[216:219], v[108:111]
	v_mfma_f32_16x16x32_bf16 v[104:107], v[164:167], v[216:219], v[104:107]
	v_mfma_f32_16x16x32_bf16 v[92:95], v[142:145], v[228:231], v[92:95]
	v_mfma_f32_16x16x32_bf16 v[88:91], v[164:167], v[228:231], v[88:91]
	v_mfma_f32_16x16x32_bf16 v[76:79], v[142:145], v[236:239], v[76:79]
	v_mfma_f32_16x16x32_bf16 v[72:75], v[164:167], v[236:239], v[72:75]
	s_setprio 0
	s_setprio 1
	v_mfma_f32_16x16x32_bf16 v[116:119], v[168:171], v[204:207], 0
	v_mfma_f32_16x16x32_bf16 v[112:115], v[176:179], v[204:207], 0
	v_mfma_f32_16x16x32_bf16 v[100:103], v[168:171], v[212:215], 0
	v_mfma_f32_16x16x32_bf16 v[96:99], v[176:179], v[212:215], 0
	v_mfma_f32_16x16x32_bf16 v[84:87], v[168:171], v[220:223], 0
	v_mfma_f32_16x16x32_bf16 v[80:83], v[176:179], v[220:223], 0
	v_mfma_f32_16x16x32_bf16 v[68:71], v[168:171], v[232:235], 0
	v_mfma_f32_16x16x32_bf16 v[64:67], v[176:179], v[232:235], 0
	v_mfma_f32_16x16x32_bf16 v[116:119], v[172:175], v[208:211], v[116:119]
	v_mfma_f32_16x16x32_bf16 v[112:115], v[200:203], v[208:211], v[112:115]
	v_mfma_f32_16x16x32_bf16 v[100:103], v[172:175], v[216:219], v[100:103]
	v_mfma_f32_16x16x32_bf16 v[96:99], v[200:203], v[216:219], v[96:99]
	v_mfma_f32_16x16x32_bf16 v[84:87], v[172:175], v[228:231], v[84:87]
	v_mfma_f32_16x16x32_bf16 v[80:83], v[200:203], v[228:231], v[80:83]
	v_mfma_f32_16x16x32_bf16 v[68:71], v[172:175], v[236:239], v[68:71]
	v_mfma_f32_16x16x32_bf16 v[64:67], v[200:203], v[236:239], v[64:67]
	s_setprio 0
	s_barrier
	s_mov_b32 m0, s25
	v_lshl_add_u64 v[150:151], s[10:11], 0, v[156:157]
	s_add_u32 s36, s10, 0x40000
	ds_read_b128 v[204:207], v135 offset:16384
	ds_read_b128 v[208:211], v135 offset:17408
	ds_read_b128 v[212:215], v135 offset:18432
	ds_read_b128 v[216:219], v135 offset:19456
	ds_read_b128 v[220:223], v135 offset:20480
	ds_read_b128 v[228:231], v135 offset:21504
	ds_read_b128 v[232:235], v135 offset:22528
	ds_read_b128 v[236:239], v135 offset:23552
	global_load_lds_dwordx4 v[150:151], off
	v_lshl_add_u64 v[180:181], s[10:11], 0, v[152:153]
	s_mov_b32 m0, s26
	s_addc_u32 s37, s11, 0
	global_load_lds_dwordx4 v[180:181], off
	v_lshl_add_u64 v[224:225], s[36:37], 0, v[156:157]
	s_mov_b32 m0, s27
	v_lshl_add_u64 v[240:241], s[12:13], 0, v[154:155]
	global_load_lds_dwordx4 v[224:225], off
	v_lshl_add_u64 v[224:225], s[36:37], 0, v[152:153]
	s_mov_b32 m0, s28
	s_nop 0
	global_load_lds_dwordx4 v[224:225], off
	v_lshl_add_u64 v[224:225], s[12:13], 0, v[158:159]
	s_mov_b32 m0, s15
	s_nop 0
	global_load_lds_dwordx4 v[224:225], off
	s_mov_b32 m0, s16
	s_nop 0
	global_load_lds_dwordx4 v[240:241], off
	s_waitcnt vmcnt(8)
	s_waitcnt lgkmcnt(0)
	s_barrier
	s_setprio 1
	v_mfma_f32_16x16x32_bf16 v[60:63], v[138:141], v[204:207], 0
	v_mfma_f32_16x16x32_bf16 v[56:59], v[146:149], v[204:207], 0
	v_mfma_f32_16x16x32_bf16 v[44:47], v[138:141], v[212:215], 0
	v_mfma_f32_16x16x32_bf16 v[40:43], v[146:149], v[212:215], 0
	v_mfma_f32_16x16x32_bf16 v[28:31], v[138:141], v[220:223], 0
	v_mfma_f32_16x16x32_bf16 v[24:27], v[146:149], v[220:223], 0
	v_mfma_f32_16x16x32_bf16 v[12:15], v[138:141], v[232:235], 0
	v_mfma_f32_16x16x32_bf16 v[8:11], v[146:149], v[232:235], 0
	v_mfma_f32_16x16x32_bf16 v[60:63], v[142:145], v[208:211], v[60:63]
	v_mfma_f32_16x16x32_bf16 v[56:59], v[164:167], v[208:211], v[56:59]
	v_mfma_f32_16x16x32_bf16 v[44:47], v[142:145], v[216:219], v[44:47]
	v_mfma_f32_16x16x32_bf16 v[40:43], v[164:167], v[216:219], v[40:43]
	v_mfma_f32_16x16x32_bf16 v[28:31], v[142:145], v[228:231], v[28:31]
	v_mfma_f32_16x16x32_bf16 v[24:27], v[164:167], v[228:231], v[24:27]
	v_mfma_f32_16x16x32_bf16 v[12:15], v[142:145], v[236:239], v[12:15]
	v_mfma_f32_16x16x32_bf16 v[8:11], v[164:167], v[236:239], v[8:11]
	s_setprio 0
	s_setprio 1
	v_mfma_f32_16x16x32_bf16 v[52:55], v[168:171], v[204:207], 0
	v_mfma_f32_16x16x32_bf16 v[48:51], v[176:179], v[204:207], 0
	v_mfma_f32_16x16x32_bf16 v[36:39], v[168:171], v[212:215], 0
	v_mfma_f32_16x16x32_bf16 v[32:35], v[176:179], v[212:215], 0
	v_mfma_f32_16x16x32_bf16 v[20:23], v[168:171], v[220:223], 0
	v_mfma_f32_16x16x32_bf16 v[16:19], v[176:179], v[220:223], 0
	v_mfma_f32_16x16x32_bf16 v[4:7], v[168:171], v[232:235], 0
	v_mfma_f32_16x16x32_bf16 v[0:3], v[176:179], v[232:235], 0
	v_mfma_f32_16x16x32_bf16 v[52:55], v[172:175], v[208:211], v[52:55]
	v_mfma_f32_16x16x32_bf16 v[48:51], v[200:203], v[208:211], v[48:51]
	v_mfma_f32_16x16x32_bf16 v[36:39], v[172:175], v[216:219], v[36:39]
	v_mfma_f32_16x16x32_bf16 v[32:35], v[200:203], v[216:219], v[32:35]
	v_mfma_f32_16x16x32_bf16 v[20:23], v[172:175], v[228:231], v[20:23]
	v_mfma_f32_16x16x32_bf16 v[16:19], v[200:203], v[228:231], v[16:19]
	v_mfma_f32_16x16x32_bf16 v[4:7], v[172:175], v[236:239], v[4:7]
	v_mfma_f32_16x16x32_bf16 v[0:3], v[200:203], v[236:239], v[0:3]
	s_setprio 0
	s_barrier
	ds_read_b128 v[138:141], v136
	ds_read_b128 v[142:145], v136 offset:1024
	ds_read_b128 v[146:149], v136 offset:2048
	ds_read_b128 v[164:167], v136 offset:3072
	ds_read_b128 v[168:171], v137
	ds_read_b128 v[172:175], v137 offset:1024
	ds_read_b128 v[176:179], v137 offset:2048
	ds_read_b128 v[200:203], v137 offset:3072
	s_add_u32 s12, s12, 0x40000
	s_addc_u32 s13, s13, 0
	s_mov_b32 m0, s17
	v_lshl_add_u64 v[242:243], s[12:13], 0, v[158:159]
	ds_read_b128 v[204:207], v135 offset:32768
	ds_read_b128 v[208:211], v135 offset:33792
	ds_read_b128 v[212:215], v135 offset:34816
	ds_read_b128 v[216:219], v135 offset:35840
	ds_read_b128 v[220:223], v135 offset:36864
	ds_read_b128 v[228:231], v135 offset:37888
	ds_read_b128 v[232:235], v135 offset:38912
	ds_read_b128 v[236:239], v135 offset:39936
	global_load_lds_dwordx4 v[242:243], off
	v_lshl_add_u64 v[242:243], s[12:13], 0, v[154:155]
	s_mov_b32 m0, s18
	s_nop 0
	global_load_lds_dwordx4 v[242:243], off
	s_waitcnt vmcnt(8)
	s_waitcnt lgkmcnt(0)
	s_barrier
	s_setprio 1
	v_mfma_f32_16x16x32_bf16 v[124:127], v[138:141], v[204:207], v[124:127]
	v_mfma_f32_16x16x32_bf16 v[120:123], v[146:149], v[204:207], v[120:123]
	v_mfma_f32_16x16x32_bf16 v[108:111], v[138:141], v[212:215], v[108:111]
	v_mfma_f32_16x16x32_bf16 v[104:107], v[146:149], v[212:215], v[104:107]
	v_mfma_f32_16x16x32_bf16 v[92:95], v[138:141], v[220:223], v[92:95]
	v_mfma_f32_16x16x32_bf16 v[88:91], v[146:149], v[220:223], v[88:91]
	v_mfma_f32_16x16x32_bf16 v[76:79], v[138:141], v[232:235], v[76:79]
	v_mfma_f32_16x16x32_bf16 v[72:75], v[146:149], v[232:235], v[72:75]
	v_mfma_f32_16x16x32_bf16 v[124:127], v[142:145], v[208:211], v[124:127]
	v_mfma_f32_16x16x32_bf16 v[120:123], v[164:167], v[208:211], v[120:123]
	v_mfma_f32_16x16x32_bf16 v[108:111], v[142:145], v[216:219], v[108:111]
	v_mfma_f32_16x16x32_bf16 v[104:107], v[164:167], v[216:219], v[104:107]
	v_mfma_f32_16x16x32_bf16 v[92:95], v[142:145], v[228:231], v[92:95]
	v_mfma_f32_16x16x32_bf16 v[88:91], v[164:167], v[228:231], v[88:91]
	v_mfma_f32_16x16x32_bf16 v[76:79], v[142:145], v[236:239], v[76:79]
	v_mfma_f32_16x16x32_bf16 v[72:75], v[164:167], v[236:239], v[72:75]
	s_setprio 0
	s_setprio 1
	v_mfma_f32_16x16x32_bf16 v[116:119], v[168:171], v[204:207], v[116:119]
	v_mfma_f32_16x16x32_bf16 v[112:115], v[176:179], v[204:207], v[112:115]
	v_mfma_f32_16x16x32_bf16 v[100:103], v[168:171], v[212:215], v[100:103]
	v_mfma_f32_16x16x32_bf16 v[96:99], v[176:179], v[212:215], v[96:99]
	v_mfma_f32_16x16x32_bf16 v[84:87], v[168:171], v[220:223], v[84:87]
	v_mfma_f32_16x16x32_bf16 v[80:83], v[176:179], v[220:223], v[80:83]
	v_mfma_f32_16x16x32_bf16 v[68:71], v[168:171], v[232:235], v[68:71]
	v_mfma_f32_16x16x32_bf16 v[64:67], v[176:179], v[232:235], v[64:67]
	v_mfma_f32_16x16x32_bf16 v[116:119], v[172:175], v[208:211], v[116:119]
	v_mfma_f32_16x16x32_bf16 v[112:115], v[200:203], v[208:211], v[112:115]
	v_mfma_f32_16x16x32_bf16 v[100:103], v[172:175], v[216:219], v[100:103]
	v_mfma_f32_16x16x32_bf16 v[96:99], v[200:203], v[216:219], v[96:99]
	v_mfma_f32_16x16x32_bf16 v[84:87], v[172:175], v[228:231], v[84:87]
	v_mfma_f32_16x16x32_bf16 v[80:83], v[200:203], v[228:231], v[80:83]
	v_mfma_f32_16x16x32_bf16 v[68:71], v[172:175], v[236:239], v[68:71]
	v_mfma_f32_16x16x32_bf16 v[64:67], v[200:203], v[236:239], v[64:67]
	s_setprio 0
	s_barrier
	s_mov_b32 m0, s29
	v_lshl_add_u64 v[150:151], v[150:151], 0, s[6:7]
	s_add_u32 s10, s10, 0x40080
	ds_read_b128 v[204:207], v135 offset:49152
	ds_read_b128 v[208:211], v135 offset:50176
	ds_read_b128 v[212:215], v135 offset:51200
	ds_read_b128 v[216:219], v135 offset:52224
	ds_read_b128 v[220:223], v135 offset:53248
	ds_read_b128 v[228:231], v135 offset:54272
	ds_read_b128 v[232:235], v135 offset:55296
	ds_read_b128 v[236:239], v135 offset:56320
	global_load_lds_dwordx4 v[150:151], off
	v_lshl_add_u64 v[150:151], v[180:181], 0, s[6:7]
	s_mov_b32 m0, s30
	s_addc_u32 s11, s11, 0
	global_load_lds_dwordx4 v[150:151], off
	v_lshl_add_u64 v[150:151], s[10:11], 0, v[156:157]
	s_mov_b32 m0, s31
	s_nop 0
	global_load_lds_dwordx4 v[150:151], off
	v_lshl_add_u64 v[150:151], s[10:11], 0, v[152:153]
	s_mov_b32 m0, s34
	s_nop 0
	global_load_lds_dwordx4 v[150:151], off
	v_lshl_add_u64 v[150:151], v[224:225], 0, s[6:7]
	s_mov_b32 m0, s20
	s_nop 0
	global_load_lds_dwordx4 v[150:151], off
	v_lshl_add_u64 v[150:151], v[240:241], 0, s[6:7]
	s_mov_b32 m0, s21
	s_nop 0
	global_load_lds_dwordx4 v[150:151], off
	s_waitcnt vmcnt(8)
	s_waitcnt lgkmcnt(0)
	s_barrier
	s_setprio 1
	v_mfma_f32_16x16x32_bf16 v[60:63], v[138:141], v[204:207], v[60:63]
	v_mfma_f32_16x16x32_bf16 v[56:59], v[146:149], v[204:207], v[56:59]
	v_mfma_f32_16x16x32_bf16 v[44:47], v[138:141], v[212:215], v[44:47]
	v_mfma_f32_16x16x32_bf16 v[40:43], v[146:149], v[212:215], v[40:43]
	v_mfma_f32_16x16x32_bf16 v[28:31], v[138:141], v[220:223], v[28:31]
	v_mfma_f32_16x16x32_bf16 v[24:27], v[146:149], v[220:223], v[24:27]
	v_mfma_f32_16x16x32_bf16 v[12:15], v[138:141], v[232:235], v[12:15]
	v_mfma_f32_16x16x32_bf16 v[8:11], v[146:149], v[232:235], v[8:11]
	v_mfma_f32_16x16x32_bf16 v[60:63], v[142:145], v[208:211], v[60:63]
	v_mfma_f32_16x16x32_bf16 v[56:59], v[164:167], v[208:211], v[56:59]
	v_mfma_f32_16x16x32_bf16 v[44:47], v[142:145], v[216:219], v[44:47]
	v_mfma_f32_16x16x32_bf16 v[40:43], v[164:167], v[216:219], v[40:43]
	v_mfma_f32_16x16x32_bf16 v[28:31], v[142:145], v[228:231], v[28:31]
	v_mfma_f32_16x16x32_bf16 v[24:27], v[164:167], v[228:231], v[24:27]
	v_mfma_f32_16x16x32_bf16 v[12:15], v[142:145], v[236:239], v[12:15]
	v_mfma_f32_16x16x32_bf16 v[8:11], v[164:167], v[236:239], v[8:11]
	s_setprio 0
	s_setprio 1
	v_mfma_f32_16x16x32_bf16 v[52:55], v[168:171], v[204:207], v[52:55]
	v_mfma_f32_16x16x32_bf16 v[48:51], v[176:179], v[204:207], v[48:51]
	v_mfma_f32_16x16x32_bf16 v[36:39], v[168:171], v[212:215], v[36:39]
	v_mfma_f32_16x16x32_bf16 v[32:35], v[176:179], v[212:215], v[32:35]
	v_mfma_f32_16x16x32_bf16 v[20:23], v[168:171], v[220:223], v[20:23]
	v_mfma_f32_16x16x32_bf16 v[16:19], v[176:179], v[220:223], v[16:19]
	v_mfma_f32_16x16x32_bf16 v[4:7], v[168:171], v[232:235], v[4:7]
	v_mfma_f32_16x16x32_bf16 v[0:3], v[176:179], v[232:235], v[0:3]
	v_mfma_f32_16x16x32_bf16 v[52:55], v[172:175], v[208:211], v[52:55]
	v_mfma_f32_16x16x32_bf16 v[48:51], v[200:203], v[208:211], v[48:51]
	v_mfma_f32_16x16x32_bf16 v[36:39], v[172:175], v[216:219], v[36:39]
	v_mfma_f32_16x16x32_bf16 v[32:35], v[200:203], v[216:219], v[32:35]
	v_mfma_f32_16x16x32_bf16 v[20:23], v[172:175], v[228:231], v[20:23]
	v_mfma_f32_16x16x32_bf16 v[16:19], v[200:203], v[228:231], v[16:19]
	v_mfma_f32_16x16x32_bf16 v[4:7], v[172:175], v[236:239], v[4:7]
	v_mfma_f32_16x16x32_bf16 v[0:3], v[200:203], v[236:239], v[0:3]
	s_setprio 0
	s_barrier
	s_add_i32 s22, s22, 2
	s_add_u32 s8, s8, 0x100
	s_addc_u32 s9, s9, 0
	s_cmp_gt_u32 s22, 13
.LBB0_953:
	ds_read_b128 v[138:141], v133
	ds_read_b128 v[142:145], v133 offset:1024
	ds_read_b128 v[146:149], v133 offset:2048
	ds_read_b128 v[164:167], v133 offset:3072
	ds_read_b128 v[168:171], v134
	ds_read_b128 v[172:175], v134 offset:1024
	ds_read_b128 v[176:179], v134 offset:2048
	ds_read_b128 v[200:203], v134 offset:3072
	s_add_u32 s10, s8, 0xfffc0080
	s_addc_u32 s11, s9, -1
	s_cmp_lg_u32 s22, 12
	s_cselect_b32 s10, s10, 0
	s_cselect_b32 s11, s11, 0
	s_add_u32 s12, s4, s10
	s_addc_u32 s13, s5, s11
	s_add_u32 s10, s0, s10
	s_addc_u32 s11, s1, s11
	s_mov_b32 m0, s23
	v_lshl_add_u64 v[150:151], v[128:129], 0, s[8:9]
	ds_read_b128 v[204:207], v135
	ds_read_b128 v[208:211], v135 offset:1024
	ds_read_b128 v[212:215], v135 offset:2048
	ds_read_b128 v[216:219], v135 offset:3072
	ds_read_b128 v[220:223], v135 offset:4096
	ds_read_b128 v[228:231], v135 offset:5120
	ds_read_b128 v[232:235], v135 offset:6144
	ds_read_b128 v[236:239], v135 offset:7168
	global_load_lds_dwordx4 v[150:151], off
	v_lshl_add_u64 v[150:151], v[130:131], 0, s[8:9]
	s_mov_b32 m0, s24
	s_nop 0
	global_load_lds_dwordx4 v[150:151], off
	s_waitcnt vmcnt(8)
	s_waitcnt lgkmcnt(0)
	s_barrier
	s_setprio 1
	v_mfma_f32_16x16x32_bf16 v[124:127], v[138:141], v[204:207], v[124:127]
	v_mfma_f32_16x16x32_bf16 v[120:123], v[146:149], v[204:207], v[120:123]
	v_mfma_f32_16x16x32_bf16 v[108:111], v[138:141], v[212:215], v[108:111]
	v_mfma_f32_16x16x32_bf16 v[104:107], v[146:149], v[212:215], v[104:107]
	v_mfma_f32_16x16x32_bf16 v[92:95], v[138:141], v[220:223], v[92:95]
	v_mfma_f32_16x16x32_bf16 v[88:91], v[146:149], v[220:223], v[88:91]
	v_mfma_f32_16x16x32_bf16 v[76:79], v[138:141], v[232:235], v[76:79]
	v_mfma_f32_16x16x32_bf16 v[72:75], v[146:149], v[232:235], v[72:75]
	v_mfma_f32_16x16x32_bf16 v[124:127], v[142:145], v[208:211], v[124:127]
	v_mfma_f32_16x16x32_bf16 v[120:123], v[164:167], v[208:211], v[120:123]
	v_mfma_f32_16x16x32_bf16 v[108:111], v[142:145], v[216:219], v[108:111]
	v_mfma_f32_16x16x32_bf16 v[104:107], v[164:167], v[216:219], v[104:107]
	v_mfma_f32_16x16x32_bf16 v[92:95], v[142:145], v[228:231], v[92:95]
	v_mfma_f32_16x16x32_bf16 v[88:91], v[164:167], v[228:231], v[88:91]
	v_mfma_f32_16x16x32_bf16 v[76:79], v[142:145], v[236:239], v[76:79]
	v_mfma_f32_16x16x32_bf16 v[72:75], v[164:167], v[236:239], v[72:75]
	s_setprio 0
	s_setprio 1
	v_mfma_f32_16x16x32_bf16 v[116:119], v[168:171], v[204:207], v[116:119]
	v_mfma_f32_16x16x32_bf16 v[112:115], v[176:179], v[204:207], v[112:115]
	v_mfma_f32_16x16x32_bf16 v[100:103], v[168:171], v[212:215], v[100:103]
	v_mfma_f32_16x16x32_bf16 v[96:99], v[176:179], v[212:215], v[96:99]
	v_mfma_f32_16x16x32_bf16 v[84:87], v[168:171], v[220:223], v[84:87]
	v_mfma_f32_16x16x32_bf16 v[80:83], v[176:179], v[220:223], v[80:83]
	v_mfma_f32_16x16x32_bf16 v[68:71], v[168:171], v[232:235], v[68:71]
	v_mfma_f32_16x16x32_bf16 v[64:67], v[176:179], v[232:235], v[64:67]
	v_mfma_f32_16x16x32_bf16 v[116:119], v[172:175], v[208:211], v[116:119]
	v_mfma_f32_16x16x32_bf16 v[112:115], v[200:203], v[208:211], v[112:115]
	v_mfma_f32_16x16x32_bf16 v[100:103], v[172:175], v[216:219], v[100:103]
	v_mfma_f32_16x16x32_bf16 v[96:99], v[200:203], v[216:219], v[96:99]
	v_mfma_f32_16x16x32_bf16 v[84:87], v[172:175], v[228:231], v[84:87]
	v_mfma_f32_16x16x32_bf16 v[80:83], v[200:203], v[228:231], v[80:83]
	v_mfma_f32_16x16x32_bf16 v[68:71], v[172:175], v[236:239], v[68:71]
	v_mfma_f32_16x16x32_bf16 v[64:67], v[200:203], v[236:239], v[64:67]
	s_setprio 0
	s_barrier
	s_mov_b32 m0, s25
	v_lshl_add_u64 v[150:151], s[10:11], 0, v[156:157]
	s_add_u32 s36, s10, 0x40000
	ds_read_b128 v[204:207], v135 offset:16384
	ds_read_b128 v[208:211], v135 offset:17408
	ds_read_b128 v[212:215], v135 offset:18432
	ds_read_b128 v[216:219], v135 offset:19456
	ds_read_b128 v[220:223], v135 offset:20480
	ds_read_b128 v[228:231], v135 offset:21504
	ds_read_b128 v[232:235], v135 offset:22528
	ds_read_b128 v[236:239], v135 offset:23552
	global_load_lds_dwordx4 v[150:151], off
	v_lshl_add_u64 v[180:181], s[10:11], 0, v[152:153]
	s_mov_b32 m0, s26
	s_addc_u32 s37, s11, 0
	global_load_lds_dwordx4 v[180:181], off
	v_lshl_add_u64 v[224:225], s[36:37], 0, v[156:157]
	s_mov_b32 m0, s27
	v_lshl_add_u64 v[240:241], s[12:13], 0, v[154:155]
	global_load_lds_dwordx4 v[224:225], off
	v_lshl_add_u64 v[224:225], s[36:37], 0, v[152:153]
	s_mov_b32 m0, s28
	s_nop 0
	global_load_lds_dwordx4 v[224:225], off
	v_lshl_add_u64 v[224:225], s[12:13], 0, v[158:159]
	s_mov_b32 m0, s15
	s_nop 0
	global_load_lds_dwordx4 v[224:225], off
	s_mov_b32 m0, s16
	s_nop 0
	global_load_lds_dwordx4 v[240:241], off
	s_waitcnt vmcnt(8)
	s_waitcnt lgkmcnt(0)
	s_barrier
	s_setprio 1
	v_mfma_f32_16x16x32_bf16 v[60:63], v[138:141], v[204:207], v[60:63]
	v_mfma_f32_16x16x32_bf16 v[56:59], v[146:149], v[204:207], v[56:59]
	v_mfma_f32_16x16x32_bf16 v[44:47], v[138:141], v[212:215], v[44:47]
	v_mfma_f32_16x16x32_bf16 v[40:43], v[146:149], v[212:215], v[40:43]
	v_mfma_f32_16x16x32_bf16 v[28:31], v[138:141], v[220:223], v[28:31]
	v_mfma_f32_16x16x32_bf16 v[24:27], v[146:149], v[220:223], v[24:27]
	v_mfma_f32_16x16x32_bf16 v[12:15], v[138:141], v[232:235], v[12:15]
	v_mfma_f32_16x16x32_bf16 v[8:11], v[146:149], v[232:235], v[8:11]
	v_mfma_f32_16x16x32_bf16 v[60:63], v[142:145], v[208:211], v[60:63]
	v_mfma_f32_16x16x32_bf16 v[56:59], v[164:167], v[208:211], v[56:59]
	v_mfma_f32_16x16x32_bf16 v[44:47], v[142:145], v[216:219], v[44:47]
	v_mfma_f32_16x16x32_bf16 v[40:43], v[164:167], v[216:219], v[40:43]
	v_mfma_f32_16x16x32_bf16 v[28:31], v[142:145], v[228:231], v[28:31]
	v_mfma_f32_16x16x32_bf16 v[24:27], v[164:167], v[228:231], v[24:27]
	v_mfma_f32_16x16x32_bf16 v[12:15], v[142:145], v[236:239], v[12:15]
	v_mfma_f32_16x16x32_bf16 v[8:11], v[164:167], v[236:239], v[8:11]
	s_setprio 0
	s_setprio 1
	v_mfma_f32_16x16x32_bf16 v[52:55], v[168:171], v[204:207], v[52:55]
	v_mfma_f32_16x16x32_bf16 v[48:51], v[176:179], v[204:207], v[48:51]
	v_mfma_f32_16x16x32_bf16 v[36:39], v[168:171], v[212:215], v[36:39]
	v_mfma_f32_16x16x32_bf16 v[32:35], v[176:179], v[212:215], v[32:35]
	v_mfma_f32_16x16x32_bf16 v[20:23], v[168:171], v[220:223], v[20:23]
	v_mfma_f32_16x16x32_bf16 v[16:19], v[176:179], v[220:223], v[16:19]
	v_mfma_f32_16x16x32_bf16 v[4:7], v[168:171], v[232:235], v[4:7]
	v_mfma_f32_16x16x32_bf16 v[0:3], v[176:179], v[232:235], v[0:3]
	v_mfma_f32_16x16x32_bf16 v[52:55], v[172:175], v[208:211], v[52:55]
	v_mfma_f32_16x16x32_bf16 v[48:51], v[200:203], v[208:211], v[48:51]
	v_mfma_f32_16x16x32_bf16 v[36:39], v[172:175], v[216:219], v[36:39]
	v_mfma_f32_16x16x32_bf16 v[32:35], v[200:203], v[216:219], v[32:35]
	v_mfma_f32_16x16x32_bf16 v[20:23], v[172:175], v[228:231], v[20:23]
	v_mfma_f32_16x16x32_bf16 v[16:19], v[200:203], v[228:231], v[16:19]
	v_mfma_f32_16x16x32_bf16 v[4:7], v[172:175], v[236:239], v[4:7]
	v_mfma_f32_16x16x32_bf16 v[0:3], v[200:203], v[236:239], v[0:3]
	s_setprio 0
	s_barrier
	ds_read_b128 v[138:141], v136
	ds_read_b128 v[142:145], v136 offset:1024
	ds_read_b128 v[146:149], v136 offset:2048
	ds_read_b128 v[164:167], v136 offset:3072
	ds_read_b128 v[168:171], v137
	ds_read_b128 v[172:175], v137 offset:1024
	ds_read_b128 v[176:179], v137 offset:2048
	ds_read_b128 v[200:203], v137 offset:3072
	s_add_u32 s12, s12, 0x40000
	s_addc_u32 s13, s13, 0
	s_mov_b32 m0, s17
	v_lshl_add_u64 v[242:243], s[12:13], 0, v[158:159]
	ds_read_b128 v[204:207], v135 offset:32768
	ds_read_b128 v[208:211], v135 offset:33792
	ds_read_b128 v[212:215], v135 offset:34816
	ds_read_b128 v[216:219], v135 offset:35840
	ds_read_b128 v[220:223], v135 offset:36864
	ds_read_b128 v[228:231], v135 offset:37888
	ds_read_b128 v[232:235], v135 offset:38912
	ds_read_b128 v[236:239], v135 offset:39936
	global_load_lds_dwordx4 v[242:243], off
	v_lshl_add_u64 v[242:243], s[12:13], 0, v[154:155]
	s_mov_b32 m0, s18
	s_nop 0
	global_load_lds_dwordx4 v[242:243], off
	s_waitcnt vmcnt(8)
	s_waitcnt lgkmcnt(0)
	s_barrier
	s_setprio 1
	v_mfma_f32_16x16x32_bf16 v[124:127], v[138:141], v[204:207], v[124:127]
	v_mfma_f32_16x16x32_bf16 v[120:123], v[146:149], v[204:207], v[120:123]
	v_mfma_f32_16x16x32_bf16 v[108:111], v[138:141], v[212:215], v[108:111]
	v_mfma_f32_16x16x32_bf16 v[104:107], v[146:149], v[212:215], v[104:107]
	v_mfma_f32_16x16x32_bf16 v[92:95], v[138:141], v[220:223], v[92:95]
	v_mfma_f32_16x16x32_bf16 v[88:91], v[146:149], v[220:223], v[88:91]
	v_mfma_f32_16x16x32_bf16 v[76:79], v[138:141], v[232:235], v[76:79]
	v_mfma_f32_16x16x32_bf16 v[72:75], v[146:149], v[232:235], v[72:75]
	v_mfma_f32_16x16x32_bf16 v[124:127], v[142:145], v[208:211], v[124:127]
	v_mfma_f32_16x16x32_bf16 v[120:123], v[164:167], v[208:211], v[120:123]
	v_mfma_f32_16x16x32_bf16 v[108:111], v[142:145], v[216:219], v[108:111]
	v_mfma_f32_16x16x32_bf16 v[104:107], v[164:167], v[216:219], v[104:107]
	v_mfma_f32_16x16x32_bf16 v[92:95], v[142:145], v[228:231], v[92:95]
	v_mfma_f32_16x16x32_bf16 v[88:91], v[164:167], v[228:231], v[88:91]
	v_mfma_f32_16x16x32_bf16 v[76:79], v[142:145], v[236:239], v[76:79]
	v_mfma_f32_16x16x32_bf16 v[72:75], v[164:167], v[236:239], v[72:75]
	s_setprio 0
	s_setprio 1
	v_mfma_f32_16x16x32_bf16 v[116:119], v[168:171], v[204:207], v[116:119]
	v_mfma_f32_16x16x32_bf16 v[112:115], v[176:179], v[204:207], v[112:115]
	v_mfma_f32_16x16x32_bf16 v[100:103], v[168:171], v[212:215], v[100:103]
	v_mfma_f32_16x16x32_bf16 v[96:99], v[176:179], v[212:215], v[96:99]
	v_mfma_f32_16x16x32_bf16 v[84:87], v[168:171], v[220:223], v[84:87]
	v_mfma_f32_16x16x32_bf16 v[80:83], v[176:179], v[220:223], v[80:83]
	v_mfma_f32_16x16x32_bf16 v[68:71], v[168:171], v[232:235], v[68:71]
	v_mfma_f32_16x16x32_bf16 v[64:67], v[176:179], v[232:235], v[64:67]
	v_mfma_f32_16x16x32_bf16 v[116:119], v[172:175], v[208:211], v[116:119]
	v_mfma_f32_16x16x32_bf16 v[112:115], v[200:203], v[208:211], v[112:115]
	v_mfma_f32_16x16x32_bf16 v[100:103], v[172:175], v[216:219], v[100:103]
	v_mfma_f32_16x16x32_bf16 v[96:99], v[200:203], v[216:219], v[96:99]
	v_mfma_f32_16x16x32_bf16 v[84:87], v[172:175], v[228:231], v[84:87]
	v_mfma_f32_16x16x32_bf16 v[80:83], v[200:203], v[228:231], v[80:83]
	v_mfma_f32_16x16x32_bf16 v[68:71], v[172:175], v[236:239], v[68:71]
	v_mfma_f32_16x16x32_bf16 v[64:67], v[200:203], v[236:239], v[64:67]
	s_setprio 0
	s_barrier
	s_mov_b32 m0, s29
	v_lshl_add_u64 v[150:151], v[150:151], 0, s[6:7]
	s_add_u32 s10, s10, 0x40080
	ds_read_b128 v[204:207], v135 offset:49152
	ds_read_b128 v[208:211], v135 offset:50176
	ds_read_b128 v[212:215], v135 offset:51200
	ds_read_b128 v[216:219], v135 offset:52224
	ds_read_b128 v[220:223], v135 offset:53248
	ds_read_b128 v[228:231], v135 offset:54272
	ds_read_b128 v[232:235], v135 offset:55296
	ds_read_b128 v[236:239], v135 offset:56320
	global_load_lds_dwordx4 v[150:151], off
	v_lshl_add_u64 v[150:151], v[180:181], 0, s[6:7]
	s_mov_b32 m0, s30
	s_addc_u32 s11, s11, 0
	global_load_lds_dwordx4 v[150:151], off
	v_lshl_add_u64 v[150:151], s[10:11], 0, v[156:157]
	s_mov_b32 m0, s31
	s_nop 0
	global_load_lds_dwordx4 v[150:151], off
	v_lshl_add_u64 v[150:151], s[10:11], 0, v[152:153]
	s_mov_b32 m0, s34
	s_nop 0
	global_load_lds_dwordx4 v[150:151], off
	v_lshl_add_u64 v[150:151], v[224:225], 0, s[6:7]
	s_mov_b32 m0, s20
	s_nop 0
	global_load_lds_dwordx4 v[150:151], off
	v_lshl_add_u64 v[150:151], v[240:241], 0, s[6:7]
	s_mov_b32 m0, s21
	s_nop 0
	global_load_lds_dwordx4 v[150:151], off
	s_waitcnt vmcnt(8)
	s_waitcnt lgkmcnt(0)
	s_barrier
	s_setprio 1
	v_mfma_f32_16x16x32_bf16 v[60:63], v[138:141], v[204:207], v[60:63]
	v_mfma_f32_16x16x32_bf16 v[56:59], v[146:149], v[204:207], v[56:59]
	v_mfma_f32_16x16x32_bf16 v[44:47], v[138:141], v[212:215], v[44:47]
	v_mfma_f32_16x16x32_bf16 v[40:43], v[146:149], v[212:215], v[40:43]
	v_mfma_f32_16x16x32_bf16 v[28:31], v[138:141], v[220:223], v[28:31]
	v_mfma_f32_16x16x32_bf16 v[24:27], v[146:149], v[220:223], v[24:27]
	v_mfma_f32_16x16x32_bf16 v[12:15], v[138:141], v[232:235], v[12:15]
	v_mfma_f32_16x16x32_bf16 v[8:11], v[146:149], v[232:235], v[8:11]
	v_mfma_f32_16x16x32_bf16 v[60:63], v[142:145], v[208:211], v[60:63]
	v_mfma_f32_16x16x32_bf16 v[56:59], v[164:167], v[208:211], v[56:59]
	v_mfma_f32_16x16x32_bf16 v[44:47], v[142:145], v[216:219], v[44:47]
	v_mfma_f32_16x16x32_bf16 v[40:43], v[164:167], v[216:219], v[40:43]
	v_mfma_f32_16x16x32_bf16 v[28:31], v[142:145], v[228:231], v[28:31]
	v_mfma_f32_16x16x32_bf16 v[24:27], v[164:167], v[228:231], v[24:27]
	v_mfma_f32_16x16x32_bf16 v[12:15], v[142:145], v[236:239], v[12:15]
	v_mfma_f32_16x16x32_bf16 v[8:11], v[164:167], v[236:239], v[8:11]
	s_setprio 0
	s_setprio 1
	v_mfma_f32_16x16x32_bf16 v[52:55], v[168:171], v[204:207], v[52:55]
	v_mfma_f32_16x16x32_bf16 v[48:51], v[176:179], v[204:207], v[48:51]
	v_mfma_f32_16x16x32_bf16 v[36:39], v[168:171], v[212:215], v[36:39]
	v_mfma_f32_16x16x32_bf16 v[32:35], v[176:179], v[212:215], v[32:35]
	v_mfma_f32_16x16x32_bf16 v[20:23], v[168:171], v[220:223], v[20:23]
	v_mfma_f32_16x16x32_bf16 v[16:19], v[176:179], v[220:223], v[16:19]
	v_mfma_f32_16x16x32_bf16 v[4:7], v[168:171], v[232:235], v[4:7]
	v_mfma_f32_16x16x32_bf16 v[0:3], v[176:179], v[232:235], v[0:3]
	v_mfma_f32_16x16x32_bf16 v[52:55], v[172:175], v[208:211], v[52:55]
	v_mfma_f32_16x16x32_bf16 v[48:51], v[200:203], v[208:211], v[48:51]
	v_mfma_f32_16x16x32_bf16 v[36:39], v[172:175], v[216:219], v[36:39]
	v_mfma_f32_16x16x32_bf16 v[32:35], v[200:203], v[216:219], v[32:35]
	v_mfma_f32_16x16x32_bf16 v[20:23], v[172:175], v[228:231], v[20:23]
	v_mfma_f32_16x16x32_bf16 v[16:19], v[200:203], v[228:231], v[16:19]
	v_mfma_f32_16x16x32_bf16 v[4:7], v[172:175], v[236:239], v[4:7]
	v_mfma_f32_16x16x32_bf16 v[0:3], v[200:203], v[236:239], v[0:3]
	s_setprio 0
	s_barrier
	s_add_i32 s22, s22, 2
	s_add_u32 s8, s8, 0x100
	s_addc_u32 s9, s9, 0
	s_cmp_gt_u32 s22, 13
	s_cbranch_scc0 .LBB0_953
	s_cmpk_lt_u32 s14, 0x100
	s_cbranch_scc0 .LBB0_956
	s_barrier

.LBB0_993:
	s_mov_b32 s69, s41
	s_add_i32 s41, s41, 1
	s_cmp_lt_u32 s69, 3
	s_mov_b64 s[0:1], s[18:19]
	s_cselect_b64 s[46:47], -1, 0
	s_add_i32 s18, s41, s52
	s_mov_b64 s[4:5], s[16:17]
	s_and_b64 s[16:17], s[46:47], exec
	s_mov_b32 s71, s42
	s_cselect_b32 s42, s40, s42
	s_mov_b32 s70, s36
	s_cselect_b32 s36, s18, s36
	s_ashr_i32 s43, s42, 31
	s_lshl_b64 s[16:17], s[42:43], 19
	s_add_u32 s18, s6, s16
	s_addc_u32 s19, s7, s17
	s_and_b64 s[16:17], s[46:47], exec
	s_cselect_b32 s43, s19, s1
	s_cselect_b32 s72, s18, s0
	s_ashr_i32 s37, s36, 31
	s_lshl_b64 s[16:17], s[36:37], 19
	s_add_u32 s16, s55, s16
	s_addc_u32 s17, s56, s17
	s_and_b64 s[46:47], s[46:47], exec
	s_cselect_b32 s37, s17, s5
	s_cselect_b32 s73, s16, s4
	s_add_u32 s0, s0, 0x40080
	s_addc_u32 s1, s1, 0
	s_add_u32 s74, s4, 0x100
	s_addc_u32 s75, s5, 0
	s_mov_b32 s76, -2
	ds_read_b128 v[128:131], v144
	ds_read_b128 v[132:135], v144 offset:1024
	ds_read_b128 v[164:167], v144 offset:2048
	ds_read_b128 v[168:171], v144 offset:3072
	ds_read_b128 v[172:175], v145
	ds_read_b128 v[176:179], v145 offset:1024
	ds_read_b128 v[194:197], v145 offset:2048
	ds_read_b128 v[198:201], v145 offset:3072
	s_add_u32 s4, s0, 0xfffc0080
	s_addc_u32 s5, s1, -1
	s_cmp_eq_u32 s76, 12
	s_cselect_b32 s47, s43, s5
	s_cselect_b32 s46, s72, s4
	s_cselect_b32 s5, s37, s75
	s_cselect_b32 s4, s73, s74
	v_lshl_add_u64 v[136:137], s[0:1], 0, v[160:161]
	s_add_i32 m0, s58, 0xc000
	ds_read_b128 v[202:205], v146
	ds_read_b128 v[206:209], v146 offset:1024
	ds_read_b128 v[210:213], v146 offset:2048
	ds_read_b128 v[214:217], v146 offset:3072
	ds_read_b128 v[218:221], v146 offset:4096
	ds_read_b128 v[222:225], v146 offset:5120
	ds_read_b128 v[228:231], v146 offset:6144
	ds_read_b128 v[232:235], v146 offset:7168
	global_load_lds_dwordx4 v[136:137], off
	v_lshl_add_u64 v[136:137], s[0:1], 0, v[162:163]
	s_add_i32 m0, s58, 0xe000
	s_nop 0
	global_load_lds_dwordx4 v[136:137], off
	s_waitcnt vmcnt(8)
	s_waitcnt lgkmcnt(0)
	s_barrier
	s_setprio 1
	v_mfma_f32_16x16x32_bf16 v[124:127], v[128:131], v[202:205], 0
	v_mfma_f32_16x16x32_bf16 v[120:123], v[164:167], v[202:205], 0
	v_mfma_f32_16x16x32_bf16 v[108:111], v[128:131], v[210:213], 0
	v_mfma_f32_16x16x32_bf16 v[104:107], v[164:167], v[210:213], 0
	v_mfma_f32_16x16x32_bf16 v[92:95], v[128:131], v[218:221], 0
	v_mfma_f32_16x16x32_bf16 v[88:91], v[164:167], v[218:221], 0
	v_mfma_f32_16x16x32_bf16 v[76:79], v[128:131], v[228:231], 0
	v_mfma_f32_16x16x32_bf16 v[72:75], v[164:167], v[228:231], 0
	v_mfma_f32_16x16x32_bf16 v[124:127], v[132:135], v[206:209], v[124:127]
	v_mfma_f32_16x16x32_bf16 v[120:123], v[168:171], v[206:209], v[120:123]
	v_mfma_f32_16x16x32_bf16 v[108:111], v[132:135], v[214:217], v[108:111]
	v_mfma_f32_16x16x32_bf16 v[104:107], v[168:171], v[214:217], v[104:107]
	v_mfma_f32_16x16x32_bf16 v[92:95], v[132:135], v[222:225], v[92:95]
	v_mfma_f32_16x16x32_bf16 v[88:91], v[168:171], v[222:225], v[88:91]
	v_mfma_f32_16x16x32_bf16 v[76:79], v[132:135], v[232:235], v[76:79]
	v_mfma_f32_16x16x32_bf16 v[72:75], v[168:171], v[232:235], v[72:75]
	s_setprio 0
	s_setprio 1
	v_mfma_f32_16x16x32_bf16 v[116:119], v[172:175], v[202:205], 0
	v_mfma_f32_16x16x32_bf16 v[112:115], v[194:197], v[202:205], 0
	v_mfma_f32_16x16x32_bf16 v[100:103], v[172:175], v[210:213], 0
	v_mfma_f32_16x16x32_bf16 v[96:99], v[194:197], v[210:213], 0
	v_mfma_f32_16x16x32_bf16 v[84:87], v[172:175], v[218:221], 0
	v_mfma_f32_16x16x32_bf16 v[80:83], v[194:197], v[218:221], 0
	v_mfma_f32_16x16x32_bf16 v[68:71], v[172:175], v[228:231], 0
	v_mfma_f32_16x16x32_bf16 v[64:67], v[194:197], v[228:231], 0
	v_mfma_f32_16x16x32_bf16 v[116:119], v[176:179], v[206:209], v[116:119]
	v_mfma_f32_16x16x32_bf16 v[112:115], v[198:201], v[206:209], v[112:115]
	v_mfma_f32_16x16x32_bf16 v[100:103], v[176:179], v[214:217], v[100:103]
	v_mfma_f32_16x16x32_bf16 v[96:99], v[198:201], v[214:217], v[96:99]
	v_mfma_f32_16x16x32_bf16 v[84:87], v[176:179], v[222:225], v[84:87]
	v_mfma_f32_16x16x32_bf16 v[80:83], v[198:201], v[222:225], v[80:83]
	v_mfma_f32_16x16x32_bf16 v[68:71], v[176:179], v[232:235], v[68:71]
	v_mfma_f32_16x16x32_bf16 v[64:67], v[198:201], v[232:235], v[64:67]
	s_setprio 0
	s_barrier
	s_add_i32 s77, s48, s57
	v_lshl_add_u64 v[136:137], s[4:5], 0, v[156:157]
	s_mov_b32 m0, s77
	ds_read_b128 v[202:205], v146 offset:16384
	ds_read_b128 v[206:209], v146 offset:17408
	ds_read_b128 v[210:213], v146 offset:18432
	ds_read_b128 v[214:217], v146 offset:19456
	ds_read_b128 v[218:221], v146 offset:20480
	ds_read_b128 v[222:225], v146 offset:21504
	ds_read_b128 v[228:231], v146 offset:22528
	ds_read_b128 v[232:235], v146 offset:23552
	global_load_lds_dwordx4 v[136:137], off
	s_add_i32 m0, s77, 0x2000
	s_add_u32 s78, s4, 0x40000
	v_lshl_add_u64 v[150:151], s[4:5], 0, v[152:153]
	s_addc_u32 s79, s5, 0
	s_add_i32 s77, s49, s57
	global_load_lds_dwordx4 v[150:151], off
	v_lshl_add_u64 v[180:181], s[78:79], 0, v[156:157]
	s_mov_b32 m0, s77
	v_lshl_add_u64 v[236:237], s[46:47], 0, v[154:155]
	global_load_lds_dwordx4 v[180:181], off
	v_lshl_add_u64 v[180:181], s[78:79], 0, v[152:153]
	s_add_i32 m0, s77, 0x2000
	s_nop 0
	global_load_lds_dwordx4 v[180:181], off
	v_lshl_add_u64 v[180:181], s[46:47], 0, v[158:159]
	s_mov_b32 m0, s58
	s_nop 0
	global_load_lds_dwordx4 v[180:181], off
	s_mov_b32 m0, s59
	s_nop 0
	global_load_lds_dwordx4 v[236:237], off
	s_waitcnt vmcnt(8)
	s_waitcnt lgkmcnt(0)
	s_barrier
	s_setprio 1
	v_mfma_f32_16x16x32_bf16 v[60:63], v[128:131], v[202:205], 0
	v_mfma_f32_16x16x32_bf16 v[56:59], v[164:167], v[202:205], 0
	v_mfma_f32_16x16x32_bf16 v[44:47], v[128:131], v[210:213], 0
	v_mfma_f32_16x16x32_bf16 v[40:43], v[164:167], v[210:213], 0
	v_mfma_f32_16x16x32_bf16 v[28:31], v[128:131], v[218:221], 0
	v_mfma_f32_16x16x32_bf16 v[24:27], v[164:167], v[218:221], 0
	v_mfma_f32_16x16x32_bf16 v[12:15], v[128:131], v[228:231], 0
	v_mfma_f32_16x16x32_bf16 v[8:11], v[164:167], v[228:231], 0
	v_mfma_f32_16x16x32_bf16 v[60:63], v[132:135], v[206:209], v[60:63]
	v_mfma_f32_16x16x32_bf16 v[56:59], v[168:171], v[206:209], v[56:59]
	v_mfma_f32_16x16x32_bf16 v[44:47], v[132:135], v[214:217], v[44:47]
	v_mfma_f32_16x16x32_bf16 v[40:43], v[168:171], v[214:217], v[40:43]
	v_mfma_f32_16x16x32_bf16 v[28:31], v[132:135], v[222:225], v[28:31]
	v_mfma_f32_16x16x32_bf16 v[24:27], v[168:171], v[222:225], v[24:27]
	v_mfma_f32_16x16x32_bf16 v[12:15], v[132:135], v[232:235], v[12:15]
	v_mfma_f32_16x16x32_bf16 v[8:11], v[168:171], v[232:235], v[8:11]
	s_setprio 0
	s_setprio 1
	v_mfma_f32_16x16x32_bf16 v[52:55], v[172:175], v[202:205], 0
	v_mfma_f32_16x16x32_bf16 v[48:51], v[194:197], v[202:205], 0
	v_mfma_f32_16x16x32_bf16 v[36:39], v[172:175], v[210:213], 0
	v_mfma_f32_16x16x32_bf16 v[32:35], v[194:197], v[210:213], 0
	v_mfma_f32_16x16x32_bf16 v[20:23], v[172:175], v[218:221], 0
	v_mfma_f32_16x16x32_bf16 v[16:19], v[194:197], v[218:221], 0
	v_mfma_f32_16x16x32_bf16 v[4:7], v[172:175], v[228:231], 0
	v_mfma_f32_16x16x32_bf16 v[0:3], v[194:197], v[228:231], 0
	v_mfma_f32_16x16x32_bf16 v[52:55], v[176:179], v[206:209], v[52:55]
	v_mfma_f32_16x16x32_bf16 v[48:51], v[198:201], v[206:209], v[48:51]
	v_mfma_f32_16x16x32_bf16 v[36:39], v[176:179], v[214:217], v[36:39]
	v_mfma_f32_16x16x32_bf16 v[32:35], v[198:201], v[214:217], v[32:35]
	v_mfma_f32_16x16x32_bf16 v[20:23], v[176:179], v[222:225], v[20:23]
	v_mfma_f32_16x16x32_bf16 v[16:19], v[198:201], v[222:225], v[16:19]
	v_mfma_f32_16x16x32_bf16 v[4:7], v[176:179], v[232:235], v[4:7]
	v_mfma_f32_16x16x32_bf16 v[0:3], v[198:201], v[232:235], v[0:3]
	s_setprio 0
	s_barrier
	v_add_u32_e32 v149, s51, v142
	ds_read_b128 v[128:131], v149
	ds_read_b128 v[132:135], v149 offset:1024
	ds_read_b128 v[164:167], v149 offset:2048
	ds_read_b128 v[168:171], v149 offset:3072
	v_add_u32_e32 v149, s53, v142
	ds_read_b128 v[172:175], v149
	ds_read_b128 v[176:179], v149 offset:1024
	ds_read_b128 v[194:197], v149 offset:2048
	ds_read_b128 v[198:201], v149 offset:3072
	s_add_u32 s46, s46, 0x40000
	s_addc_u32 s47, s47, 0
	s_mov_b32 m0, s60
	v_lshl_add_u64 v[238:239], s[46:47], 0, v[158:159]
	ds_read_b128 v[202:205], v146 offset:32768
	ds_read_b128 v[206:209], v146 offset:33792
	ds_read_b128 v[210:213], v146 offset:34816
	ds_read_b128 v[214:217], v146 offset:35840
	ds_read_b128 v[218:221], v146 offset:36864
	ds_read_b128 v[222:225], v146 offset:37888
	ds_read_b128 v[228:231], v146 offset:38912
	ds_read_b128 v[232:235], v146 offset:39936
	global_load_lds_dwordx4 v[238:239], off
	v_lshl_add_u64 v[238:239], s[46:47], 0, v[154:155]
	s_mov_b32 m0, s61
	s_nop 0
	global_load_lds_dwordx4 v[238:239], off
	s_waitcnt vmcnt(8)
	s_waitcnt lgkmcnt(0)
	s_barrier
	s_setprio 1
	v_mfma_f32_16x16x32_bf16 v[124:127], v[128:131], v[202:205], v[124:127]
	v_mfma_f32_16x16x32_bf16 v[120:123], v[164:167], v[202:205], v[120:123]
	v_mfma_f32_16x16x32_bf16 v[108:111], v[128:131], v[210:213], v[108:111]
	v_mfma_f32_16x16x32_bf16 v[104:107], v[164:167], v[210:213], v[104:107]
	v_mfma_f32_16x16x32_bf16 v[92:95], v[128:131], v[218:221], v[92:95]
	v_mfma_f32_16x16x32_bf16 v[88:91], v[164:167], v[218:221], v[88:91]
	v_mfma_f32_16x16x32_bf16 v[76:79], v[128:131], v[228:231], v[76:79]
	v_mfma_f32_16x16x32_bf16 v[72:75], v[164:167], v[228:231], v[72:75]
	v_mfma_f32_16x16x32_bf16 v[124:127], v[132:135], v[206:209], v[124:127]
	v_mfma_f32_16x16x32_bf16 v[120:123], v[168:171], v[206:209], v[120:123]
	v_mfma_f32_16x16x32_bf16 v[108:111], v[132:135], v[214:217], v[108:111]
	v_mfma_f32_16x16x32_bf16 v[104:107], v[168:171], v[214:217], v[104:107]
	v_mfma_f32_16x16x32_bf16 v[92:95], v[132:135], v[222:225], v[92:95]
	v_mfma_f32_16x16x32_bf16 v[88:91], v[168:171], v[222:225], v[88:91]
	v_mfma_f32_16x16x32_bf16 v[76:79], v[132:135], v[232:235], v[76:79]
	v_mfma_f32_16x16x32_bf16 v[72:75], v[168:171], v[232:235], v[72:75]
	s_setprio 0
	s_setprio 1
	v_mfma_f32_16x16x32_bf16 v[116:119], v[172:175], v[202:205], v[116:119]
	v_mfma_f32_16x16x32_bf16 v[112:115], v[194:197], v[202:205], v[112:115]
	v_mfma_f32_16x16x32_bf16 v[100:103], v[172:175], v[210:213], v[100:103]
	v_mfma_f32_16x16x32_bf16 v[96:99], v[194:197], v[210:213], v[96:99]
	v_mfma_f32_16x16x32_bf16 v[84:87], v[172:175], v[218:221], v[84:87]
	v_mfma_f32_16x16x32_bf16 v[80:83], v[194:197], v[218:221], v[80:83]
	v_mfma_f32_16x16x32_bf16 v[68:71], v[172:175], v[228:231], v[68:71]
	v_mfma_f32_16x16x32_bf16 v[64:67], v[194:197], v[228:231], v[64:67]
	v_mfma_f32_16x16x32_bf16 v[116:119], v[176:179], v[206:209], v[116:119]
	v_mfma_f32_16x16x32_bf16 v[112:115], v[198:201], v[206:209], v[112:115]
	v_mfma_f32_16x16x32_bf16 v[100:103], v[176:179], v[214:217], v[100:103]
	v_mfma_f32_16x16x32_bf16 v[96:99], v[198:201], v[214:217], v[96:99]
	v_mfma_f32_16x16x32_bf16 v[84:87], v[176:179], v[222:225], v[84:87]
	v_mfma_f32_16x16x32_bf16 v[80:83], v[198:201], v[222:225], v[80:83]
	v_mfma_f32_16x16x32_bf16 v[68:71], v[176:179], v[232:235], v[68:71]
	v_mfma_f32_16x16x32_bf16 v[64:67], v[198:201], v[232:235], v[64:67]
	s_setprio 0
	s_barrier
	s_add_i32 s46, s51, s57
	v_lshl_add_u64 v[136:137], v[136:137], 0, s[22:23]
	s_mov_b32 m0, s46
	ds_read_b128 v[202:205], v146 offset:49152
	ds_read_b128 v[206:209], v146 offset:50176
	ds_read_b128 v[210:213], v146 offset:51200
	ds_read_b128 v[214:217], v146 offset:52224
	ds_read_b128 v[218:221], v146 offset:53248
	ds_read_b128 v[222:225], v146 offset:54272
	ds_read_b128 v[228:231], v146 offset:55296
	ds_read_b128 v[232:235], v146 offset:56320
	global_load_lds_dwordx4 v[136:137], off
	s_add_i32 m0, s46, 0x2000
	s_add_u32 s4, s4, 0x40080
	v_lshl_add_u64 v[136:137], v[150:151], 0, s[22:23]
	s_addc_u32 s5, s5, 0
	s_add_i32 s46, s53, s57
	global_load_lds_dwordx4 v[136:137], off
	v_lshl_add_u64 v[136:137], s[4:5], 0, v[156:157]
	s_mov_b32 m0, s46
	s_nop 0
	global_load_lds_dwordx4 v[136:137], off
	v_lshl_add_u64 v[136:137], s[4:5], 0, v[152:153]
	s_add_i32 m0, s46, 0x2000
	s_nop 0
	global_load_lds_dwordx4 v[136:137], off
	v_lshl_add_u64 v[136:137], v[180:181], 0, s[22:23]
	s_mov_b32 m0, s62
	s_nop 0
	global_load_lds_dwordx4 v[136:137], off
	v_lshl_add_u64 v[136:137], v[236:237], 0, s[22:23]
	s_mov_b32 m0, s63
	s_nop 0
	global_load_lds_dwordx4 v[136:137], off
	s_waitcnt vmcnt(8)
	s_waitcnt lgkmcnt(0)
	s_barrier
	s_setprio 1
	v_mfma_f32_16x16x32_bf16 v[60:63], v[128:131], v[202:205], v[60:63]
	v_mfma_f32_16x16x32_bf16 v[56:59], v[164:167], v[202:205], v[56:59]
	v_mfma_f32_16x16x32_bf16 v[44:47], v[128:131], v[210:213], v[44:47]
	v_mfma_f32_16x16x32_bf16 v[40:43], v[164:167], v[210:213], v[40:43]
	v_mfma_f32_16x16x32_bf16 v[28:31], v[128:131], v[218:221], v[28:31]
	v_mfma_f32_16x16x32_bf16 v[24:27], v[164:167], v[218:221], v[24:27]
	v_mfma_f32_16x16x32_bf16 v[12:15], v[128:131], v[228:231], v[12:15]
	v_mfma_f32_16x16x32_bf16 v[8:11], v[164:167], v[228:231], v[8:11]
	v_mfma_f32_16x16x32_bf16 v[60:63], v[132:135], v[206:209], v[60:63]
	v_mfma_f32_16x16x32_bf16 v[56:59], v[168:171], v[206:209], v[56:59]
	v_mfma_f32_16x16x32_bf16 v[44:47], v[132:135], v[214:217], v[44:47]
	v_mfma_f32_16x16x32_bf16 v[40:43], v[168:171], v[214:217], v[40:43]
	v_mfma_f32_16x16x32_bf16 v[28:31], v[132:135], v[222:225], v[28:31]
	v_mfma_f32_16x16x32_bf16 v[24:27], v[168:171], v[222:225], v[24:27]
	v_mfma_f32_16x16x32_bf16 v[12:15], v[132:135], v[232:235], v[12:15]
	v_mfma_f32_16x16x32_bf16 v[8:11], v[168:171], v[232:235], v[8:11]
	s_setprio 0
	s_setprio 1
	v_mfma_f32_16x16x32_bf16 v[52:55], v[172:175], v[202:205], v[52:55]
	v_mfma_f32_16x16x32_bf16 v[48:51], v[194:197], v[202:205], v[48:51]
	v_mfma_f32_16x16x32_bf16 v[36:39], v[172:175], v[210:213], v[36:39]
	v_mfma_f32_16x16x32_bf16 v[32:35], v[194:197], v[210:213], v[32:35]
	v_mfma_f32_16x16x32_bf16 v[20:23], v[172:175], v[218:221], v[20:23]
	v_mfma_f32_16x16x32_bf16 v[16:19], v[194:197], v[218:221], v[16:19]
	v_mfma_f32_16x16x32_bf16 v[4:7], v[172:175], v[228:231], v[4:7]
	v_mfma_f32_16x16x32_bf16 v[0:3], v[194:197], v[228:231], v[0:3]
	v_mfma_f32_16x16x32_bf16 v[52:55], v[176:179], v[206:209], v[52:55]
	v_mfma_f32_16x16x32_bf16 v[48:51], v[198:201], v[206:209], v[48:51]
	v_mfma_f32_16x16x32_bf16 v[36:39], v[176:179], v[214:217], v[36:39]
	v_mfma_f32_16x16x32_bf16 v[32:35], v[198:201], v[214:217], v[32:35]
	v_mfma_f32_16x16x32_bf16 v[20:23], v[176:179], v[222:225], v[20:23]
	v_mfma_f32_16x16x32_bf16 v[16:19], v[198:201], v[222:225], v[16:19]
	v_mfma_f32_16x16x32_bf16 v[4:7], v[176:179], v[232:235], v[4:7]
	v_mfma_f32_16x16x32_bf16 v[0:3], v[198:201], v[232:235], v[0:3]
	s_setprio 0
	s_barrier
	s_add_i32 s76, s76, 2
	s_add_u32 s0, s0, 0x100
	s_addc_u32 s1, s1, 0
	s_add_u32 s74, s74, 0x100
	s_addc_u32 s75, s75, 0
	s_cmp_gt_u32 s76, 13
.LBB0_994:
	ds_read_b128 v[128:131], v144
	ds_read_b128 v[132:135], v144 offset:1024
	ds_read_b128 v[164:167], v144 offset:2048
	ds_read_b128 v[168:171], v144 offset:3072
	ds_read_b128 v[172:175], v145
	ds_read_b128 v[176:179], v145 offset:1024
	ds_read_b128 v[194:197], v145 offset:2048
	ds_read_b128 v[198:201], v145 offset:3072
	s_add_u32 s4, s0, 0xfffc0080
	s_addc_u32 s5, s1, -1
	s_cmp_eq_u32 s76, 12
	s_cselect_b32 s47, s43, s5
	s_cselect_b32 s46, s72, s4
	s_cselect_b32 s5, s37, s75
	s_cselect_b32 s4, s73, s74
	v_lshl_add_u64 v[136:137], s[0:1], 0, v[160:161]
	s_add_i32 m0, s58, 0xc000
	ds_read_b128 v[202:205], v146
	ds_read_b128 v[206:209], v146 offset:1024
	ds_read_b128 v[210:213], v146 offset:2048
	ds_read_b128 v[214:217], v146 offset:3072
	ds_read_b128 v[218:221], v146 offset:4096
	ds_read_b128 v[222:225], v146 offset:5120
	ds_read_b128 v[228:231], v146 offset:6144
	ds_read_b128 v[232:235], v146 offset:7168
	global_load_lds_dwordx4 v[136:137], off
	v_lshl_add_u64 v[136:137], s[0:1], 0, v[162:163]
	s_add_i32 m0, s58, 0xe000
	s_nop 0
	global_load_lds_dwordx4 v[136:137], off
	s_waitcnt vmcnt(8)
	s_waitcnt lgkmcnt(0)
	s_barrier
	s_setprio 1
	v_mfma_f32_16x16x32_bf16 v[124:127], v[128:131], v[202:205], v[124:127]
	v_mfma_f32_16x16x32_bf16 v[120:123], v[164:167], v[202:205], v[120:123]
	v_mfma_f32_16x16x32_bf16 v[108:111], v[128:131], v[210:213], v[108:111]
	v_mfma_f32_16x16x32_bf16 v[104:107], v[164:167], v[210:213], v[104:107]
	v_mfma_f32_16x16x32_bf16 v[92:95], v[128:131], v[218:221], v[92:95]
	v_mfma_f32_16x16x32_bf16 v[88:91], v[164:167], v[218:221], v[88:91]
	v_mfma_f32_16x16x32_bf16 v[76:79], v[128:131], v[228:231], v[76:79]
	v_mfma_f32_16x16x32_bf16 v[72:75], v[164:167], v[228:231], v[72:75]
	v_mfma_f32_16x16x32_bf16 v[124:127], v[132:135], v[206:209], v[124:127]
	v_mfma_f32_16x16x32_bf16 v[120:123], v[168:171], v[206:209], v[120:123]
	v_mfma_f32_16x16x32_bf16 v[108:111], v[132:135], v[214:217], v[108:111]
	v_mfma_f32_16x16x32_bf16 v[104:107], v[168:171], v[214:217], v[104:107]
	v_mfma_f32_16x16x32_bf16 v[92:95], v[132:135], v[222:225], v[92:95]
	v_mfma_f32_16x16x32_bf16 v[88:91], v[168:171], v[222:225], v[88:91]
	v_mfma_f32_16x16x32_bf16 v[76:79], v[132:135], v[232:235], v[76:79]
	v_mfma_f32_16x16x32_bf16 v[72:75], v[168:171], v[232:235], v[72:75]
	s_setprio 0
	s_setprio 1
	v_mfma_f32_16x16x32_bf16 v[116:119], v[172:175], v[202:205], v[116:119]
	v_mfma_f32_16x16x32_bf16 v[112:115], v[194:197], v[202:205], v[112:115]
	v_mfma_f32_16x16x32_bf16 v[100:103], v[172:175], v[210:213], v[100:103]
	v_mfma_f32_16x16x32_bf16 v[96:99], v[194:197], v[210:213], v[96:99]
	v_mfma_f32_16x16x32_bf16 v[84:87], v[172:175], v[218:221], v[84:87]
	v_mfma_f32_16x16x32_bf16 v[80:83], v[194:197], v[218:221], v[80:83]
	v_mfma_f32_16x16x32_bf16 v[68:71], v[172:175], v[228:231], v[68:71]
	v_mfma_f32_16x16x32_bf16 v[64:67], v[194:197], v[228:231], v[64:67]
	v_mfma_f32_16x16x32_bf16 v[116:119], v[176:179], v[206:209], v[116:119]
	v_mfma_f32_16x16x32_bf16 v[112:115], v[198:201], v[206:209], v[112:115]
	v_mfma_f32_16x16x32_bf16 v[100:103], v[176:179], v[214:217], v[100:103]
	v_mfma_f32_16x16x32_bf16 v[96:99], v[198:201], v[214:217], v[96:99]
	v_mfma_f32_16x16x32_bf16 v[84:87], v[176:179], v[222:225], v[84:87]
	v_mfma_f32_16x16x32_bf16 v[80:83], v[198:201], v[222:225], v[80:83]
	v_mfma_f32_16x16x32_bf16 v[68:71], v[176:179], v[232:235], v[68:71]
	v_mfma_f32_16x16x32_bf16 v[64:67], v[198:201], v[232:235], v[64:67]
	s_setprio 0
	s_barrier
	s_add_i32 s77, s48, s57
	v_lshl_add_u64 v[136:137], s[4:5], 0, v[156:157]
	s_mov_b32 m0, s77
	ds_read_b128 v[202:205], v146 offset:16384
	ds_read_b128 v[206:209], v146 offset:17408
	ds_read_b128 v[210:213], v146 offset:18432
	ds_read_b128 v[214:217], v146 offset:19456
	ds_read_b128 v[218:221], v146 offset:20480
	ds_read_b128 v[222:225], v146 offset:21504
	ds_read_b128 v[228:231], v146 offset:22528
	ds_read_b128 v[232:235], v146 offset:23552
	global_load_lds_dwordx4 v[136:137], off
	s_add_i32 m0, s77, 0x2000
	s_add_u32 s78, s4, 0x40000
	v_lshl_add_u64 v[150:151], s[4:5], 0, v[152:153]
	s_addc_u32 s79, s5, 0
	s_add_i32 s77, s49, s57
	global_load_lds_dwordx4 v[150:151], off
	v_lshl_add_u64 v[180:181], s[78:79], 0, v[156:157]
	s_mov_b32 m0, s77
	v_lshl_add_u64 v[236:237], s[46:47], 0, v[154:155]
	global_load_lds_dwordx4 v[180:181], off
	v_lshl_add_u64 v[180:181], s[78:79], 0, v[152:153]
	s_add_i32 m0, s77, 0x2000
	s_nop 0
	global_load_lds_dwordx4 v[180:181], off
	v_lshl_add_u64 v[180:181], s[46:47], 0, v[158:159]
	s_mov_b32 m0, s58
	s_nop 0
	global_load_lds_dwordx4 v[180:181], off
	s_mov_b32 m0, s59
	s_nop 0
	global_load_lds_dwordx4 v[236:237], off
	s_waitcnt vmcnt(8)
	s_waitcnt lgkmcnt(0)
	s_barrier
	s_setprio 1
	v_mfma_f32_16x16x32_bf16 v[60:63], v[128:131], v[202:205], v[60:63]
	v_mfma_f32_16x16x32_bf16 v[56:59], v[164:167], v[202:205], v[56:59]
	v_mfma_f32_16x16x32_bf16 v[44:47], v[128:131], v[210:213], v[44:47]
	v_mfma_f32_16x16x32_bf16 v[40:43], v[164:167], v[210:213], v[40:43]
	v_mfma_f32_16x16x32_bf16 v[28:31], v[128:131], v[218:221], v[28:31]
	v_mfma_f32_16x16x32_bf16 v[24:27], v[164:167], v[218:221], v[24:27]
	v_mfma_f32_16x16x32_bf16 v[12:15], v[128:131], v[228:231], v[12:15]
	v_mfma_f32_16x16x32_bf16 v[8:11], v[164:167], v[228:231], v[8:11]
	v_mfma_f32_16x16x32_bf16 v[60:63], v[132:135], v[206:209], v[60:63]
	v_mfma_f32_16x16x32_bf16 v[56:59], v[168:171], v[206:209], v[56:59]
	v_mfma_f32_16x16x32_bf16 v[44:47], v[132:135], v[214:217], v[44:47]
	v_mfma_f32_16x16x32_bf16 v[40:43], v[168:171], v[214:217], v[40:43]
	v_mfma_f32_16x16x32_bf16 v[28:31], v[132:135], v[222:225], v[28:31]
	v_mfma_f32_16x16x32_bf16 v[24:27], v[168:171], v[222:225], v[24:27]
	v_mfma_f32_16x16x32_bf16 v[12:15], v[132:135], v[232:235], v[12:15]
	v_mfma_f32_16x16x32_bf16 v[8:11], v[168:171], v[232:235], v[8:11]
	s_setprio 0
	s_setprio 1
	v_mfma_f32_16x16x32_bf16 v[52:55], v[172:175], v[202:205], v[52:55]
	v_mfma_f32_16x16x32_bf16 v[48:51], v[194:197], v[202:205], v[48:51]
	v_mfma_f32_16x16x32_bf16 v[36:39], v[172:175], v[210:213], v[36:39]
	v_mfma_f32_16x16x32_bf16 v[32:35], v[194:197], v[210:213], v[32:35]
	v_mfma_f32_16x16x32_bf16 v[20:23], v[172:175], v[218:221], v[20:23]
	v_mfma_f32_16x16x32_bf16 v[16:19], v[194:197], v[218:221], v[16:19]
	v_mfma_f32_16x16x32_bf16 v[4:7], v[172:175], v[228:231], v[4:7]
	v_mfma_f32_16x16x32_bf16 v[0:3], v[194:197], v[228:231], v[0:3]
	v_mfma_f32_16x16x32_bf16 v[52:55], v[176:179], v[206:209], v[52:55]
	v_mfma_f32_16x16x32_bf16 v[48:51], v[198:201], v[206:209], v[48:51]
	v_mfma_f32_16x16x32_bf16 v[36:39], v[176:179], v[214:217], v[36:39]
	v_mfma_f32_16x16x32_bf16 v[32:35], v[198:201], v[214:217], v[32:35]
	v_mfma_f32_16x16x32_bf16 v[20:23], v[176:179], v[222:225], v[20:23]
	v_mfma_f32_16x16x32_bf16 v[16:19], v[198:201], v[222:225], v[16:19]
	v_mfma_f32_16x16x32_bf16 v[4:7], v[176:179], v[232:235], v[4:7]
	v_mfma_f32_16x16x32_bf16 v[0:3], v[198:201], v[232:235], v[0:3]
	s_setprio 0
	s_barrier
	v_add_u32_e32 v149, s51, v142
	ds_read_b128 v[128:131], v149
	ds_read_b128 v[132:135], v149 offset:1024
	ds_read_b128 v[164:167], v149 offset:2048
	ds_read_b128 v[168:171], v149 offset:3072
	v_add_u32_e32 v149, s53, v142
	ds_read_b128 v[172:175], v149
	ds_read_b128 v[176:179], v149 offset:1024
	ds_read_b128 v[194:197], v149 offset:2048
	ds_read_b128 v[198:201], v149 offset:3072
	s_add_u32 s46, s46, 0x40000
	s_addc_u32 s47, s47, 0
	s_mov_b32 m0, s60
	v_lshl_add_u64 v[238:239], s[46:47], 0, v[158:159]
	ds_read_b128 v[202:205], v146 offset:32768
	ds_read_b128 v[206:209], v146 offset:33792
	ds_read_b128 v[210:213], v146 offset:34816
	ds_read_b128 v[214:217], v146 offset:35840
	ds_read_b128 v[218:221], v146 offset:36864
	ds_read_b128 v[222:225], v146 offset:37888
	ds_read_b128 v[228:231], v146 offset:38912
	ds_read_b128 v[232:235], v146 offset:39936
	global_load_lds_dwordx4 v[238:239], off
	v_lshl_add_u64 v[238:239], s[46:47], 0, v[154:155]
	s_mov_b32 m0, s61
	s_nop 0
	global_load_lds_dwordx4 v[238:239], off
	s_waitcnt vmcnt(8)
	s_waitcnt lgkmcnt(0)
	s_barrier
	s_setprio 1
	v_mfma_f32_16x16x32_bf16 v[124:127], v[128:131], v[202:205], v[124:127]
	v_mfma_f32_16x16x32_bf16 v[120:123], v[164:167], v[202:205], v[120:123]
	v_mfma_f32_16x16x32_bf16 v[108:111], v[128:131], v[210:213], v[108:111]
	v_mfma_f32_16x16x32_bf16 v[104:107], v[164:167], v[210:213], v[104:107]
	v_mfma_f32_16x16x32_bf16 v[92:95], v[128:131], v[218:221], v[92:95]
	v_mfma_f32_16x16x32_bf16 v[88:91], v[164:167], v[218:221], v[88:91]
	v_mfma_f32_16x16x32_bf16 v[76:79], v[128:131], v[228:231], v[76:79]
	v_mfma_f32_16x16x32_bf16 v[72:75], v[164:167], v[228:231], v[72:75]
	v_mfma_f32_16x16x32_bf16 v[124:127], v[132:135], v[206:209], v[124:127]
	v_mfma_f32_16x16x32_bf16 v[120:123], v[168:171], v[206:209], v[120:123]
	v_mfma_f32_16x16x32_bf16 v[108:111], v[132:135], v[214:217], v[108:111]
	v_mfma_f32_16x16x32_bf16 v[104:107], v[168:171], v[214:217], v[104:107]
	v_mfma_f32_16x16x32_bf16 v[92:95], v[132:135], v[222:225], v[92:95]
	v_mfma_f32_16x16x32_bf16 v[88:91], v[168:171], v[222:225], v[88:91]
	v_mfma_f32_16x16x32_bf16 v[76:79], v[132:135], v[232:235], v[76:79]
	v_mfma_f32_16x16x32_bf16 v[72:75], v[168:171], v[232:235], v[72:75]
	s_setprio 0
	s_setprio 1
	v_mfma_f32_16x16x32_bf16 v[116:119], v[172:175], v[202:205], v[116:119]
	v_mfma_f32_16x16x32_bf16 v[112:115], v[194:197], v[202:205], v[112:115]
	v_mfma_f32_16x16x32_bf16 v[100:103], v[172:175], v[210:213], v[100:103]
	v_mfma_f32_16x16x32_bf16 v[96:99], v[194:197], v[210:213], v[96:99]
	v_mfma_f32_16x16x32_bf16 v[84:87], v[172:175], v[218:221], v[84:87]
	v_mfma_f32_16x16x32_bf16 v[80:83], v[194:197], v[218:221], v[80:83]
	v_mfma_f32_16x16x32_bf16 v[68:71], v[172:175], v[228:231], v[68:71]
	v_mfma_f32_16x16x32_bf16 v[64:67], v[194:197], v[228:231], v[64:67]
	v_mfma_f32_16x16x32_bf16 v[116:119], v[176:179], v[206:209], v[116:119]
	v_mfma_f32_16x16x32_bf16 v[112:115], v[198:201], v[206:209], v[112:115]
	v_mfma_f32_16x16x32_bf16 v[100:103], v[176:179], v[214:217], v[100:103]
	v_mfma_f32_16x16x32_bf16 v[96:99], v[198:201], v[214:217], v[96:99]
	v_mfma_f32_16x16x32_bf16 v[84:87], v[176:179], v[222:225], v[84:87]
	v_mfma_f32_16x16x32_bf16 v[80:83], v[198:201], v[222:225], v[80:83]
	v_mfma_f32_16x16x32_bf16 v[68:71], v[176:179], v[232:235], v[68:71]
	v_mfma_f32_16x16x32_bf16 v[64:67], v[198:201], v[232:235], v[64:67]
	s_setprio 0
	s_barrier
	s_add_i32 s46, s51, s57
	v_lshl_add_u64 v[136:137], v[136:137], 0, s[22:23]
	s_mov_b32 m0, s46
	ds_read_b128 v[202:205], v146 offset:49152
	ds_read_b128 v[206:209], v146 offset:50176
	ds_read_b128 v[210:213], v146 offset:51200
	ds_read_b128 v[214:217], v146 offset:52224
	ds_read_b128 v[218:221], v146 offset:53248
	ds_read_b128 v[222:225], v146 offset:54272
	ds_read_b128 v[228:231], v146 offset:55296
	ds_read_b128 v[232:235], v146 offset:56320
	global_load_lds_dwordx4 v[136:137], off
	s_add_i32 m0, s46, 0x2000
	s_add_u32 s4, s4, 0x40080
	v_lshl_add_u64 v[136:137], v[150:151], 0, s[22:23]
	s_addc_u32 s5, s5, 0
	s_add_i32 s46, s53, s57
	global_load_lds_dwordx4 v[136:137], off
	v_lshl_add_u64 v[136:137], s[4:5], 0, v[156:157]
	s_mov_b32 m0, s46
	s_nop 0
	global_load_lds_dwordx4 v[136:137], off
	v_lshl_add_u64 v[136:137], s[4:5], 0, v[152:153]
	s_add_i32 m0, s46, 0x2000
	s_nop 0
	global_load_lds_dwordx4 v[136:137], off
	v_lshl_add_u64 v[136:137], v[180:181], 0, s[22:23]
	s_mov_b32 m0, s62
	s_nop 0
	global_load_lds_dwordx4 v[136:137], off
	v_lshl_add_u64 v[136:137], v[236:237], 0, s[22:23]
	s_mov_b32 m0, s63
	s_nop 0
	global_load_lds_dwordx4 v[136:137], off
	s_waitcnt vmcnt(8)
	s_waitcnt lgkmcnt(0)
	s_barrier
	s_setprio 1
	v_mfma_f32_16x16x32_bf16 v[60:63], v[128:131], v[202:205], v[60:63]
	v_mfma_f32_16x16x32_bf16 v[56:59], v[164:167], v[202:205], v[56:59]
	v_mfma_f32_16x16x32_bf16 v[44:47], v[128:131], v[210:213], v[44:47]
	v_mfma_f32_16x16x32_bf16 v[40:43], v[164:167], v[210:213], v[40:43]
	v_mfma_f32_16x16x32_bf16 v[28:31], v[128:131], v[218:221], v[28:31]
	v_mfma_f32_16x16x32_bf16 v[24:27], v[164:167], v[218:221], v[24:27]
	v_mfma_f32_16x16x32_bf16 v[12:15], v[128:131], v[228:231], v[12:15]
	v_mfma_f32_16x16x32_bf16 v[8:11], v[164:167], v[228:231], v[8:11]
	v_mfma_f32_16x16x32_bf16 v[60:63], v[132:135], v[206:209], v[60:63]
	v_mfma_f32_16x16x32_bf16 v[56:59], v[168:171], v[206:209], v[56:59]
	v_mfma_f32_16x16x32_bf16 v[44:47], v[132:135], v[214:217], v[44:47]
	v_mfma_f32_16x16x32_bf16 v[40:43], v[168:171], v[214:217], v[40:43]
	v_mfma_f32_16x16x32_bf16 v[28:31], v[132:135], v[222:225], v[28:31]
	v_mfma_f32_16x16x32_bf16 v[24:27], v[168:171], v[222:225], v[24:27]
	v_mfma_f32_16x16x32_bf16 v[12:15], v[132:135], v[232:235], v[12:15]
	v_mfma_f32_16x16x32_bf16 v[8:11], v[168:171], v[232:235], v[8:11]
	s_setprio 0
	s_setprio 1
	v_mfma_f32_16x16x32_bf16 v[52:55], v[172:175], v[202:205], v[52:55]
	v_mfma_f32_16x16x32_bf16 v[48:51], v[194:197], v[202:205], v[48:51]
	v_mfma_f32_16x16x32_bf16 v[36:39], v[172:175], v[210:213], v[36:39]
	v_mfma_f32_16x16x32_bf16 v[32:35], v[194:197], v[210:213], v[32:35]
	v_mfma_f32_16x16x32_bf16 v[20:23], v[172:175], v[218:221], v[20:23]
	v_mfma_f32_16x16x32_bf16 v[16:19], v[194:197], v[218:221], v[16:19]
	v_mfma_f32_16x16x32_bf16 v[4:7], v[172:175], v[228:231], v[4:7]
	v_mfma_f32_16x16x32_bf16 v[0:3], v[194:197], v[228:231], v[0:3]
	v_mfma_f32_16x16x32_bf16 v[52:55], v[176:179], v[206:209], v[52:55]
	v_mfma_f32_16x16x32_bf16 v[48:51], v[198:201], v[206:209], v[48:51]
	v_mfma_f32_16x16x32_bf16 v[36:39], v[176:179], v[214:217], v[36:39]
	v_mfma_f32_16x16x32_bf16 v[32:35], v[198:201], v[214:217], v[32:35]
	v_mfma_f32_16x16x32_bf16 v[20:23], v[176:179], v[222:225], v[20:23]
	v_mfma_f32_16x16x32_bf16 v[16:19], v[198:201], v[222:225], v[16:19]
	v_mfma_f32_16x16x32_bf16 v[4:7], v[176:179], v[232:235], v[4:7]
	v_mfma_f32_16x16x32_bf16 v[0:3], v[198:201], v[232:235], v[0:3]
	s_setprio 0
	s_barrier
	s_add_i32 s76, s76, 2
	s_add_u32 s0, s0, 0x100
	s_addc_u32 s1, s1, 0
	s_add_u32 s74, s74, 0x100
	s_addc_u32 s75, s75, 0
	s_cmp_gt_u32 s76, 13
	s_cbranch_scc0 .LBB0_994
	s_and_b64 vcc, exec, s[24:25]
	s_cbranch_vccz .LBB0_997
	s_barrier

.LBB0_1016:
	v_lshl_or_b32 v141, s5, 6, v191
	s_lshl_b32 s5, s5, 13
	s_lshl_b32 s4, s4, 5
	v_bitop3_b32 v8, v138, s5, v140 bitop3:0xde
	s_and_b32 s21, s4, 0x60
	s_mov_b64 s[4:5], 0x80
	s_add_i32 m0, s17, 0x18000
	v_lshl_add_u64 v[6:7], v[6:7], 0, s[4:5]
	s_waitcnt vmcnt(2)
	s_barrier
	global_load_lds_dwordx4 v[6:7], off
	v_lshl_add_u64 v[4:5], v[4:5], 0, s[4:5]
	s_add_i32 m0, s17, 0x1a000
	s_add_i32 s22, s17, 0x8000
	s_add_i32 s23, s17, 0xa000
	global_load_lds_dwordx4 v[4:5], off
	v_lshl_add_u64 v[2:3], v[2:3], 0, s[4:5]
	s_mov_b32 m0, s22
	s_add_u32 s10, s0, 0x100080
	global_load_lds_dwordx4 v[2:3], off
	v_lshl_add_u64 v[0:1], v[0:1], 0, s[4:5]
	s_mov_b32 m0, s23
	s_addc_u32 s11, s1, 0
	global_load_lds_dwordx4 v[0:1], off
	s_add_i32 m0, s17, 0x1c000
	v_lshl_add_u64 v[0:1], s[10:11], 0, v[132:133]
	global_load_lds_dwordx4 v[0:1], off
	v_lshl_add_u64 v[0:1], s[10:11], 0, v[128:129]
	s_add_i32 m0, s17, 0x1e000
	s_add_u32 s10, s44, 0x100080
	global_load_lds_dwordx4 v[0:1], off
	s_addc_u32 s11, s45, 0
	v_lshlrev_b32_e32 v0, 17, v192
	v_lshlrev_b32_e32 v1, 13, v185
	s_add_u32 s12, s96, s54
	v_or3_b32 v0, v183, v0, v1
	s_addc_u32 s13, s97, 0
	s_waitcnt vmcnt(6)
	v_add_u32_e32 v136, v0, v184
	v_lshlrev_b32_e32 v0, 17, v193
	s_add_u32 s24, s12, 0x2100100
	v_lshl_or_b32 v9, s21, 7, v139
	v_or3_b32 v0, v183, v0, v1
	s_addc_u32 s25, s13, 0
	s_add_i32 s29, s48, s37
	s_add_i32 s31, s49, s37
	s_add_i32 s35, s51, s37
	s_add_i32 s37, s53, s37
	v_mov_b32_e32 v137, v133
	v_add_u32_e32 v138, v0, v184
	v_mov_b32_e32 v139, v133
	s_mov_b32 s26, -2
	v_add_u32_e32 v140, s48, v9
	v_add_u32_e32 v142, s49, v9
	v_add_u32_e32 v143, 0, v8
	s_add_i32 s27, s17, 0xc000
	s_add_i32 s28, s17, 0xe000
	s_add_i32 s30, s29, 0x2000
	s_add_i32 s34, s31, 0x2000
	v_add_u32_e32 v144, s51, v9
	v_add_u32_e32 v145, s53, v9
	s_add_i32 s36, s35, 0x2000
	s_add_i32 s38, s37, 0x2000
	s_barrier
	ds_read_b128 v[146:149], v140
	ds_read_b128 v[150:153], v140 offset:1024
	ds_read_b128 v[154:157], v140 offset:2048
	ds_read_b128 v[158:161], v140 offset:3072
	ds_read_b128 v[162:165], v142
	ds_read_b128 v[166:169], v142 offset:1024
	ds_read_b128 v[170:173], v142 offset:2048
	ds_read_b128 v[174:177], v142 offset:3072
	s_add_u32 s12, s10, 0xfff00080
	s_addc_u32 s13, s11, -1
	s_cmp_eq_u32 s26, 60
	s_cselect_b32 s15, s3, s13
	s_cselect_b32 s14, s2, s12
	s_cselect_b32 s13, s1, s25
	s_cselect_b32 s12, s0, s24
	s_mov_b32 m0, s27
	v_lshl_add_u64 v[212:213], s[10:11], 0, v[136:137]
	ds_read_b128 v[178:181], v143
	ds_read_b128 v[184:187], v143 offset:1024
	ds_read_b128 v[188:191], v143 offset:2048
	ds_read_b128 v[192:195], v143 offset:3072
	ds_read_b128 v[196:199], v143 offset:4096
	ds_read_b128 v[200:203], v143 offset:5120
	ds_read_b128 v[204:207], v143 offset:6144
	ds_read_b128 v[208:211], v143 offset:7168
	global_load_lds_dwordx4 v[212:213], off
	v_lshl_add_u64 v[212:213], s[10:11], 0, v[138:139]
	s_mov_b32 m0, s28
	s_nop 0
	global_load_lds_dwordx4 v[212:213], off
	s_waitcnt vmcnt(8)
	s_waitcnt lgkmcnt(0)
	s_barrier
	s_setprio 1
	v_mfma_f32_16x16x32_bf16 v[124:127], v[146:149], v[178:181], 0
	v_mfma_f32_16x16x32_bf16 v[120:123], v[154:157], v[178:181], 0
	v_mfma_f32_16x16x32_bf16 v[112:115], v[146:149], v[188:191], 0
	v_mfma_f32_16x16x32_bf16 v[104:107], v[154:157], v[188:191], 0
	v_mfma_f32_16x16x32_bf16 v[96:99], v[146:149], v[196:199], 0
	v_mfma_f32_16x16x32_bf16 v[88:91], v[154:157], v[196:199], 0
	v_mfma_f32_16x16x32_bf16 v[80:83], v[146:149], v[204:207], 0
	v_mfma_f32_16x16x32_bf16 v[72:75], v[154:157], v[204:207], 0
	v_mfma_f32_16x16x32_bf16 v[124:127], v[150:153], v[184:187], v[124:127]
	v_mfma_f32_16x16x32_bf16 v[120:123], v[158:161], v[184:187], v[120:123]
	v_mfma_f32_16x16x32_bf16 v[112:115], v[150:153], v[192:195], v[112:115]
	v_mfma_f32_16x16x32_bf16 v[104:107], v[158:161], v[192:195], v[104:107]
	v_mfma_f32_16x16x32_bf16 v[96:99], v[150:153], v[200:203], v[96:99]
	v_mfma_f32_16x16x32_bf16 v[88:91], v[158:161], v[200:203], v[88:91]
	v_mfma_f32_16x16x32_bf16 v[80:83], v[150:153], v[208:211], v[80:83]
	v_mfma_f32_16x16x32_bf16 v[72:75], v[158:161], v[208:211], v[72:75]
	s_setprio 0
	s_setprio 1
	v_mfma_f32_16x16x32_bf16 v[116:119], v[162:165], v[178:181], 0
	v_mfma_f32_16x16x32_bf16 v[108:111], v[170:173], v[178:181], 0
	v_mfma_f32_16x16x32_bf16 v[100:103], v[162:165], v[188:191], 0
	v_mfma_f32_16x16x32_bf16 v[92:95], v[170:173], v[188:191], 0
	v_mfma_f32_16x16x32_bf16 v[84:87], v[162:165], v[196:199], 0
	v_mfma_f32_16x16x32_bf16 v[76:79], v[170:173], v[196:199], 0
	v_mfma_f32_16x16x32_bf16 v[68:71], v[162:165], v[204:207], 0
	v_mfma_f32_16x16x32_bf16 v[64:67], v[170:173], v[204:207], 0
	v_mfma_f32_16x16x32_bf16 v[116:119], v[166:169], v[184:187], v[116:119]
	v_mfma_f32_16x16x32_bf16 v[108:111], v[174:177], v[184:187], v[108:111]
	v_mfma_f32_16x16x32_bf16 v[100:103], v[166:169], v[192:195], v[100:103]
	v_mfma_f32_16x16x32_bf16 v[92:95], v[174:177], v[192:195], v[92:95]
	v_mfma_f32_16x16x32_bf16 v[84:87], v[166:169], v[200:203], v[84:87]
	v_mfma_f32_16x16x32_bf16 v[76:79], v[174:177], v[200:203], v[76:79]
	v_mfma_f32_16x16x32_bf16 v[68:71], v[166:169], v[208:211], v[68:71]
	v_mfma_f32_16x16x32_bf16 v[64:67], v[174:177], v[208:211], v[64:67]
	s_setprio 0
	s_barrier
	s_mov_b32 m0, s29
	v_lshl_add_u64 v[212:213], s[12:13], 0, v[132:133]
	s_add_u32 s40, s12, 0x100000
	ds_read_b128 v[178:181], v143 offset:16384
	ds_read_b128 v[184:187], v143 offset:17408
	ds_read_b128 v[188:191], v143 offset:18432
	ds_read_b128 v[192:195], v143 offset:19456
	ds_read_b128 v[196:199], v143 offset:20480
	ds_read_b128 v[200:203], v143 offset:21504
	ds_read_b128 v[204:207], v143 offset:22528
	ds_read_b128 v[208:211], v143 offset:23552
	global_load_lds_dwordx4 v[212:213], off
	v_lshl_add_u64 v[214:215], s[12:13], 0, v[128:129]
	s_mov_b32 m0, s30
	s_addc_u32 s41, s13, 0
	global_load_lds_dwordx4 v[214:215], off
	v_lshl_add_u64 v[216:217], s[40:41], 0, v[132:133]
	s_mov_b32 m0, s31
	v_lshl_add_u64 v[218:219], s[14:15], 0, v[130:131]
	global_load_lds_dwordx4 v[216:217], off
	v_lshl_add_u64 v[216:217], s[40:41], 0, v[128:129]
	s_mov_b32 m0, s34
	s_nop 0
	global_load_lds_dwordx4 v[216:217], off
	v_lshl_add_u64 v[216:217], s[14:15], 0, v[134:135]
	s_mov_b32 m0, s17
	s_nop 0
	global_load_lds_dwordx4 v[216:217], off
	s_mov_b32 m0, s18
	s_nop 0
	global_load_lds_dwordx4 v[218:219], off
	s_waitcnt vmcnt(8)
	s_waitcnt lgkmcnt(0)
	s_barrier
	s_setprio 1
	v_mfma_f32_16x16x32_bf16 v[60:63], v[146:149], v[178:181], 0
	v_mfma_f32_16x16x32_bf16 v[56:59], v[154:157], v[178:181], 0
	v_mfma_f32_16x16x32_bf16 v[48:51], v[146:149], v[188:191], 0
	v_mfma_f32_16x16x32_bf16 v[40:43], v[154:157], v[188:191], 0
	v_mfma_f32_16x16x32_bf16 v[32:35], v[146:149], v[196:199], 0
	v_mfma_f32_16x16x32_bf16 v[24:27], v[154:157], v[196:199], 0
	v_mfma_f32_16x16x32_bf16 v[16:19], v[146:149], v[204:207], 0
	v_mfma_f32_16x16x32_bf16 v[8:11], v[154:157], v[204:207], 0
	v_mfma_f32_16x16x32_bf16 v[60:63], v[150:153], v[184:187], v[60:63]
	v_mfma_f32_16x16x32_bf16 v[56:59], v[158:161], v[184:187], v[56:59]
	v_mfma_f32_16x16x32_bf16 v[48:51], v[150:153], v[192:195], v[48:51]
	v_mfma_f32_16x16x32_bf16 v[40:43], v[158:161], v[192:195], v[40:43]
	v_mfma_f32_16x16x32_bf16 v[32:35], v[150:153], v[200:203], v[32:35]
	v_mfma_f32_16x16x32_bf16 v[24:27], v[158:161], v[200:203], v[24:27]
	v_mfma_f32_16x16x32_bf16 v[16:19], v[150:153], v[208:211], v[16:19]
	v_mfma_f32_16x16x32_bf16 v[8:11], v[158:161], v[208:211], v[8:11]
	s_setprio 0
	s_setprio 1
	v_mfma_f32_16x16x32_bf16 v[52:55], v[162:165], v[178:181], 0
	v_mfma_f32_16x16x32_bf16 v[44:47], v[170:173], v[178:181], 0
	v_mfma_f32_16x16x32_bf16 v[36:39], v[162:165], v[188:191], 0
	v_mfma_f32_16x16x32_bf16 v[28:31], v[170:173], v[188:191], 0
	v_mfma_f32_16x16x32_bf16 v[20:23], v[162:165], v[196:199], 0
	v_mfma_f32_16x16x32_bf16 v[12:15], v[170:173], v[196:199], 0
	v_mfma_f32_16x16x32_bf16 v[4:7], v[162:165], v[204:207], 0
	v_mfma_f32_16x16x32_bf16 v[0:3], v[170:173], v[204:207], 0
	v_mfma_f32_16x16x32_bf16 v[52:55], v[166:169], v[184:187], v[52:55]
	v_mfma_f32_16x16x32_bf16 v[44:47], v[174:177], v[184:187], v[44:47]
	v_mfma_f32_16x16x32_bf16 v[36:39], v[166:169], v[192:195], v[36:39]
	v_mfma_f32_16x16x32_bf16 v[28:31], v[174:177], v[192:195], v[28:31]
	v_mfma_f32_16x16x32_bf16 v[20:23], v[166:169], v[200:203], v[20:23]
	v_mfma_f32_16x16x32_bf16 v[12:15], v[174:177], v[200:203], v[12:15]
	v_mfma_f32_16x16x32_bf16 v[4:7], v[166:169], v[208:211], v[4:7]
	v_mfma_f32_16x16x32_bf16 v[0:3], v[174:177], v[208:211], v[0:3]
	s_setprio 0
	s_barrier
	ds_read_b128 v[146:149], v144
	ds_read_b128 v[150:153], v144 offset:1024
	ds_read_b128 v[154:157], v144 offset:2048
	ds_read_b128 v[158:161], v144 offset:3072
	ds_read_b128 v[162:165], v145
	ds_read_b128 v[166:169], v145 offset:1024
	ds_read_b128 v[170:173], v145 offset:2048
	ds_read_b128 v[174:177], v145 offset:3072
	s_add_u32 s14, s14, 0x100000
	s_addc_u32 s15, s15, 0
	s_mov_b32 m0, s19
	v_lshl_add_u64 v[220:221], s[14:15], 0, v[134:135]
	ds_read_b128 v[178:181], v143 offset:32768
	ds_read_b128 v[184:187], v143 offset:33792
	ds_read_b128 v[188:191], v143 offset:34816
	ds_read_b128 v[192:195], v143 offset:35840
	ds_read_b128 v[196:199], v143 offset:36864
	ds_read_b128 v[200:203], v143 offset:37888
	ds_read_b128 v[204:207], v143 offset:38912
	ds_read_b128 v[208:211], v143 offset:39936
	global_load_lds_dwordx4 v[220:221], off
	v_lshl_add_u64 v[220:221], s[14:15], 0, v[130:131]
	s_mov_b32 m0, s20
	s_nop 0
	global_load_lds_dwordx4 v[220:221], off
	s_waitcnt vmcnt(8)
	s_waitcnt lgkmcnt(0)
	s_barrier
	s_setprio 1
	v_mfma_f32_16x16x32_bf16 v[124:127], v[146:149], v[178:181], v[124:127]
	v_mfma_f32_16x16x32_bf16 v[120:123], v[154:157], v[178:181], v[120:123]
	v_mfma_f32_16x16x32_bf16 v[112:115], v[146:149], v[188:191], v[112:115]
	v_mfma_f32_16x16x32_bf16 v[104:107], v[154:157], v[188:191], v[104:107]
	v_mfma_f32_16x16x32_bf16 v[96:99], v[146:149], v[196:199], v[96:99]
	v_mfma_f32_16x16x32_bf16 v[88:91], v[154:157], v[196:199], v[88:91]
	v_mfma_f32_16x16x32_bf16 v[80:83], v[146:149], v[204:207], v[80:83]
	v_mfma_f32_16x16x32_bf16 v[72:75], v[154:157], v[204:207], v[72:75]
	v_mfma_f32_16x16x32_bf16 v[124:127], v[150:153], v[184:187], v[124:127]
	v_mfma_f32_16x16x32_bf16 v[120:123], v[158:161], v[184:187], v[120:123]
	v_mfma_f32_16x16x32_bf16 v[112:115], v[150:153], v[192:195], v[112:115]
	v_mfma_f32_16x16x32_bf16 v[104:107], v[158:161], v[192:195], v[104:107]
	v_mfma_f32_16x16x32_bf16 v[96:99], v[150:153], v[200:203], v[96:99]
	v_mfma_f32_16x16x32_bf16 v[88:91], v[158:161], v[200:203], v[88:91]
	v_mfma_f32_16x16x32_bf16 v[80:83], v[150:153], v[208:211], v[80:83]
	v_mfma_f32_16x16x32_bf16 v[72:75], v[158:161], v[208:211], v[72:75]
	s_setprio 0
	s_setprio 1
	v_mfma_f32_16x16x32_bf16 v[116:119], v[162:165], v[178:181], v[116:119]
	v_mfma_f32_16x16x32_bf16 v[108:111], v[170:173], v[178:181], v[108:111]
	v_mfma_f32_16x16x32_bf16 v[100:103], v[162:165], v[188:191], v[100:103]
	v_mfma_f32_16x16x32_bf16 v[92:95], v[170:173], v[188:191], v[92:95]
	v_mfma_f32_16x16x32_bf16 v[84:87], v[162:165], v[196:199], v[84:87]
	v_mfma_f32_16x16x32_bf16 v[76:79], v[170:173], v[196:199], v[76:79]
	v_mfma_f32_16x16x32_bf16 v[68:71], v[162:165], v[204:207], v[68:71]
	v_mfma_f32_16x16x32_bf16 v[64:67], v[170:173], v[204:207], v[64:67]
	v_mfma_f32_16x16x32_bf16 v[116:119], v[166:169], v[184:187], v[116:119]
	v_mfma_f32_16x16x32_bf16 v[108:111], v[174:177], v[184:187], v[108:111]
	v_mfma_f32_16x16x32_bf16 v[100:103], v[166:169], v[192:195], v[100:103]
	v_mfma_f32_16x16x32_bf16 v[92:95], v[174:177], v[192:195], v[92:95]
	v_mfma_f32_16x16x32_bf16 v[84:87], v[166:169], v[200:203], v[84:87]
	v_mfma_f32_16x16x32_bf16 v[76:79], v[174:177], v[200:203], v[76:79]
	v_mfma_f32_16x16x32_bf16 v[68:71], v[166:169], v[208:211], v[68:71]
	v_mfma_f32_16x16x32_bf16 v[64:67], v[174:177], v[208:211], v[64:67]
	s_setprio 0
	s_barrier
	s_mov_b32 m0, s35
	v_lshl_add_u64 v[212:213], v[212:213], 0, s[4:5]
	s_add_u32 s12, s12, 0x100080
	ds_read_b128 v[178:181], v143 offset:49152
	ds_read_b128 v[184:187], v143 offset:50176
	ds_read_b128 v[188:191], v143 offset:51200
	ds_read_b128 v[192:195], v143 offset:52224
	ds_read_b128 v[196:199], v143 offset:53248
	ds_read_b128 v[200:203], v143 offset:54272
	ds_read_b128 v[204:207], v143 offset:55296
	ds_read_b128 v[208:211], v143 offset:56320
	global_load_lds_dwordx4 v[212:213], off
	v_lshl_add_u64 v[212:213], v[214:215], 0, s[4:5]
	s_mov_b32 m0, s36
	s_addc_u32 s13, s13, 0
	global_load_lds_dwordx4 v[212:213], off
	v_lshl_add_u64 v[212:213], s[12:13], 0, v[132:133]
	s_mov_b32 m0, s37
	s_nop 0
	global_load_lds_dwordx4 v[212:213], off
	v_lshl_add_u64 v[212:213], s[12:13], 0, v[128:129]
	s_mov_b32 m0, s38
	s_nop 0
	global_load_lds_dwordx4 v[212:213], off
	v_lshl_add_u64 v[212:213], v[216:217], 0, s[4:5]
	s_mov_b32 m0, s22
	s_nop 0
	global_load_lds_dwordx4 v[212:213], off
	v_lshl_add_u64 v[212:213], v[218:219], 0, s[4:5]
	s_mov_b32 m0, s23
	s_nop 0
	global_load_lds_dwordx4 v[212:213], off
	s_waitcnt vmcnt(8)
	s_waitcnt lgkmcnt(0)
	s_barrier
	s_setprio 1
	v_mfma_f32_16x16x32_bf16 v[60:63], v[146:149], v[178:181], v[60:63]
	v_mfma_f32_16x16x32_bf16 v[56:59], v[154:157], v[178:181], v[56:59]
	v_mfma_f32_16x16x32_bf16 v[48:51], v[146:149], v[188:191], v[48:51]
	v_mfma_f32_16x16x32_bf16 v[40:43], v[154:157], v[188:191], v[40:43]
	v_mfma_f32_16x16x32_bf16 v[32:35], v[146:149], v[196:199], v[32:35]
	v_mfma_f32_16x16x32_bf16 v[24:27], v[154:157], v[196:199], v[24:27]
	v_mfma_f32_16x16x32_bf16 v[16:19], v[146:149], v[204:207], v[16:19]
	v_mfma_f32_16x16x32_bf16 v[8:11], v[154:157], v[204:207], v[8:11]
	v_mfma_f32_16x16x32_bf16 v[60:63], v[150:153], v[184:187], v[60:63]
	v_mfma_f32_16x16x32_bf16 v[56:59], v[158:161], v[184:187], v[56:59]
	v_mfma_f32_16x16x32_bf16 v[48:51], v[150:153], v[192:195], v[48:51]
	v_mfma_f32_16x16x32_bf16 v[40:43], v[158:161], v[192:195], v[40:43]
	v_mfma_f32_16x16x32_bf16 v[32:35], v[150:153], v[200:203], v[32:35]
	v_mfma_f32_16x16x32_bf16 v[24:27], v[158:161], v[200:203], v[24:27]
	v_mfma_f32_16x16x32_bf16 v[16:19], v[150:153], v[208:211], v[16:19]
	v_mfma_f32_16x16x32_bf16 v[8:11], v[158:161], v[208:211], v[8:11]
	s_setprio 0
	s_setprio 1
	v_mfma_f32_16x16x32_bf16 v[52:55], v[162:165], v[178:181], v[52:55]
	v_mfma_f32_16x16x32_bf16 v[44:47], v[170:173], v[178:181], v[44:47]
	v_mfma_f32_16x16x32_bf16 v[36:39], v[162:165], v[188:191], v[36:39]
	v_mfma_f32_16x16x32_bf16 v[28:31], v[170:173], v[188:191], v[28:31]
	v_mfma_f32_16x16x32_bf16 v[20:23], v[162:165], v[196:199], v[20:23]
	v_mfma_f32_16x16x32_bf16 v[12:15], v[170:173], v[196:199], v[12:15]
	v_mfma_f32_16x16x32_bf16 v[4:7], v[162:165], v[204:207], v[4:7]
	v_mfma_f32_16x16x32_bf16 v[0:3], v[170:173], v[204:207], v[0:3]
	v_mfma_f32_16x16x32_bf16 v[52:55], v[166:169], v[184:187], v[52:55]
	v_mfma_f32_16x16x32_bf16 v[44:47], v[174:177], v[184:187], v[44:47]
	v_mfma_f32_16x16x32_bf16 v[36:39], v[166:169], v[192:195], v[36:39]
	v_mfma_f32_16x16x32_bf16 v[28:31], v[174:177], v[192:195], v[28:31]
	v_mfma_f32_16x16x32_bf16 v[20:23], v[166:169], v[200:203], v[20:23]
	v_mfma_f32_16x16x32_bf16 v[12:15], v[174:177], v[200:203], v[12:15]
	v_mfma_f32_16x16x32_bf16 v[4:7], v[166:169], v[208:211], v[4:7]
	v_mfma_f32_16x16x32_bf16 v[0:3], v[174:177], v[208:211], v[0:3]
	s_setprio 0
	s_barrier
	s_add_i32 s26, s26, 2
	s_add_u32 s10, s10, 0x100
	s_addc_u32 s11, s11, 0
	s_add_u32 s24, s24, 0x100
	s_addc_u32 s25, s25, 0
	s_cmp_gt_u32 s26, 61
.LBB0_1017:
	ds_read_b128 v[146:149], v140
	ds_read_b128 v[150:153], v140 offset:1024
	ds_read_b128 v[154:157], v140 offset:2048
	ds_read_b128 v[158:161], v140 offset:3072
	ds_read_b128 v[162:165], v142
	ds_read_b128 v[166:169], v142 offset:1024
	ds_read_b128 v[170:173], v142 offset:2048
	ds_read_b128 v[174:177], v142 offset:3072
	s_add_u32 s12, s10, 0xfff00080
	s_addc_u32 s13, s11, -1
	s_cmp_eq_u32 s26, 60
	s_cselect_b32 s15, s3, s13
	s_cselect_b32 s14, s2, s12
	s_cselect_b32 s13, s1, s25
	s_cselect_b32 s12, s0, s24
	s_mov_b32 m0, s27
	v_lshl_add_u64 v[212:213], s[10:11], 0, v[136:137]
	ds_read_b128 v[178:181], v143
	ds_read_b128 v[184:187], v143 offset:1024
	ds_read_b128 v[188:191], v143 offset:2048
	ds_read_b128 v[192:195], v143 offset:3072
	ds_read_b128 v[196:199], v143 offset:4096
	ds_read_b128 v[200:203], v143 offset:5120
	ds_read_b128 v[204:207], v143 offset:6144
	ds_read_b128 v[208:211], v143 offset:7168
	global_load_lds_dwordx4 v[212:213], off
	v_lshl_add_u64 v[212:213], s[10:11], 0, v[138:139]
	s_mov_b32 m0, s28
	s_nop 0
	global_load_lds_dwordx4 v[212:213], off
	s_waitcnt vmcnt(8)
	s_waitcnt lgkmcnt(0)
	s_barrier
	s_setprio 1
	v_mfma_f32_16x16x32_bf16 v[124:127], v[146:149], v[178:181], v[124:127]
	v_mfma_f32_16x16x32_bf16 v[120:123], v[154:157], v[178:181], v[120:123]
	v_mfma_f32_16x16x32_bf16 v[112:115], v[146:149], v[188:191], v[112:115]
	v_mfma_f32_16x16x32_bf16 v[104:107], v[154:157], v[188:191], v[104:107]
	v_mfma_f32_16x16x32_bf16 v[96:99], v[146:149], v[196:199], v[96:99]
	v_mfma_f32_16x16x32_bf16 v[88:91], v[154:157], v[196:199], v[88:91]
	v_mfma_f32_16x16x32_bf16 v[80:83], v[146:149], v[204:207], v[80:83]
	v_mfma_f32_16x16x32_bf16 v[72:75], v[154:157], v[204:207], v[72:75]
	v_mfma_f32_16x16x32_bf16 v[124:127], v[150:153], v[184:187], v[124:127]
	v_mfma_f32_16x16x32_bf16 v[120:123], v[158:161], v[184:187], v[120:123]
	v_mfma_f32_16x16x32_bf16 v[112:115], v[150:153], v[192:195], v[112:115]
	v_mfma_f32_16x16x32_bf16 v[104:107], v[158:161], v[192:195], v[104:107]
	v_mfma_f32_16x16x32_bf16 v[96:99], v[150:153], v[200:203], v[96:99]
	v_mfma_f32_16x16x32_bf16 v[88:91], v[158:161], v[200:203], v[88:91]
	v_mfma_f32_16x16x32_bf16 v[80:83], v[150:153], v[208:211], v[80:83]
	v_mfma_f32_16x16x32_bf16 v[72:75], v[158:161], v[208:211], v[72:75]
	s_setprio 0
	s_setprio 1
	v_mfma_f32_16x16x32_bf16 v[116:119], v[162:165], v[178:181], v[116:119]
	v_mfma_f32_16x16x32_bf16 v[108:111], v[170:173], v[178:181], v[108:111]
	v_mfma_f32_16x16x32_bf16 v[100:103], v[162:165], v[188:191], v[100:103]
	v_mfma_f32_16x16x32_bf16 v[92:95], v[170:173], v[188:191], v[92:95]
	v_mfma_f32_16x16x32_bf16 v[84:87], v[162:165], v[196:199], v[84:87]
	v_mfma_f32_16x16x32_bf16 v[76:79], v[170:173], v[196:199], v[76:79]
	v_mfma_f32_16x16x32_bf16 v[68:71], v[162:165], v[204:207], v[68:71]
	v_mfma_f32_16x16x32_bf16 v[64:67], v[170:173], v[204:207], v[64:67]
	v_mfma_f32_16x16x32_bf16 v[116:119], v[166:169], v[184:187], v[116:119]
	v_mfma_f32_16x16x32_bf16 v[108:111], v[174:177], v[184:187], v[108:111]
	v_mfma_f32_16x16x32_bf16 v[100:103], v[166:169], v[192:195], v[100:103]
	v_mfma_f32_16x16x32_bf16 v[92:95], v[174:177], v[192:195], v[92:95]
	v_mfma_f32_16x16x32_bf16 v[84:87], v[166:169], v[200:203], v[84:87]
	v_mfma_f32_16x16x32_bf16 v[76:79], v[174:177], v[200:203], v[76:79]
	v_mfma_f32_16x16x32_bf16 v[68:71], v[166:169], v[208:211], v[68:71]
	v_mfma_f32_16x16x32_bf16 v[64:67], v[174:177], v[208:211], v[64:67]
	s_setprio 0
	s_barrier
	s_mov_b32 m0, s29
	v_lshl_add_u64 v[212:213], s[12:13], 0, v[132:133]
	s_add_u32 s40, s12, 0x100000
	ds_read_b128 v[178:181], v143 offset:16384
	ds_read_b128 v[184:187], v143 offset:17408
	ds_read_b128 v[188:191], v143 offset:18432
	ds_read_b128 v[192:195], v143 offset:19456
	ds_read_b128 v[196:199], v143 offset:20480
	ds_read_b128 v[200:203], v143 offset:21504
	ds_read_b128 v[204:207], v143 offset:22528
	ds_read_b128 v[208:211], v143 offset:23552
	global_load_lds_dwordx4 v[212:213], off
	v_lshl_add_u64 v[214:215], s[12:13], 0, v[128:129]
	s_mov_b32 m0, s30
	s_addc_u32 s41, s13, 0
	global_load_lds_dwordx4 v[214:215], off
	v_lshl_add_u64 v[216:217], s[40:41], 0, v[132:133]
	s_mov_b32 m0, s31
	v_lshl_add_u64 v[218:219], s[14:15], 0, v[130:131]
	global_load_lds_dwordx4 v[216:217], off
	v_lshl_add_u64 v[216:217], s[40:41], 0, v[128:129]
	s_mov_b32 m0, s34
	s_nop 0
	global_load_lds_dwordx4 v[216:217], off
	v_lshl_add_u64 v[216:217], s[14:15], 0, v[134:135]
	s_mov_b32 m0, s17
	s_nop 0
	global_load_lds_dwordx4 v[216:217], off
	s_mov_b32 m0, s18
	s_nop 0
	global_load_lds_dwordx4 v[218:219], off
	s_waitcnt vmcnt(8)
	s_waitcnt lgkmcnt(0)
	s_barrier
	s_setprio 1
	v_mfma_f32_16x16x32_bf16 v[60:63], v[146:149], v[178:181], v[60:63]
	v_mfma_f32_16x16x32_bf16 v[56:59], v[154:157], v[178:181], v[56:59]
	v_mfma_f32_16x16x32_bf16 v[48:51], v[146:149], v[188:191], v[48:51]
	v_mfma_f32_16x16x32_bf16 v[40:43], v[154:157], v[188:191], v[40:43]
	v_mfma_f32_16x16x32_bf16 v[32:35], v[146:149], v[196:199], v[32:35]
	v_mfma_f32_16x16x32_bf16 v[24:27], v[154:157], v[196:199], v[24:27]
	v_mfma_f32_16x16x32_bf16 v[16:19], v[146:149], v[204:207], v[16:19]
	v_mfma_f32_16x16x32_bf16 v[8:11], v[154:157], v[204:207], v[8:11]
	v_mfma_f32_16x16x32_bf16 v[60:63], v[150:153], v[184:187], v[60:63]
	v_mfma_f32_16x16x32_bf16 v[56:59], v[158:161], v[184:187], v[56:59]
	v_mfma_f32_16x16x32_bf16 v[48:51], v[150:153], v[192:195], v[48:51]
	v_mfma_f32_16x16x32_bf16 v[40:43], v[158:161], v[192:195], v[40:43]
	v_mfma_f32_16x16x32_bf16 v[32:35], v[150:153], v[200:203], v[32:35]
	v_mfma_f32_16x16x32_bf16 v[24:27], v[158:161], v[200:203], v[24:27]
	v_mfma_f32_16x16x32_bf16 v[16:19], v[150:153], v[208:211], v[16:19]
	v_mfma_f32_16x16x32_bf16 v[8:11], v[158:161], v[208:211], v[8:11]
	s_setprio 0
	s_setprio 1
	v_mfma_f32_16x16x32_bf16 v[52:55], v[162:165], v[178:181], v[52:55]
	v_mfma_f32_16x16x32_bf16 v[44:47], v[170:173], v[178:181], v[44:47]
	v_mfma_f32_16x16x32_bf16 v[36:39], v[162:165], v[188:191], v[36:39]
	v_mfma_f32_16x16x32_bf16 v[28:31], v[170:173], v[188:191], v[28:31]
	v_mfma_f32_16x16x32_bf16 v[20:23], v[162:165], v[196:199], v[20:23]
	v_mfma_f32_16x16x32_bf16 v[12:15], v[170:173], v[196:199], v[12:15]
	v_mfma_f32_16x16x32_bf16 v[4:7], v[162:165], v[204:207], v[4:7]
	v_mfma_f32_16x16x32_bf16 v[0:3], v[170:173], v[204:207], v[0:3]
	v_mfma_f32_16x16x32_bf16 v[52:55], v[166:169], v[184:187], v[52:55]
	v_mfma_f32_16x16x32_bf16 v[44:47], v[174:177], v[184:187], v[44:47]
	v_mfma_f32_16x16x32_bf16 v[36:39], v[166:169], v[192:195], v[36:39]
	v_mfma_f32_16x16x32_bf16 v[28:31], v[174:177], v[192:195], v[28:31]
	v_mfma_f32_16x16x32_bf16 v[20:23], v[166:169], v[200:203], v[20:23]
	v_mfma_f32_16x16x32_bf16 v[12:15], v[174:177], v[200:203], v[12:15]
	v_mfma_f32_16x16x32_bf16 v[4:7], v[166:169], v[208:211], v[4:7]
	v_mfma_f32_16x16x32_bf16 v[0:3], v[174:177], v[208:211], v[0:3]
	s_setprio 0
	s_barrier
	ds_read_b128 v[146:149], v144
	ds_read_b128 v[150:153], v144 offset:1024
	ds_read_b128 v[154:157], v144 offset:2048
	ds_read_b128 v[158:161], v144 offset:3072
	ds_read_b128 v[162:165], v145
	ds_read_b128 v[166:169], v145 offset:1024
	ds_read_b128 v[170:173], v145 offset:2048
	ds_read_b128 v[174:177], v145 offset:3072
	s_add_u32 s14, s14, 0x100000
	s_addc_u32 s15, s15, 0
	s_mov_b32 m0, s19
	v_lshl_add_u64 v[220:221], s[14:15], 0, v[134:135]
	ds_read_b128 v[178:181], v143 offset:32768
	ds_read_b128 v[184:187], v143 offset:33792
	ds_read_b128 v[188:191], v143 offset:34816
	ds_read_b128 v[192:195], v143 offset:35840
	ds_read_b128 v[196:199], v143 offset:36864
	ds_read_b128 v[200:203], v143 offset:37888
	ds_read_b128 v[204:207], v143 offset:38912
	ds_read_b128 v[208:211], v143 offset:39936
	global_load_lds_dwordx4 v[220:221], off
	v_lshl_add_u64 v[220:221], s[14:15], 0, v[130:131]
	s_mov_b32 m0, s20
	s_nop 0
	global_load_lds_dwordx4 v[220:221], off
	s_waitcnt vmcnt(8)
	s_waitcnt lgkmcnt(0)
	s_barrier
	s_setprio 1
	v_mfma_f32_16x16x32_bf16 v[124:127], v[146:149], v[178:181], v[124:127]
	v_mfma_f32_16x16x32_bf16 v[120:123], v[154:157], v[178:181], v[120:123]
	v_mfma_f32_16x16x32_bf16 v[112:115], v[146:149], v[188:191], v[112:115]
	v_mfma_f32_16x16x32_bf16 v[104:107], v[154:157], v[188:191], v[104:107]
	v_mfma_f32_16x16x32_bf16 v[96:99], v[146:149], v[196:199], v[96:99]
	v_mfma_f32_16x16x32_bf16 v[88:91], v[154:157], v[196:199], v[88:91]
	v_mfma_f32_16x16x32_bf16 v[80:83], v[146:149], v[204:207], v[80:83]
	v_mfma_f32_16x16x32_bf16 v[72:75], v[154:157], v[204:207], v[72:75]
	v_mfma_f32_16x16x32_bf16 v[124:127], v[150:153], v[184:187], v[124:127]
	v_mfma_f32_16x16x32_bf16 v[120:123], v[158:161], v[184:187], v[120:123]
	v_mfma_f32_16x16x32_bf16 v[112:115], v[150:153], v[192:195], v[112:115]
	v_mfma_f32_16x16x32_bf16 v[104:107], v[158:161], v[192:195], v[104:107]
	v_mfma_f32_16x16x32_bf16 v[96:99], v[150:153], v[200:203], v[96:99]
	v_mfma_f32_16x16x32_bf16 v[88:91], v[158:161], v[200:203], v[88:91]
	v_mfma_f32_16x16x32_bf16 v[80:83], v[150:153], v[208:211], v[80:83]
	v_mfma_f32_16x16x32_bf16 v[72:75], v[158:161], v[208:211], v[72:75]
	s_setprio 0
	s_setprio 1
	v_mfma_f32_16x16x32_bf16 v[116:119], v[162:165], v[178:181], v[116:119]
	v_mfma_f32_16x16x32_bf16 v[108:111], v[170:173], v[178:181], v[108:111]
	v_mfma_f32_16x16x32_bf16 v[100:103], v[162:165], v[188:191], v[100:103]
	v_mfma_f32_16x16x32_bf16 v[92:95], v[170:173], v[188:191], v[92:95]
	v_mfma_f32_16x16x32_bf16 v[84:87], v[162:165], v[196:199], v[84:87]
	v_mfma_f32_16x16x32_bf16 v[76:79], v[170:173], v[196:199], v[76:79]
	v_mfma_f32_16x16x32_bf16 v[68:71], v[162:165], v[204:207], v[68:71]
	v_mfma_f32_16x16x32_bf16 v[64:67], v[170:173], v[204:207], v[64:67]
	v_mfma_f32_16x16x32_bf16 v[116:119], v[166:169], v[184:187], v[116:119]
	v_mfma_f32_16x16x32_bf16 v[108:111], v[174:177], v[184:187], v[108:111]
	v_mfma_f32_16x16x32_bf16 v[100:103], v[166:169], v[192:195], v[100:103]
	v_mfma_f32_16x16x32_bf16 v[92:95], v[174:177], v[192:195], v[92:95]
	v_mfma_f32_16x16x32_bf16 v[84:87], v[166:169], v[200:203], v[84:87]
	v_mfma_f32_16x16x32_bf16 v[76:79], v[174:177], v[200:203], v[76:79]
	v_mfma_f32_16x16x32_bf16 v[68:71], v[166:169], v[208:211], v[68:71]
	v_mfma_f32_16x16x32_bf16 v[64:67], v[174:177], v[208:211], v[64:67]
	s_setprio 0
	s_barrier
	s_mov_b32 m0, s35
	v_lshl_add_u64 v[212:213], v[212:213], 0, s[4:5]
	s_add_u32 s12, s12, 0x100080
	ds_read_b128 v[178:181], v143 offset:49152
	ds_read_b128 v[184:187], v143 offset:50176
	ds_read_b128 v[188:191], v143 offset:51200
	ds_read_b128 v[192:195], v143 offset:52224
	ds_read_b128 v[196:199], v143 offset:53248
	ds_read_b128 v[200:203], v143 offset:54272
	ds_read_b128 v[204:207], v143 offset:55296
	ds_read_b128 v[208:211], v143 offset:56320
	global_load_lds_dwordx4 v[212:213], off
	v_lshl_add_u64 v[212:213], v[214:215], 0, s[4:5]
	s_mov_b32 m0, s36
	s_addc_u32 s13, s13, 0
	global_load_lds_dwordx4 v[212:213], off
	v_lshl_add_u64 v[212:213], s[12:13], 0, v[132:133]
	s_mov_b32 m0, s37
	s_nop 0
	global_load_lds_dwordx4 v[212:213], off
	v_lshl_add_u64 v[212:213], s[12:13], 0, v[128:129]
	s_mov_b32 m0, s38
	s_nop 0
	global_load_lds_dwordx4 v[212:213], off
	v_lshl_add_u64 v[212:213], v[216:217], 0, s[4:5]
	s_mov_b32 m0, s22
	s_nop 0
	global_load_lds_dwordx4 v[212:213], off
	v_lshl_add_u64 v[212:213], v[218:219], 0, s[4:5]
	s_mov_b32 m0, s23
	s_nop 0
	global_load_lds_dwordx4 v[212:213], off
	s_waitcnt vmcnt(8)
	s_waitcnt lgkmcnt(0)
	s_barrier
	s_setprio 1
	v_mfma_f32_16x16x32_bf16 v[60:63], v[146:149], v[178:181], v[60:63]
	v_mfma_f32_16x16x32_bf16 v[56:59], v[154:157], v[178:181], v[56:59]
	v_mfma_f32_16x16x32_bf16 v[48:51], v[146:149], v[188:191], v[48:51]
	v_mfma_f32_16x16x32_bf16 v[40:43], v[154:157], v[188:191], v[40:43]
	v_mfma_f32_16x16x32_bf16 v[32:35], v[146:149], v[196:199], v[32:35]
	v_mfma_f32_16x16x32_bf16 v[24:27], v[154:157], v[196:199], v[24:27]
	v_mfma_f32_16x16x32_bf16 v[16:19], v[146:149], v[204:207], v[16:19]
	v_mfma_f32_16x16x32_bf16 v[8:11], v[154:157], v[204:207], v[8:11]
	v_mfma_f32_16x16x32_bf16 v[60:63], v[150:153], v[184:187], v[60:63]
	v_mfma_f32_16x16x32_bf16 v[56:59], v[158:161], v[184:187], v[56:59]
	v_mfma_f32_16x16x32_bf16 v[48:51], v[150:153], v[192:195], v[48:51]
	v_mfma_f32_16x16x32_bf16 v[40:43], v[158:161], v[192:195], v[40:43]
	v_mfma_f32_16x16x32_bf16 v[32:35], v[150:153], v[200:203], v[32:35]
	v_mfma_f32_16x16x32_bf16 v[24:27], v[158:161], v[200:203], v[24:27]
	v_mfma_f32_16x16x32_bf16 v[16:19], v[150:153], v[208:211], v[16:19]
	v_mfma_f32_16x16x32_bf16 v[8:11], v[158:161], v[208:211], v[8:11]
	s_setprio 0
	s_setprio 1
	v_mfma_f32_16x16x32_bf16 v[52:55], v[162:165], v[178:181], v[52:55]
	v_mfma_f32_16x16x32_bf16 v[44:47], v[170:173], v[178:181], v[44:47]
	v_mfma_f32_16x16x32_bf16 v[36:39], v[162:165], v[188:191], v[36:39]
	v_mfma_f32_16x16x32_bf16 v[28:31], v[170:173], v[188:191], v[28:31]
	v_mfma_f32_16x16x32_bf16 v[20:23], v[162:165], v[196:199], v[20:23]
	v_mfma_f32_16x16x32_bf16 v[12:15], v[170:173], v[196:199], v[12:15]
	v_mfma_f32_16x16x32_bf16 v[4:7], v[162:165], v[204:207], v[4:7]
	v_mfma_f32_16x16x32_bf16 v[0:3], v[170:173], v[204:207], v[0:3]
	v_mfma_f32_16x16x32_bf16 v[52:55], v[166:169], v[184:187], v[52:55]
	v_mfma_f32_16x16x32_bf16 v[44:47], v[174:177], v[184:187], v[44:47]
	v_mfma_f32_16x16x32_bf16 v[36:39], v[166:169], v[192:195], v[36:39]
	v_mfma_f32_16x16x32_bf16 v[28:31], v[174:177], v[192:195], v[28:31]
	v_mfma_f32_16x16x32_bf16 v[20:23], v[166:169], v[200:203], v[20:23]
	v_mfma_f32_16x16x32_bf16 v[12:15], v[174:177], v[200:203], v[12:15]
	v_mfma_f32_16x16x32_bf16 v[4:7], v[166:169], v[208:211], v[4:7]
	v_mfma_f32_16x16x32_bf16 v[0:3], v[174:177], v[208:211], v[0:3]
	s_setprio 0
	s_barrier
	s_add_i32 s26, s26, 2
	s_add_u32 s10, s10, 0x100
	s_addc_u32 s11, s11, 0
	s_add_u32 s24, s24, 0x100
	s_addc_u32 s25, s25, 0
	s_cmp_gt_u32 s26, 61
	s_cbranch_scc0 .LBB0_1017
	s_cmpk_lt_u32 s16, 0x100
	s_cbranch_scc0 .LBB0_1020
	s_barrier
